# v10: accumulator zeroing with 64 v_mov_b64 instead of 128 v_mov_b32 in all six GEMM unit headers + trailing half's re-stagger barrier moved behind the unit header, on top of v5
# speedup vs baseline: 1.0036x; 1.0036x over previous
.LBB0_258:
	s_or_b64 exec, exec, s[2:3]
	s_mov_b32 s99, 0
	v_add_u32_e32 v224, s59, v223
	s_mov_b64 s[2:3], s[90:91]
	s_waitcnt lgkmcnt(0)
	v_mov_b32_e32 v0, v224
	s_barrier
	s_nop 0
	v_readfirstlane_b32 s0, v0
	s_ashr_i32 s1, s0, 6
	s_lshl_b32 s4, s1, 10
	s_add_i32 s27, s4, 0
	s_cmpk_lt_i32 s85, 0x700
	s_cselect_b64 s[4:5], -1, 0
	s_cmpk_gt_i32 s85, 0x6ff
	s_cbranch_scc1 .LBB0_260
	s_ashr_i32 s6, s85, 31
	s_lshr_b32 s6, s6, 29
	s_add_i32 s6, s85, s6
	s_ashr_i32 s7, s6, 3
	s_and_b32 s6, s6, -8
	s_sub_i32 s6, s85, s6
	s_cmp_lt_i32 s6, 0
	s_movk_i32 s8, 0xe1
	s_cselect_b32 s8, s8, 0xe0
	s_mul_i32 s6, s6, s8
	s_add_i32 s6, s6, s7
	s_mul_hi_i32 s7, s6, 0x92492493
	s_add_i32 s7, s7, s6
	s_lshr_b32 s8, s7, 31
	s_ashr_i32 s7, s7, 8
	s_add_i32 s7, s7, s8
	s_lshl_b32 s8, s7, 3
	s_mulk_i32 s7, 0x1c0
	s_sub_i32 s6, s6, s7
	s_sext_i32_i16 s7, s6
	s_bfe_u32 s7, s7, 0x3001c
	s_add_i32 s7, s6, s7
	s_sext_i32_i16 s9, s7
	s_and_b32 s7, s7, 0xfff8
	s_sub_i32 s6, s6, s7
	s_sext_i32_i16 s6, s6
	s_add_i32 s6, s8, s6
	s_ashr_i32 s10, s9, 3

.LBB0_268:
	s_ashr_i32 s39, s38, 31
	s_lshl_b64 s[0:1], s[38:39], 20
	s_add_u32 s40, s29, s0
	s_addc_u32 s41, s52, s1
	s_and_b64 s[0:1], s[4:5], exec
	s_cselect_b32 s1, s41, s9
	s_cselect_b32 s7, s40, s8
	s_ashr_i32 s37, s36, 31
	s_lshl_b64 s[42:43], s[36:37], 20
	s_add_u32 s42, s53, s42
	s_addc_u32 s43, s56, s43
	s_and_b64 s[46:47], s[4:5], exec
	s_cselect_b32 s11, s43, s45
	s_cselect_b32 s33, s42, s44
	s_add_u32 s37, s44, 0x100
	s_addc_u32 s39, s45, 0
	s_mov_b32 s72, -2
	s_waitcnt vmcnt(24)
	s_waitcnt vmcnt(23)
	s_waitcnt vmcnt(22)
	s_waitcnt vmcnt(21)
	s_waitcnt vmcnt(20)
	s_waitcnt vmcnt(19)
	s_waitcnt vmcnt(18)
	s_waitcnt vmcnt(17)
	s_waitcnt vmcnt(16)
	s_waitcnt vmcnt(15)
	s_waitcnt vmcnt(14)
	s_waitcnt vmcnt(13)
	s_waitcnt vmcnt(12)
	s_waitcnt vmcnt(11)
	s_waitcnt vmcnt(10)
	s_waitcnt vmcnt(9)
	s_waitcnt vmcnt(8)
	v_mov_b64_e32 v[32:33], 0
	v_mov_b64_e32 v[34:35], 0
	v_mov_b64_e32 v[36:37], 0
	v_mov_b64_e32 v[38:39], 0
	v_mov_b64_e32 v[40:41], 0
	v_mov_b64_e32 v[42:43], 0
	v_mov_b64_e32 v[44:45], 0
	v_mov_b64_e32 v[46:47], 0
	v_mov_b64_e32 v[48:49], 0
	v_mov_b64_e32 v[50:51], 0
	v_mov_b64_e32 v[52:53], 0
	v_mov_b64_e32 v[54:55], 0
	v_mov_b64_e32 v[56:57], 0
	v_mov_b64_e32 v[58:59], 0
	v_mov_b64_e32 v[60:61], 0
	v_mov_b64_e32 v[62:63], 0
	v_mov_b64_e32 v[64:65], 0
	v_mov_b64_e32 v[66:67], 0
	v_mov_b64_e32 v[68:69], 0
	v_mov_b64_e32 v[70:71], 0
	v_mov_b64_e32 v[72:73], 0
	v_mov_b64_e32 v[74:75], 0
	v_mov_b64_e32 v[76:77], 0
	v_mov_b64_e32 v[78:79], 0
	v_mov_b64_e32 v[80:81], 0
	v_mov_b64_e32 v[82:83], 0
	v_mov_b64_e32 v[84:85], 0
	v_mov_b64_e32 v[86:87], 0
	v_mov_b64_e32 v[88:89], 0
	v_mov_b64_e32 v[90:91], 0
	v_mov_b64_e32 v[92:93], 0
	v_mov_b64_e32 v[94:95], 0
	v_mov_b64_e32 v[96:97], 0
	v_mov_b64_e32 v[98:99], 0
	v_mov_b64_e32 v[100:101], 0
	v_mov_b64_e32 v[102:103], 0
	v_mov_b64_e32 v[104:105], 0
	v_mov_b64_e32 v[106:107], 0
	v_mov_b64_e32 v[108:109], 0
	v_mov_b64_e32 v[110:111], 0
	v_mov_b64_e32 v[112:113], 0
	v_mov_b64_e32 v[114:115], 0
	v_mov_b64_e32 v[116:117], 0
	v_mov_b64_e32 v[118:119], 0
	v_mov_b64_e32 v[120:121], 0
	v_mov_b64_e32 v[122:123], 0
	v_mov_b64_e32 v[124:125], 0
	v_mov_b64_e32 v[126:127], 0
	v_mov_b64_e32 v[128:129], 0
	v_mov_b64_e32 v[130:131], 0
	v_mov_b64_e32 v[132:133], 0
	v_mov_b64_e32 v[134:135], 0
	v_mov_b64_e32 v[136:137], 0
	v_mov_b64_e32 v[138:139], 0
	v_mov_b64_e32 v[140:141], 0
	v_mov_b64_e32 v[142:143], 0
	v_mov_b64_e32 v[144:145], 0
	v_mov_b64_e32 v[146:147], 0
	v_mov_b64_e32 v[148:149], 0
	v_mov_b64_e32 v[150:151], 0
	v_mov_b64_e32 v[152:153], 0
	v_mov_b64_e32 v[154:155], 0
	v_mov_b64_e32 v[156:157], 0
	v_mov_b64_e32 v[158:159], 0
	s_cmp_eq_u32 s99, 1
	s_cbranch_scc0 .Lue_269
	s_mov_b32 s99, 0
	s_barrier
.Lue_269:
.LBB0_269:
	ds_read_b128 v[16:19], v185
	ds_read_b128 v[24:27], v185 offset:2048
	ds_read_b128 v[20:23], v186
	ds_read_b128 v[28:31], v186 offset:2048
	ds_read_b128 v[0:3], v187
	ds_read_b128 v[8:11], v187 offset:2048
	ds_read_b128 v[4:7], v188
	ds_read_b128 v[12:15], v188 offset:2048
	s_add_u32 s44, s8, 0x100
	s_addc_u32 s45, s9, 0
	s_cmp_eq_u32 s72, 28
	s_cselect_b32 s50, s7, s44
	s_cselect_b32 s51, s1, s45
	s_cselect_b32 s48, s33, s37
	s_cselect_b32 s49, s11, s39
	s_add_u32 s46, s50, 0x80
	s_addc_u32 s47, s51, 0
	ds_read_b128 v[160:163], v189
	ds_read_b128 v[172:175], v189 offset:2048
	ds_read_b128 v[164:167], v190
	ds_read_b128 v[176:179], v190 offset:2048
	ds_read_b128 v[212:215], v189 offset:4096
	ds_read_b128 v[226:229], v189 offset:6144
	ds_read_b128 v[216:219], v190 offset:4096
	ds_read_b128 v[230:233], v190 offset:6144
	s_add_u32 s8, s8, 0x80080
	s_addc_u32 s9, s9, 0
	s_add_i32 m0, s27, 0xc000
	s_nop 0
	global_load_lds_dwordx4 v180, s[8:9]
	s_nop 0
	s_add_i32 m0, s27, 0xe000
	s_nop 0
	global_load_lds_dwordx4 v181, s[8:9]
	s_waitcnt vmcnt(8)
	s_waitcnt lgkmcnt(0)
	s_barrier
	s_setprio 1
	v_mfma_scale_f32_16x16x128_f8f6f4 v[156:159], v[16:23], v[160:167], v[156:159], v182, v182 op_sel_hi:[0,0,0]
	v_mfma_scale_f32_16x16x128_f8f6f4 v[152:155], v[24:31], v[160:167], v[152:155], v182, v182 op_sel_hi:[0,0,0]
	v_mfma_scale_f32_16x16x128_f8f6f4 v[140:143], v[16:23], v[172:179], v[140:143], v182, v182 op_sel_hi:[0,0,0]
	v_mfma_scale_f32_16x16x128_f8f6f4 v[136:139], v[24:31], v[172:179], v[136:139], v182, v182 op_sel_hi:[0,0,0]
	v_mfma_scale_f32_16x16x128_f8f6f4 v[124:127], v[16:23], v[212:219], v[124:127], v182, v182 op_sel_hi:[0,0,0]
	v_mfma_scale_f32_16x16x128_f8f6f4 v[120:123], v[24:31], v[212:219], v[120:123], v182, v182 op_sel_hi:[0,0,0]
	v_mfma_scale_f32_16x16x128_f8f6f4 v[108:111], v[16:23], v[226:233], v[108:111], v182, v182 op_sel_hi:[0,0,0]
	v_mfma_scale_f32_16x16x128_f8f6f4 v[104:107], v[24:31], v[226:233], v[104:107], v182, v182 op_sel_hi:[0,0,0]
	v_mfma_scale_f32_16x16x128_f8f6f4 v[148:151], v[0:7], v[160:167], v[148:151], v182, v182 op_sel_hi:[0,0,0]
	v_mfma_scale_f32_16x16x128_f8f6f4 v[144:147], v[8:15], v[160:167], v[144:147], v182, v182 op_sel_hi:[0,0,0]
	v_mfma_scale_f32_16x16x128_f8f6f4 v[132:135], v[0:7], v[172:179], v[132:135], v182, v182 op_sel_hi:[0,0,0]
	v_mfma_scale_f32_16x16x128_f8f6f4 v[128:131], v[8:15], v[172:179], v[128:131], v182, v182 op_sel_hi:[0,0,0]
	v_mfma_scale_f32_16x16x128_f8f6f4 v[116:119], v[0:7], v[212:219], v[116:119], v182, v182 op_sel_hi:[0,0,0]
	v_mfma_scale_f32_16x16x128_f8f6f4 v[112:115], v[8:15], v[212:219], v[112:115], v182, v182 op_sel_hi:[0,0,0]
	v_mfma_scale_f32_16x16x128_f8f6f4 v[100:103], v[0:7], v[226:233], v[100:103], v182, v182 op_sel_hi:[0,0,0]
	v_mfma_scale_f32_16x16x128_f8f6f4 v[96:99], v[8:15], v[226:233], v[96:99], v182, v182 op_sel_hi:[0,0,0]
	s_setprio 0
	s_barrier
	ds_read_b128 v[160:163], v189 offset:16384
	ds_read_b128 v[172:175], v189 offset:18432
	ds_read_b128 v[164:167], v190 offset:16384
	ds_read_b128 v[176:179], v190 offset:18432
	ds_read_b128 v[212:215], v189 offset:20480
	ds_read_b128 v[226:229], v189 offset:22528
	ds_read_b128 v[216:219], v190 offset:20480
	ds_read_b128 v[230:233], v190 offset:22528
	s_add_i32 m0, s27, 0x10000
	s_nop 0
	global_load_lds_dwordx4 v180, s[48:49]
	s_nop 0
	s_add_i32 m0, s27, 0x12000
	s_nop 0
	global_load_lds_dwordx4 v181, s[48:49]
	s_add_u32 s8, s48, 0x80000
	s_addc_u32 s9, s49, 0
	s_add_i32 m0, s27, 0x14000
	s_nop 0
	global_load_lds_dwordx4 v180, s[8:9]
	s_nop 0
	s_add_i32 m0, s27, 0x16000
	s_nop 0
	global_load_lds_dwordx4 v181, s[8:9]
	s_nop 0
	s_add_i32 m0, s27, 0
	s_nop 0
	global_load_lds_dwordx4 v180, s[50:51]
	s_nop 0
	s_add_i32 m0, s27, 0x2000
	s_nop 0
	global_load_lds_dwordx4 v181, s[50:51]
	s_waitcnt vmcnt(8)
	s_waitcnt lgkmcnt(0)
	s_barrier
	s_setprio 1
	v_mfma_scale_f32_16x16x128_f8f6f4 v[92:95], v[16:23], v[160:167], v[92:95], v182, v182 op_sel_hi:[0,0,0]
	v_mfma_scale_f32_16x16x128_f8f6f4 v[88:91], v[24:31], v[160:167], v[88:91], v182, v182 op_sel_hi:[0,0,0]
	v_mfma_scale_f32_16x16x128_f8f6f4 v[76:79], v[16:23], v[172:179], v[76:79], v182, v182 op_sel_hi:[0,0,0]
	v_mfma_scale_f32_16x16x128_f8f6f4 v[72:75], v[24:31], v[172:179], v[72:75], v182, v182 op_sel_hi:[0,0,0]
	v_mfma_scale_f32_16x16x128_f8f6f4 v[60:63], v[16:23], v[212:219], v[60:63], v182, v182 op_sel_hi:[0,0,0]
	v_mfma_scale_f32_16x16x128_f8f6f4 v[56:59], v[24:31], v[212:219], v[56:59], v182, v182 op_sel_hi:[0,0,0]
	v_mfma_scale_f32_16x16x128_f8f6f4 v[44:47], v[16:23], v[226:233], v[44:47], v182, v182 op_sel_hi:[0,0,0]
	v_mfma_scale_f32_16x16x128_f8f6f4 v[40:43], v[24:31], v[226:233], v[40:43], v182, v182 op_sel_hi:[0,0,0]
	v_mfma_scale_f32_16x16x128_f8f6f4 v[84:87], v[0:7], v[160:167], v[84:87], v182, v182 op_sel_hi:[0,0,0]
	v_mfma_scale_f32_16x16x128_f8f6f4 v[80:83], v[8:15], v[160:167], v[80:83], v182, v182 op_sel_hi:[0,0,0]
	v_mfma_scale_f32_16x16x128_f8f6f4 v[68:71], v[0:7], v[172:179], v[68:71], v182, v182 op_sel_hi:[0,0,0]
	v_mfma_scale_f32_16x16x128_f8f6f4 v[64:67], v[8:15], v[172:179], v[64:67], v182, v182 op_sel_hi:[0,0,0]
	v_mfma_scale_f32_16x16x128_f8f6f4 v[52:55], v[0:7], v[212:219], v[52:55], v182, v182 op_sel_hi:[0,0,0]
	v_mfma_scale_f32_16x16x128_f8f6f4 v[48:51], v[8:15], v[212:219], v[48:51], v182, v182 op_sel_hi:[0,0,0]
	v_mfma_scale_f32_16x16x128_f8f6f4 v[36:39], v[0:7], v[226:233], v[36:39], v182, v182 op_sel_hi:[0,0,0]
	v_mfma_scale_f32_16x16x128_f8f6f4 v[32:35], v[8:15], v[226:233], v[32:35], v182, v182 op_sel_hi:[0,0,0]
	s_setprio 0
	s_barrier
	ds_read_b128 v[0:3], v191
	ds_read_b128 v[8:11], v191 offset:2048
	ds_read_b128 v[4:7], v192
	ds_read_b128 v[12:15], v192 offset:2048
	ds_read_b128 v[16:19], v193
	ds_read_b128 v[24:27], v193 offset:2048
	ds_read_b128 v[20:23], v194
	ds_read_b128 v[28:31], v194 offset:2048
	ds_read_b128 v[160:163], v189 offset:32768
	ds_read_b128 v[172:175], v189 offset:34816
	ds_read_b128 v[164:167], v190 offset:32768
	ds_read_b128 v[176:179], v190 offset:34816
	ds_read_b128 v[212:215], v189 offset:36864
	ds_read_b128 v[226:229], v189 offset:38912
	ds_read_b128 v[216:219], v190 offset:36864
	ds_read_b128 v[230:233], v190 offset:38912
	s_add_u32 s8, s50, 0x80000
	s_addc_u32 s9, s51, 0
	s_add_i32 m0, s27, 0x4000
	s_nop 0
	global_load_lds_dwordx4 v180, s[8:9]
	s_nop 0
	s_add_i32 m0, s27, 0x6000
	s_nop 0
	global_load_lds_dwordx4 v181, s[8:9]
	s_waitcnt vmcnt(8)
	s_waitcnt lgkmcnt(0)
	s_barrier
	s_setprio 1
	v_mfma_scale_f32_16x16x128_f8f6f4 v[156:159], v[0:7], v[160:167], v[156:159], v182, v182 op_sel_hi:[0,0,0]
	v_mfma_scale_f32_16x16x128_f8f6f4 v[152:155], v[8:15], v[160:167], v[152:155], v182, v182 op_sel_hi:[0,0,0]
	v_mfma_scale_f32_16x16x128_f8f6f4 v[140:143], v[0:7], v[172:179], v[140:143], v182, v182 op_sel_hi:[0,0,0]
	v_mfma_scale_f32_16x16x128_f8f6f4 v[136:139], v[8:15], v[172:179], v[136:139], v182, v182 op_sel_hi:[0,0,0]
	v_mfma_scale_f32_16x16x128_f8f6f4 v[124:127], v[0:7], v[212:219], v[124:127], v182, v182 op_sel_hi:[0,0,0]
	v_mfma_scale_f32_16x16x128_f8f6f4 v[120:123], v[8:15], v[212:219], v[120:123], v182, v182 op_sel_hi:[0,0,0]
	v_mfma_scale_f32_16x16x128_f8f6f4 v[108:111], v[0:7], v[226:233], v[108:111], v182, v182 op_sel_hi:[0,0,0]
	v_mfma_scale_f32_16x16x128_f8f6f4 v[104:107], v[8:15], v[226:233], v[104:107], v182, v182 op_sel_hi:[0,0,0]
	v_mfma_scale_f32_16x16x128_f8f6f4 v[148:151], v[16:23], v[160:167], v[148:151], v182, v182 op_sel_hi:[0,0,0]
	v_mfma_scale_f32_16x16x128_f8f6f4 v[144:147], v[24:31], v[160:167], v[144:147], v182, v182 op_sel_hi:[0,0,0]
	v_mfma_scale_f32_16x16x128_f8f6f4 v[132:135], v[16:23], v[172:179], v[132:135], v182, v182 op_sel_hi:[0,0,0]
	v_mfma_scale_f32_16x16x128_f8f6f4 v[128:131], v[24:31], v[172:179], v[128:131], v182, v182 op_sel_hi:[0,0,0]
	v_mfma_scale_f32_16x16x128_f8f6f4 v[116:119], v[16:23], v[212:219], v[116:119], v182, v182 op_sel_hi:[0,0,0]
	v_mfma_scale_f32_16x16x128_f8f6f4 v[112:115], v[24:31], v[212:219], v[112:115], v182, v182 op_sel_hi:[0,0,0]
	v_mfma_scale_f32_16x16x128_f8f6f4 v[100:103], v[16:23], v[226:233], v[100:103], v182, v182 op_sel_hi:[0,0,0]
	v_mfma_scale_f32_16x16x128_f8f6f4 v[96:99], v[24:31], v[226:233], v[96:99], v182, v182 op_sel_hi:[0,0,0]
	s_setprio 0
	s_barrier
	s_add_u32 s8, s48, 0x80
	ds_read_b128 v[160:163], v189 offset:49152
	ds_read_b128 v[172:175], v189 offset:51200
	ds_read_b128 v[164:167], v190 offset:49152
	ds_read_b128 v[176:179], v190 offset:51200
	ds_read_b128 v[212:215], v189 offset:53248
	ds_read_b128 v[226:229], v189 offset:55296
	ds_read_b128 v[216:219], v190 offset:53248
	ds_read_b128 v[230:233], v190 offset:55296
	s_addc_u32 s9, s49, 0
	s_add_i32 m0, s27, 0x18000
	s_nop 0
	global_load_lds_dwordx4 v180, s[8:9]
	s_nop 0
	s_add_i32 m0, s27, 0x1a000
	s_nop 0
	global_load_lds_dwordx4 v181, s[8:9]
	s_add_u32 s8, s48, 0x80080
	s_addc_u32 s9, s49, 0
	s_add_i32 m0, s27, 0x1c000
	s_nop 0
	global_load_lds_dwordx4 v180, s[8:9]
	s_nop 0
	s_add_i32 m0, s27, 0x1e000
	s_nop 0
	global_load_lds_dwordx4 v181, s[8:9]
	s_nop 0
	s_add_i32 m0, s27, 0x8000
	s_nop 0
	global_load_lds_dwordx4 v180, s[46:47]
	s_nop 0
	s_add_i32 m0, s27, 0xa000
	s_nop 0
	global_load_lds_dwordx4 v181, s[46:47]
	s_waitcnt vmcnt(8)
	s_waitcnt lgkmcnt(0)
	s_barrier
	s_setprio 1
	v_mfma_scale_f32_16x16x128_f8f6f4 v[92:95], v[0:7], v[160:167], v[92:95], v182, v182 op_sel_hi:[0,0,0]
	v_mfma_scale_f32_16x16x128_f8f6f4 v[88:91], v[8:15], v[160:167], v[88:91], v182, v182 op_sel_hi:[0,0,0]
	v_mfma_scale_f32_16x16x128_f8f6f4 v[76:79], v[0:7], v[172:179], v[76:79], v182, v182 op_sel_hi:[0,0,0]
	v_mfma_scale_f32_16x16x128_f8f6f4 v[72:75], v[8:15], v[172:179], v[72:75], v182, v182 op_sel_hi:[0,0,0]
	v_mfma_scale_f32_16x16x128_f8f6f4 v[60:63], v[0:7], v[212:219], v[60:63], v182, v182 op_sel_hi:[0,0,0]
	v_mfma_scale_f32_16x16x128_f8f6f4 v[56:59], v[8:15], v[212:219], v[56:59], v182, v182 op_sel_hi:[0,0,0]
	v_mfma_scale_f32_16x16x128_f8f6f4 v[44:47], v[0:7], v[226:233], v[44:47], v182, v182 op_sel_hi:[0,0,0]
	v_mfma_scale_f32_16x16x128_f8f6f4 v[40:43], v[8:15], v[226:233], v[40:43], v182, v182 op_sel_hi:[0,0,0]
	v_mfma_scale_f32_16x16x128_f8f6f4 v[84:87], v[16:23], v[160:167], v[84:87], v182, v182 op_sel_hi:[0,0,0]
	v_mfma_scale_f32_16x16x128_f8f6f4 v[80:83], v[24:31], v[160:167], v[80:83], v182, v182 op_sel_hi:[0,0,0]
	v_mfma_scale_f32_16x16x128_f8f6f4 v[68:71], v[16:23], v[172:179], v[68:71], v182, v182 op_sel_hi:[0,0,0]
	v_mfma_scale_f32_16x16x128_f8f6f4 v[64:67], v[24:31], v[172:179], v[64:67], v182, v182 op_sel_hi:[0,0,0]
	v_mfma_scale_f32_16x16x128_f8f6f4 v[52:55], v[16:23], v[212:219], v[52:55], v182, v182 op_sel_hi:[0,0,0]
	v_mfma_scale_f32_16x16x128_f8f6f4 v[48:51], v[24:31], v[212:219], v[48:51], v182, v182 op_sel_hi:[0,0,0]
	v_mfma_scale_f32_16x16x128_f8f6f4 v[36:39], v[16:23], v[226:233], v[36:39], v182, v182 op_sel_hi:[0,0,0]
	v_mfma_scale_f32_16x16x128_f8f6f4 v[32:35], v[24:31], v[226:233], v[32:35], v182, v182 op_sel_hi:[0,0,0]
	s_setprio 0
	s_barrier
	s_add_i32 s72, s72, 2
	s_add_u32 s37, s37, 0x100
	s_addc_u32 s39, s39, 0
	s_cmp_gt_u32 s72, 29
	s_mov_b64 s[8:9], s[44:45]
	s_cbranch_scc0 .LBB0_269
	s_and_b64 vcc, exec, s[24:25]
	s_cbranch_vccz .LBB0_272
	s_barrier

.LBB0_319:
	s_andn2_b64 vcc, exec, s[18:19]
	s_cbranch_vccnz .LBB0_264
	s_mov_b32 s99, 1
	s_branch .LBB0_264

.LBB0_338:
	s_ashr_i32 s27, s26, 31
	s_lshl_b64 s[28:29], s[26:27], 20
	s_add_u32 s28, s47, s28
	s_addc_u32 s29, s48, s29
	s_and_b64 s[30:31], s[2:3], exec
	s_cselect_b32 s27, s29, s39
	s_cselect_b32 s58, s28, s38
	s_ashr_i32 s25, s24, 31
	s_lshl_b64 s[30:31], s[24:25], 20
	s_add_u32 s30, s33, s30
	s_addc_u32 s31, s46, s31
	s_and_b64 s[40:41], s[2:3], exec
	s_cselect_b32 s25, s31, s37
	s_cselect_b32 s59, s30, s36
	s_add_u32 s60, s36, 0x100
	s_addc_u32 s61, s37, 0
	s_mov_b32 s62, -2
	s_waitcnt vmcnt(24)
	s_waitcnt vmcnt(16)
	s_waitcnt vmcnt(15)
	s_waitcnt vmcnt(14)
	s_waitcnt vmcnt(13)
	s_waitcnt vmcnt(12)
	s_waitcnt vmcnt(11)
	s_waitcnt vmcnt(10)
	s_waitcnt vmcnt(9)
	s_waitcnt vmcnt(8)
	v_mov_b64_e32 v[0:1], 0
	v_mov_b64_e32 v[2:3], 0
	v_mov_b64_e32 v[4:5], 0
	v_mov_b64_e32 v[6:7], 0
	v_mov_b64_e32 v[8:9], 0
	v_mov_b64_e32 v[10:11], 0
	v_mov_b64_e32 v[12:13], 0
	v_mov_b64_e32 v[14:15], 0
	v_mov_b64_e32 v[16:17], 0
	v_mov_b64_e32 v[18:19], 0
	v_mov_b64_e32 v[20:21], 0
	v_mov_b64_e32 v[22:23], 0
	v_mov_b64_e32 v[24:25], 0
	v_mov_b64_e32 v[26:27], 0
	v_mov_b64_e32 v[28:29], 0
	v_mov_b64_e32 v[30:31], 0
	v_mov_b64_e32 v[32:33], 0
	v_mov_b64_e32 v[34:35], 0
	v_mov_b64_e32 v[36:37], 0
	v_mov_b64_e32 v[38:39], 0
	v_mov_b64_e32 v[40:41], 0
	v_mov_b64_e32 v[42:43], 0
	v_mov_b64_e32 v[44:45], 0
	v_mov_b64_e32 v[46:47], 0
	v_mov_b64_e32 v[48:49], 0
	v_mov_b64_e32 v[50:51], 0
	v_mov_b64_e32 v[52:53], 0
	v_mov_b64_e32 v[54:55], 0
	v_mov_b64_e32 v[56:57], 0
	v_mov_b64_e32 v[58:59], 0
	v_mov_b64_e32 v[60:61], 0
	v_mov_b64_e32 v[62:63], 0
	v_mov_b64_e32 v[64:65], 0
	v_mov_b64_e32 v[66:67], 0
	v_mov_b64_e32 v[68:69], 0
	v_mov_b64_e32 v[70:71], 0
	v_mov_b64_e32 v[72:73], 0
	v_mov_b64_e32 v[74:75], 0
	v_mov_b64_e32 v[76:77], 0
	v_mov_b64_e32 v[78:79], 0
	v_mov_b64_e32 v[80:81], 0
	v_mov_b64_e32 v[82:83], 0
	v_mov_b64_e32 v[84:85], 0
	v_mov_b64_e32 v[86:87], 0
	v_mov_b64_e32 v[88:89], 0
	v_mov_b64_e32 v[90:91], 0
	v_mov_b64_e32 v[92:93], 0
	v_mov_b64_e32 v[94:95], 0
	v_mov_b64_e32 v[96:97], 0
	v_mov_b64_e32 v[98:99], 0
	v_mov_b64_e32 v[100:101], 0
	v_mov_b64_e32 v[102:103], 0
	v_mov_b64_e32 v[104:105], 0
	v_mov_b64_e32 v[106:107], 0
	v_mov_b64_e32 v[108:109], 0
	v_mov_b64_e32 v[110:111], 0
	v_mov_b64_e32 v[112:113], 0
	v_mov_b64_e32 v[114:115], 0
	v_mov_b64_e32 v[116:117], 0
	v_mov_b64_e32 v[118:119], 0
	v_mov_b64_e32 v[120:121], 0
	v_mov_b64_e32 v[122:123], 0
	v_mov_b64_e32 v[124:125], 0
	v_mov_b64_e32 v[126:127], 0
	s_cmp_eq_u32 s99, 1
	s_cbranch_scc0 .Lue_339
	s_mov_b32 s99, 0
	s_barrier
.Lue_339:
.LBB0_339:
	ds_read_b128 v[156:159], v166
	ds_read_b128 v[152:155], v166 offset:1024
	ds_read_b128 v[148:151], v166 offset:2048
	ds_read_b128 v[144:147], v166 offset:3072
	ds_read_b128 v[140:143], v167
	ds_read_b128 v[136:139], v167 offset:1024
	ds_read_b128 v[132:135], v167 offset:2048
	ds_read_b128 v[128:131], v167 offset:3072
	s_add_u32 s36, s38, 0x100
	s_addc_u32 s37, s39, 0
	s_cmp_eq_u32 s62, 28
	s_cselect_b32 s44, s58, s36
	s_cselect_b32 s45, s27, s37
	s_cselect_b32 s42, s59, s60
	s_cselect_b32 s43, s25, s61
	s_add_u32 s40, s44, 0x80
	s_addc_u32 s41, s45, 0
	ds_read_b128 v[172:175], v168
	ds_read_b128 v[176:179], v168 offset:1024
	ds_read_b128 v[180:183], v168 offset:2048
	ds_read_b128 v[184:187], v168 offset:3072
	ds_read_b128 v[188:191], v168 offset:4096
	ds_read_b128 v[192:195], v168 offset:5120
	ds_read_b128 v[196:199], v168 offset:6144
	ds_read_b128 v[200:203], v168 offset:7168
	s_add_u32 s38, s38, 0x80080
	s_addc_u32 s39, s39, 0
	s_add_i32 m0, s1, 0xc000
	s_nop 0
	global_load_lds_dwordx4 v164, s[38:39]
	s_nop 0
	s_add_i32 m0, s1, 0xe000
	s_nop 0
	global_load_lds_dwordx4 v165, s[38:39]
	s_waitcnt vmcnt(8)
	s_waitcnt lgkmcnt(0)
	s_barrier
	s_setprio 1
	v_mfma_i32_16x16x64_i8 v[124:127], v[156:159], v[172:175], v[124:127]
	v_mfma_i32_16x16x64_i8 v[124:127], v[152:155], v[176:179], v[124:127]
	v_mfma_i32_16x16x64_i8 v[120:123], v[148:151], v[172:175], v[120:123]
	s_nop 0
	v_mfma_i32_16x16x64_i8 v[120:123], v[144:147], v[176:179], v[120:123]
	v_mfma_i32_16x16x64_i8 v[108:111], v[156:159], v[180:183], v[108:111]
	v_mfma_i32_16x16x64_i8 v[108:111], v[152:155], v[184:187], v[108:111]
	v_mfma_i32_16x16x64_i8 v[104:107], v[148:151], v[180:183], v[104:107]
	s_nop 0
	v_mfma_i32_16x16x64_i8 v[104:107], v[144:147], v[184:187], v[104:107]
	v_mfma_i32_16x16x64_i8 v[92:95], v[156:159], v[188:191], v[92:95]
	v_mfma_i32_16x16x64_i8 v[92:95], v[152:155], v[192:195], v[92:95]
	v_mfma_i32_16x16x64_i8 v[88:91], v[148:151], v[188:191], v[88:91]
	s_nop 0
	v_mfma_i32_16x16x64_i8 v[88:91], v[144:147], v[192:195], v[88:91]
	v_mfma_i32_16x16x64_i8 v[76:79], v[156:159], v[196:199], v[76:79]
	v_mfma_i32_16x16x64_i8 v[76:79], v[152:155], v[200:203], v[76:79]
	v_mfma_i32_16x16x64_i8 v[72:75], v[148:151], v[196:199], v[72:75]
	s_nop 0
	v_mfma_i32_16x16x64_i8 v[72:75], v[144:147], v[200:203], v[72:75]
	v_mfma_i32_16x16x64_i8 v[116:119], v[140:143], v[172:175], v[116:119]
	s_nop 0
	v_mfma_i32_16x16x64_i8 v[116:119], v[136:139], v[176:179], v[116:119]
	v_mfma_i32_16x16x64_i8 v[112:115], v[132:135], v[172:175], v[112:115]
	s_nop 0
	v_mfma_i32_16x16x64_i8 v[112:115], v[128:131], v[176:179], v[112:115]
	v_mfma_i32_16x16x64_i8 v[100:103], v[140:143], v[180:183], v[100:103]
	s_nop 0
	v_mfma_i32_16x16x64_i8 v[100:103], v[136:139], v[184:187], v[100:103]
	v_mfma_i32_16x16x64_i8 v[96:99], v[132:135], v[180:183], v[96:99]
	s_nop 0
	v_mfma_i32_16x16x64_i8 v[96:99], v[128:131], v[184:187], v[96:99]
	v_mfma_i32_16x16x64_i8 v[84:87], v[140:143], v[188:191], v[84:87]
	s_nop 0
	v_mfma_i32_16x16x64_i8 v[84:87], v[136:139], v[192:195], v[84:87]
	v_mfma_i32_16x16x64_i8 v[80:83], v[132:135], v[188:191], v[80:83]
	s_nop 0
	v_mfma_i32_16x16x64_i8 v[80:83], v[128:131], v[192:195], v[80:83]
	v_mfma_i32_16x16x64_i8 v[68:71], v[140:143], v[196:199], v[68:71]
	s_nop 0
	v_mfma_i32_16x16x64_i8 v[68:71], v[136:139], v[200:203], v[68:71]
	v_mfma_i32_16x16x64_i8 v[64:67], v[132:135], v[196:199], v[64:67]
	s_nop 0
	v_mfma_i32_16x16x64_i8 v[64:67], v[128:131], v[200:203], v[64:67]
	s_setprio 0
	s_barrier
	ds_read_b128 v[172:175], v168 offset:16384
	ds_read_b128 v[176:179], v168 offset:17408
	ds_read_b128 v[180:183], v168 offset:18432
	ds_read_b128 v[184:187], v168 offset:19456
	ds_read_b128 v[188:191], v168 offset:20480
	ds_read_b128 v[192:195], v168 offset:21504
	ds_read_b128 v[196:199], v168 offset:22528
	ds_read_b128 v[200:203], v168 offset:23552
	s_add_i32 m0, s1, 0x10000
	s_nop 0
	global_load_lds_dwordx4 v164, s[42:43]
	s_nop 0
	s_add_i32 m0, s1, 0x12000
	s_nop 0
	global_load_lds_dwordx4 v165, s[42:43]
	s_add_u32 s38, s42, 0x80000
	s_addc_u32 s39, s43, 0
	s_add_i32 m0, s1, 0x14000
	s_nop 0
	global_load_lds_dwordx4 v164, s[38:39]
	s_nop 0
	s_add_i32 m0, s1, 0x16000
	s_nop 0
	global_load_lds_dwordx4 v165, s[38:39]
	s_nop 0
	s_add_i32 m0, s1, 0
	s_nop 0
	global_load_lds_dwordx4 v164, s[44:45]
	s_nop 0
	s_add_i32 m0, s1, 0x2000
	s_nop 0
	global_load_lds_dwordx4 v165, s[44:45]
	s_waitcnt vmcnt(8)
	s_waitcnt lgkmcnt(0)
	s_barrier
	s_setprio 1
	v_mfma_i32_16x16x64_i8 v[60:63], v[156:159], v[172:175], v[60:63]
	v_mfma_i32_16x16x64_i8 v[60:63], v[152:155], v[176:179], v[60:63]
	v_mfma_i32_16x16x64_i8 v[56:59], v[148:151], v[172:175], v[56:59]
	s_nop 0
	v_mfma_i32_16x16x64_i8 v[56:59], v[144:147], v[176:179], v[56:59]
	v_mfma_i32_16x16x64_i8 v[44:47], v[156:159], v[180:183], v[44:47]
	v_mfma_i32_16x16x64_i8 v[44:47], v[152:155], v[184:187], v[44:47]
	v_mfma_i32_16x16x64_i8 v[40:43], v[148:151], v[180:183], v[40:43]
	s_nop 0
	v_mfma_i32_16x16x64_i8 v[40:43], v[144:147], v[184:187], v[40:43]
	v_mfma_i32_16x16x64_i8 v[28:31], v[156:159], v[188:191], v[28:31]
	v_mfma_i32_16x16x64_i8 v[28:31], v[152:155], v[192:195], v[28:31]
	v_mfma_i32_16x16x64_i8 v[24:27], v[148:151], v[188:191], v[24:27]
	s_nop 0
	v_mfma_i32_16x16x64_i8 v[24:27], v[144:147], v[192:195], v[24:27]
	v_mfma_i32_16x16x64_i8 v[12:15], v[156:159], v[196:199], v[12:15]
	v_mfma_i32_16x16x64_i8 v[12:15], v[152:155], v[200:203], v[12:15]
	v_mfma_i32_16x16x64_i8 v[8:11], v[148:151], v[196:199], v[8:11]
	s_nop 0
	v_mfma_i32_16x16x64_i8 v[8:11], v[144:147], v[200:203], v[8:11]
	v_mfma_i32_16x16x64_i8 v[52:55], v[140:143], v[172:175], v[52:55]
	s_nop 0
	v_mfma_i32_16x16x64_i8 v[52:55], v[136:139], v[176:179], v[52:55]
	v_mfma_i32_16x16x64_i8 v[48:51], v[132:135], v[172:175], v[48:51]
	s_nop 0
	v_mfma_i32_16x16x64_i8 v[48:51], v[128:131], v[176:179], v[48:51]
	v_mfma_i32_16x16x64_i8 v[36:39], v[140:143], v[180:183], v[36:39]
	s_nop 0
	v_mfma_i32_16x16x64_i8 v[36:39], v[136:139], v[184:187], v[36:39]
	v_mfma_i32_16x16x64_i8 v[32:35], v[132:135], v[180:183], v[32:35]
	s_nop 0
	v_mfma_i32_16x16x64_i8 v[32:35], v[128:131], v[184:187], v[32:35]
	v_mfma_i32_16x16x64_i8 v[20:23], v[140:143], v[188:191], v[20:23]
	s_nop 0
	v_mfma_i32_16x16x64_i8 v[20:23], v[136:139], v[192:195], v[20:23]
	v_mfma_i32_16x16x64_i8 v[16:19], v[132:135], v[188:191], v[16:19]
	s_nop 0
	v_mfma_i32_16x16x64_i8 v[16:19], v[128:131], v[192:195], v[16:19]
	v_mfma_i32_16x16x64_i8 v[4:7], v[140:143], v[196:199], v[4:7]
	s_nop 0
	v_mfma_i32_16x16x64_i8 v[4:7], v[136:139], v[200:203], v[4:7]
	v_mfma_i32_16x16x64_i8 v[0:3], v[132:135], v[196:199], v[0:3]
	s_nop 0
	v_mfma_i32_16x16x64_i8 v[0:3], v[128:131], v[200:203], v[0:3]
	s_setprio 0
	s_barrier
	ds_read_b128 v[128:131], v169
	ds_read_b128 v[132:135], v169 offset:1024
	ds_read_b128 v[136:139], v169 offset:2048
	ds_read_b128 v[140:143], v169 offset:3072
	ds_read_b128 v[144:147], v170
	ds_read_b128 v[148:151], v170 offset:1024
	ds_read_b128 v[152:155], v170 offset:2048
	ds_read_b128 v[156:159], v170 offset:3072
	ds_read_b128 v[172:175], v168 offset:32768
	ds_read_b128 v[176:179], v168 offset:33792
	ds_read_b128 v[180:183], v168 offset:34816
	ds_read_b128 v[184:187], v168 offset:35840
	ds_read_b128 v[188:191], v168 offset:36864
	ds_read_b128 v[192:195], v168 offset:37888
	ds_read_b128 v[196:199], v168 offset:38912
	ds_read_b128 v[200:203], v168 offset:39936
	s_add_u32 s38, s44, 0x80000
	s_addc_u32 s39, s45, 0
	s_add_i32 m0, s1, 0x4000
	s_nop 0
	global_load_lds_dwordx4 v164, s[38:39]
	s_nop 0
	s_add_i32 m0, s1, 0x6000
	s_nop 0
	global_load_lds_dwordx4 v165, s[38:39]
	s_waitcnt vmcnt(8)
	s_waitcnt lgkmcnt(0)
	s_barrier
	s_setprio 1
	v_mfma_i32_16x16x64_i8 v[124:127], v[128:131], v[172:175], v[124:127]
	v_mfma_i32_16x16x64_i8 v[124:127], v[132:135], v[176:179], v[124:127]
	v_mfma_i32_16x16x64_i8 v[120:123], v[136:139], v[172:175], v[120:123]
	s_nop 0
	v_mfma_i32_16x16x64_i8 v[120:123], v[140:143], v[176:179], v[120:123]
	v_mfma_i32_16x16x64_i8 v[108:111], v[128:131], v[180:183], v[108:111]
	v_mfma_i32_16x16x64_i8 v[108:111], v[132:135], v[184:187], v[108:111]
	v_mfma_i32_16x16x64_i8 v[104:107], v[136:139], v[180:183], v[104:107]
	s_nop 0
	v_mfma_i32_16x16x64_i8 v[104:107], v[140:143], v[184:187], v[104:107]
	v_mfma_i32_16x16x64_i8 v[92:95], v[128:131], v[188:191], v[92:95]
	v_mfma_i32_16x16x64_i8 v[92:95], v[132:135], v[192:195], v[92:95]
	v_mfma_i32_16x16x64_i8 v[88:91], v[136:139], v[188:191], v[88:91]
	s_nop 0
	v_mfma_i32_16x16x64_i8 v[88:91], v[140:143], v[192:195], v[88:91]
	v_mfma_i32_16x16x64_i8 v[76:79], v[128:131], v[196:199], v[76:79]
	v_mfma_i32_16x16x64_i8 v[76:79], v[132:135], v[200:203], v[76:79]
	v_mfma_i32_16x16x64_i8 v[72:75], v[136:139], v[196:199], v[72:75]
	s_nop 0
	v_mfma_i32_16x16x64_i8 v[72:75], v[140:143], v[200:203], v[72:75]
	v_mfma_i32_16x16x64_i8 v[116:119], v[144:147], v[172:175], v[116:119]
	s_nop 0
	v_mfma_i32_16x16x64_i8 v[116:119], v[148:151], v[176:179], v[116:119]
	v_mfma_i32_16x16x64_i8 v[112:115], v[152:155], v[172:175], v[112:115]
	s_nop 0
	v_mfma_i32_16x16x64_i8 v[112:115], v[156:159], v[176:179], v[112:115]
	v_mfma_i32_16x16x64_i8 v[100:103], v[144:147], v[180:183], v[100:103]
	s_nop 0
	v_mfma_i32_16x16x64_i8 v[100:103], v[148:151], v[184:187], v[100:103]
	v_mfma_i32_16x16x64_i8 v[96:99], v[152:155], v[180:183], v[96:99]
	s_nop 0
	v_mfma_i32_16x16x64_i8 v[96:99], v[156:159], v[184:187], v[96:99]
	v_mfma_i32_16x16x64_i8 v[84:87], v[144:147], v[188:191], v[84:87]
	s_nop 0
	v_mfma_i32_16x16x64_i8 v[84:87], v[148:151], v[192:195], v[84:87]
	v_mfma_i32_16x16x64_i8 v[80:83], v[152:155], v[188:191], v[80:83]
	s_nop 0
	v_mfma_i32_16x16x64_i8 v[80:83], v[156:159], v[192:195], v[80:83]
	v_mfma_i32_16x16x64_i8 v[68:71], v[144:147], v[196:199], v[68:71]
	s_nop 0
	v_mfma_i32_16x16x64_i8 v[68:71], v[148:151], v[200:203], v[68:71]
	v_mfma_i32_16x16x64_i8 v[64:67], v[152:155], v[196:199], v[64:67]
	s_nop 0
	v_mfma_i32_16x16x64_i8 v[64:67], v[156:159], v[200:203], v[64:67]
	s_setprio 0
	s_barrier
	s_add_u32 s38, s42, 0x80
	s_addc_u32 s39, s43, 0
	ds_read_b128 v[172:175], v168 offset:49152
	ds_read_b128 v[176:179], v168 offset:50176
	ds_read_b128 v[180:183], v168 offset:51200
	ds_read_b128 v[184:187], v168 offset:52224
	ds_read_b128 v[188:191], v168 offset:53248
	ds_read_b128 v[192:195], v168 offset:54272
	ds_read_b128 v[196:199], v168 offset:55296
	ds_read_b128 v[200:203], v168 offset:56320
	s_add_i32 m0, s1, 0x18000
	s_nop 0
	global_load_lds_dwordx4 v164, s[38:39]
	s_nop 0
	s_add_i32 m0, s1, 0x1a000
	s_nop 0
	global_load_lds_dwordx4 v165, s[38:39]
	s_add_u32 s38, s42, 0x80080
	s_addc_u32 s39, s43, 0
	s_add_i32 m0, s1, 0x1c000
	s_nop 0
	global_load_lds_dwordx4 v164, s[38:39]
	s_nop 0
	s_add_i32 m0, s1, 0x1e000
	s_nop 0
	global_load_lds_dwordx4 v165, s[38:39]
	s_nop 0
	s_add_i32 m0, s1, 0x8000
	s_nop 0
	global_load_lds_dwordx4 v164, s[40:41]
	s_nop 0
	s_add_i32 m0, s1, 0xa000
	s_nop 0
	global_load_lds_dwordx4 v165, s[40:41]
	s_waitcnt vmcnt(8)
	s_waitcnt lgkmcnt(0)
	s_barrier
	s_setprio 1
	v_mfma_i32_16x16x64_i8 v[60:63], v[128:131], v[172:175], v[60:63]
	v_mfma_i32_16x16x64_i8 v[60:63], v[132:135], v[176:179], v[60:63]
	v_mfma_i32_16x16x64_i8 v[56:59], v[136:139], v[172:175], v[56:59]
	s_nop 0
	v_mfma_i32_16x16x64_i8 v[56:59], v[140:143], v[176:179], v[56:59]
	v_mfma_i32_16x16x64_i8 v[44:47], v[128:131], v[180:183], v[44:47]
	v_mfma_i32_16x16x64_i8 v[44:47], v[132:135], v[184:187], v[44:47]
	v_mfma_i32_16x16x64_i8 v[40:43], v[136:139], v[180:183], v[40:43]
	s_nop 0
	v_mfma_i32_16x16x64_i8 v[40:43], v[140:143], v[184:187], v[40:43]
	v_mfma_i32_16x16x64_i8 v[28:31], v[128:131], v[188:191], v[28:31]
	v_mfma_i32_16x16x64_i8 v[28:31], v[132:135], v[192:195], v[28:31]
	v_mfma_i32_16x16x64_i8 v[24:27], v[136:139], v[188:191], v[24:27]
	s_nop 0
	v_mfma_i32_16x16x64_i8 v[24:27], v[140:143], v[192:195], v[24:27]
	v_mfma_i32_16x16x64_i8 v[12:15], v[128:131], v[196:199], v[12:15]
	v_mfma_i32_16x16x64_i8 v[12:15], v[132:135], v[200:203], v[12:15]
	v_mfma_i32_16x16x64_i8 v[8:11], v[136:139], v[196:199], v[8:11]
	s_nop 0
	v_mfma_i32_16x16x64_i8 v[8:11], v[140:143], v[200:203], v[8:11]
	v_mfma_i32_16x16x64_i8 v[52:55], v[144:147], v[172:175], v[52:55]
	s_nop 0
	v_mfma_i32_16x16x64_i8 v[52:55], v[148:151], v[176:179], v[52:55]
	v_mfma_i32_16x16x64_i8 v[48:51], v[152:155], v[172:175], v[48:51]
	s_nop 0
	v_mfma_i32_16x16x64_i8 v[48:51], v[156:159], v[176:179], v[48:51]
	v_mfma_i32_16x16x64_i8 v[36:39], v[144:147], v[180:183], v[36:39]
	s_nop 0
	v_mfma_i32_16x16x64_i8 v[36:39], v[148:151], v[184:187], v[36:39]
	v_mfma_i32_16x16x64_i8 v[32:35], v[152:155], v[180:183], v[32:35]
	s_nop 0
	v_mfma_i32_16x16x64_i8 v[32:35], v[156:159], v[184:187], v[32:35]
	v_mfma_i32_16x16x64_i8 v[20:23], v[144:147], v[188:191], v[20:23]
	s_nop 0
	v_mfma_i32_16x16x64_i8 v[20:23], v[148:151], v[192:195], v[20:23]
	v_mfma_i32_16x16x64_i8 v[16:19], v[152:155], v[188:191], v[16:19]
	s_nop 0
	v_mfma_i32_16x16x64_i8 v[16:19], v[156:159], v[192:195], v[16:19]
	v_mfma_i32_16x16x64_i8 v[4:7], v[144:147], v[196:199], v[4:7]
	s_nop 0
	v_mfma_i32_16x16x64_i8 v[4:7], v[148:151], v[200:203], v[4:7]
	v_mfma_i32_16x16x64_i8 v[0:3], v[152:155], v[196:199], v[0:3]
	s_nop 0
	v_mfma_i32_16x16x64_i8 v[0:3], v[156:159], v[200:203], v[0:3]
	s_setprio 0
	s_barrier
	s_add_i32 s62, s62, 2
	s_add_u32 s60, s60, 0x100
	s_addc_u32 s61, s61, 0
	s_cmp_gt_u32 s62, 29
	s_mov_b64 s[38:39], s[36:37]
	s_cbranch_scc0 .LBB0_339
	s_and_b64 vcc, exec, s[14:15]
	s_cbranch_vccz .LBB0_342
	s_barrier
.LBB0_342:
	v_mov_b32_e32 v132, v223
	s_lshl_b32 s0, s57, 8
	v_ashrrev_i32_e32 v128, 1, v132
	s_or_b32 s0, s0, s49
	v_and_b32_e32 v128, -8, v128
	v_add_u32_e32 v130, s0, v128
	s_lshl_b32 s0, s34, 8
	s_add_i32 s0, s0, s35
	v_ashrrev_i32_e32 v131, 31, v130
	v_and_or_b32 v134, v132, 15, s0
	v_lshl_add_u64 v[128:129], v[130:131], 2, s[12:13]
	v_ashrrev_i32_e32 v135, 31, v134
	global_load_dwordx4 v[136:139], v[128:129], off offset:16
	global_load_dwordx4 v[140:143], v[128:129], off
	global_load_dwordx4 v[144:147], v[128:129], off offset:528
	global_load_dwordx4 v[148:151], v[128:129], off offset:512
	v_lshl_add_u64 v[128:129], v[134:135], 2, s[10:11]
	global_load_dword v152, v[128:129], off
	v_cvt_f32_i32_e32 v155, v125
	v_cvt_f32_i32_e32 v154, v124
	v_cvt_f32_i32_e32 v157, v127
	v_cvt_f32_i32_e32 v156, v126
	v_cvt_f32_i32_e32 v159, v121
	v_cvt_f32_i32_e32 v158, v120
	v_cvt_f32_i32_e32 v173, v123
	v_cvt_f32_i32_e32 v172, v122
	v_cvt_f32_i32_e32 v179, v113
	v_cvt_f32_i32_e32 v178, v112
	v_lshlrev_b64 v[112:113], 12, v[134:135]
	v_cvt_f32_i32_e32 v175, v117
	v_cvt_f32_i32_e32 v174, v116
	v_cvt_f32_i32_e32 v177, v119
	v_cvt_f32_i32_e32 v176, v118
	v_cvt_f32_i32_e32 v181, v115
	v_cvt_f32_i32_e32 v180, v114
	v_lshl_add_u64 v[112:113], s[8:9], 0, v[112:113]
	v_lshlrev_b64 v[132:133], 1, v[130:131]
	v_lshl_add_u64 v[130:131], v[112:113], 0, v[132:133]
	v_or_b32_e32 v182, 16, v134
	v_ashrrev_i32_e32 v183, 31, v182
	v_lshl_add_u64 v[184:185], v[182:183], 2, s[10:11]
	v_cvt_f32_i32_e32 v109, v109
	v_cvt_f32_i32_e32 v108, v108
	v_cvt_f32_i32_e32 v111, v111
	v_cvt_f32_i32_e32 v110, v110
	v_cvt_f32_i32_e32 v105, v105
	v_cvt_f32_i32_e32 v104, v104
	v_cvt_f32_i32_e32 v107, v107
	v_cvt_f32_i32_e32 v106, v106
	v_cvt_f32_i32_e32 v101, v101
	v_cvt_f32_i32_e32 v100, v100
	v_cvt_f32_i32_e32 v103, v103
	v_cvt_f32_i32_e32 v102, v102
	v_cvt_f32_i32_e32 v97, v97
	v_cvt_f32_i32_e32 v96, v96
	v_cvt_f32_i32_e32 v99, v99
	v_cvt_f32_i32_e32 v98, v98
	v_cvt_f32_i32_e32 v93, v93
	v_cvt_f32_i32_e32 v92, v92
	v_cvt_f32_i32_e32 v95, v95
	v_cvt_f32_i32_e32 v94, v94
	v_cvt_f32_i32_e32 v89, v89
	v_cvt_f32_i32_e32 v88, v88
	v_cvt_f32_i32_e32 v91, v91
	v_cvt_f32_i32_e32 v90, v90
	v_cvt_f32_i32_e32 v85, v85
	v_cvt_f32_i32_e32 v84, v84
	v_cvt_f32_i32_e32 v87, v87
	v_cvt_f32_i32_e32 v86, v86
	v_cvt_f32_i32_e32 v81, v81
	v_cvt_f32_i32_e32 v80, v80
	v_cvt_f32_i32_e32 v83, v83
	v_cvt_f32_i32_e32 v82, v82
	v_cvt_f32_i32_e32 v77, v77
	v_cvt_f32_i32_e32 v76, v76
	v_cvt_f32_i32_e32 v79, v79
	v_cvt_f32_i32_e32 v78, v78
	v_cvt_f32_i32_e32 v73, v73
	v_cvt_f32_i32_e32 v72, v72
	v_cvt_f32_i32_e32 v75, v75
	v_cvt_f32_i32_e32 v74, v74
	v_cvt_f32_i32_e32 v69, v69
	v_cvt_f32_i32_e32 v68, v68
	v_cvt_f32_i32_e32 v71, v71
	v_cvt_f32_i32_e32 v70, v70
	v_cvt_f32_i32_e32 v65, v65
	v_cvt_f32_i32_e32 v64, v64
	v_cvt_f32_i32_e32 v67, v67
	v_cvt_f32_i32_e32 v66, v66
	v_cvt_f32_i32_e32 v61, v61
	v_cvt_f32_i32_e32 v60, v60
	v_cvt_f32_i32_e32 v63, v63
	v_cvt_f32_i32_e32 v62, v62
	s_waitcnt vmcnt(4)
	v_pk_mul_f32 v[116:117], v[138:139], s[16:17] op_sel_hi:[1,0]
	s_waitcnt vmcnt(3)
	v_pk_mul_f32 v[112:113], v[142:143], s[16:17] op_sel_hi:[1,0]
	v_pk_mul_f32 v[114:115], v[140:141], s[16:17] op_sel_hi:[1,0]
	v_pk_mul_f32 v[118:119], v[136:137], s[16:17] op_sel_hi:[1,0]
	s_waitcnt vmcnt(1)
	v_pk_mul_f32 v[120:121], v[150:151], s[16:17] op_sel_hi:[1,0]
	v_pk_mul_f32 v[122:123], v[148:149], s[16:17] op_sel_hi:[1,0]
	v_pk_mul_f32 v[124:125], v[146:147], s[16:17] op_sel_hi:[1,0]
	v_pk_mul_f32 v[126:127], v[144:145], s[16:17] op_sel_hi:[1,0]
	s_waitcnt vmcnt(0)
	v_pk_mul_f32 v[136:137], v[112:113], v[152:153] op_sel_hi:[1,0]
	v_pk_mul_f32 v[138:139], v[114:115], v[152:153] op_sel_hi:[1,0]
	v_pk_mul_f32 v[140:141], v[116:117], v[152:153] op_sel_hi:[1,0]
	v_pk_mul_f32 v[142:143], v[118:119], v[152:153] op_sel_hi:[1,0]
	v_pk_mul_f32 v[144:145], v[120:121], v[152:153] op_sel_hi:[1,0]
	v_pk_mul_f32 v[146:147], v[122:123], v[152:153] op_sel_hi:[1,0]
	v_pk_mul_f32 v[148:149], v[124:125], v[152:153] op_sel_hi:[1,0]
	v_pk_mul_f32 v[150:151], v[126:127], v[152:153] op_sel_hi:[1,0]
	v_pk_mul_f32 v[152:153], v[136:137], v[156:157]
	v_pk_mul_f32 v[136:137], v[138:139], v[154:155]
	v_pk_mul_f32 v[140:141], v[140:141], v[172:173]
	v_pk_mul_f32 v[138:139], v[142:143], v[158:159]
	v_pk_mul_f32 v[142:143], v[144:145], v[176:177]
	v_pk_mul_f32 v[144:145], v[146:147], v[174:175]
	v_pk_mul_f32 v[146:147], v[148:149], v[180:181]
	v_pk_mul_f32 v[148:149], v[150:151], v[178:179]
	v_cvt_pk_bf16_f32 v136, v136, v137
	v_cvt_pk_bf16_f32 v137, v152, v153
	v_cvt_pk_bf16_f32 v138, v138, v139
	v_cvt_pk_bf16_f32 v139, v140, v141
	v_cvt_pk_bf16_f32 v140, v144, v145
	v_cvt_pk_bf16_f32 v141, v142, v143
	v_cvt_pk_bf16_f32 v142, v148, v149
	v_cvt_pk_bf16_f32 v143, v146, v147
	global_store_dwordx4 v[130:131], v[136:139], off
	global_store_dwordx4 v[130:131], v[140:143], off offset:256
	global_load_dword v136, v[184:185], off
	v_or_b32_e32 v138, 32, v134
	v_lshlrev_b64 v[140:141], 12, v[182:183]
	v_lshl_add_u64 v[140:141], s[8:9], 0, v[140:141]
	v_ashrrev_i32_e32 v139, 31, v138
	v_lshl_add_u64 v[140:141], v[140:141], 0, v[132:133]
	v_lshl_add_u64 v[142:143], v[138:139], 2, s[10:11]
	v_cvt_f32_i32_e32 v57, v57
	v_cvt_f32_i32_e32 v56, v56
	v_cvt_f32_i32_e32 v59, v59
	v_cvt_f32_i32_e32 v58, v58
	v_cvt_f32_i32_e32 v53, v53
	v_cvt_f32_i32_e32 v52, v52
	v_cvt_f32_i32_e32 v55, v55
	v_cvt_f32_i32_e32 v54, v54
	v_cvt_f32_i32_e32 v49, v49
	v_cvt_f32_i32_e32 v48, v48
	v_cvt_f32_i32_e32 v51, v51
	v_cvt_f32_i32_e32 v50, v50
	v_cvt_f32_i32_e32 v45, v45
	v_cvt_f32_i32_e32 v44, v44
	v_cvt_f32_i32_e32 v47, v47
	v_cvt_f32_i32_e32 v46, v46
	v_cvt_f32_i32_e32 v41, v41
	v_cvt_f32_i32_e32 v40, v40
	v_cvt_f32_i32_e32 v43, v43
	v_cvt_f32_i32_e32 v42, v42
	v_cvt_f32_i32_e32 v37, v37
	v_cvt_f32_i32_e32 v36, v36
	v_cvt_f32_i32_e32 v39, v39
	v_cvt_f32_i32_e32 v38, v38
	v_cvt_f32_i32_e32 v33, v33
	v_cvt_f32_i32_e32 v32, v32
	v_cvt_f32_i32_e32 v35, v35
	v_cvt_f32_i32_e32 v34, v34
	v_cvt_f32_i32_e32 v29, v29
	v_cvt_f32_i32_e32 v28, v28
	v_cvt_f32_i32_e32 v31, v31
	v_cvt_f32_i32_e32 v30, v30
	v_cvt_f32_i32_e32 v25, v25
	v_cvt_f32_i32_e32 v24, v24
	v_cvt_f32_i32_e32 v27, v27
	v_cvt_f32_i32_e32 v26, v26
	v_cvt_f32_i32_e32 v21, v21
	v_cvt_f32_i32_e32 v20, v20
	v_cvt_f32_i32_e32 v23, v23
	v_cvt_f32_i32_e32 v22, v22
	v_cvt_f32_i32_e32 v17, v17
	v_cvt_f32_i32_e32 v16, v16
	v_cvt_f32_i32_e32 v19, v19
	v_cvt_f32_i32_e32 v18, v18
	v_cvt_f32_i32_e32 v13, v13
	v_cvt_f32_i32_e32 v12, v12
	v_cvt_f32_i32_e32 v15, v15
	v_cvt_f32_i32_e32 v14, v14
	v_cvt_f32_i32_e32 v9, v9
	v_cvt_f32_i32_e32 v8, v8
	v_cvt_f32_i32_e32 v11, v11
	v_cvt_f32_i32_e32 v10, v10
	v_cvt_f32_i32_e32 v5, v5
	v_cvt_f32_i32_e32 v4, v4
	v_cvt_f32_i32_e32 v7, v7
	v_cvt_f32_i32_e32 v6, v6
	v_cvt_f32_i32_e32 v1, v1
	v_cvt_f32_i32_e32 v0, v0
	v_cvt_f32_i32_e32 v3, v3
	v_cvt_f32_i32_e32 v2, v2
	s_waitcnt vmcnt(0)
	v_pk_mul_f32 v[144:145], v[112:113], v[136:137] op_sel_hi:[1,0]
	v_pk_mul_f32 v[146:147], v[114:115], v[136:137] op_sel_hi:[1,0]
	v_pk_mul_f32 v[148:149], v[116:117], v[136:137] op_sel_hi:[1,0]
	v_pk_mul_f32 v[150:151], v[118:119], v[136:137] op_sel_hi:[1,0]
	v_pk_mul_f32 v[152:153], v[120:121], v[136:137] op_sel_hi:[1,0]
	v_pk_mul_f32 v[154:155], v[122:123], v[136:137] op_sel_hi:[1,0]
	v_pk_mul_f32 v[156:157], v[124:125], v[136:137] op_sel_hi:[1,0]
	v_pk_mul_f32 v[136:137], v[126:127], v[136:137] op_sel_hi:[1,0]
	v_pk_mul_f32 v[110:111], v[144:145], v[110:111]
	v_pk_mul_f32 v[108:109], v[146:147], v[108:109]
	v_pk_mul_f32 v[106:107], v[148:149], v[106:107]
	v_pk_mul_f32 v[104:105], v[150:151], v[104:105]
	v_pk_mul_f32 v[102:103], v[152:153], v[102:103]
	v_pk_mul_f32 v[100:101], v[154:155], v[100:101]
	v_pk_mul_f32 v[144:145], v[156:157], v[98:99]
	v_pk_mul_f32 v[136:137], v[136:137], v[96:97]
	v_cvt_pk_bf16_f32 v96, v108, v109
	v_cvt_pk_bf16_f32 v97, v110, v111
	v_cvt_pk_bf16_f32 v98, v104, v105
	v_cvt_pk_bf16_f32 v99, v106, v107
	v_cvt_pk_bf16_f32 v100, v100, v101
	v_cvt_pk_bf16_f32 v101, v102, v103
	v_cvt_pk_bf16_f32 v102, v136, v137
	v_cvt_pk_bf16_f32 v103, v144, v145
	global_store_dwordx4 v[140:141], v[96:99], off
	global_store_dwordx4 v[140:141], v[100:103], off offset:256
	global_load_dword v96, v[142:143], off
	v_or_b32_e32 v98, 48, v134
	v_lshlrev_b64 v[100:101], 12, v[138:139]
	v_lshl_add_u64 v[100:101], s[8:9], 0, v[100:101]
	v_ashrrev_i32_e32 v99, 31, v98
	v_lshl_add_u64 v[100:101], v[100:101], 0, v[132:133]
	v_lshl_add_u64 v[102:103], v[98:99], 2, s[10:11]
	s_waitcnt vmcnt(0)
	v_pk_mul_f32 v[104:105], v[112:113], v[96:97] op_sel_hi:[1,0]
	v_pk_mul_f32 v[106:107], v[114:115], v[96:97] op_sel_hi:[1,0]
	v_pk_mul_f32 v[108:109], v[116:117], v[96:97] op_sel_hi:[1,0]
	v_pk_mul_f32 v[110:111], v[118:119], v[96:97] op_sel_hi:[1,0]
	v_pk_mul_f32 v[134:135], v[120:121], v[96:97] op_sel_hi:[1,0]
	v_pk_mul_f32 v[136:137], v[122:123], v[96:97] op_sel_hi:[1,0]
	v_pk_mul_f32 v[138:139], v[124:125], v[96:97] op_sel_hi:[1,0]
	v_pk_mul_f32 v[96:97], v[126:127], v[96:97] op_sel_hi:[1,0]
	v_pk_mul_f32 v[94:95], v[104:105], v[94:95]
	v_pk_mul_f32 v[92:93], v[106:107], v[92:93]
	v_pk_mul_f32 v[90:91], v[108:109], v[90:91]
	v_pk_mul_f32 v[88:89], v[110:111], v[88:89]
	v_pk_mul_f32 v[86:87], v[134:135], v[86:87]
	v_pk_mul_f32 v[84:85], v[136:137], v[84:85]
	v_pk_mul_f32 v[104:105], v[138:139], v[82:83]
	v_pk_mul_f32 v[96:97], v[96:97], v[80:81]
	v_cvt_pk_bf16_f32 v80, v92, v93
	v_cvt_pk_bf16_f32 v81, v94, v95
	v_cvt_pk_bf16_f32 v82, v88, v89
	v_cvt_pk_bf16_f32 v83, v90, v91
	v_cvt_pk_bf16_f32 v84, v84, v85
	v_cvt_pk_bf16_f32 v85, v86, v87
	v_cvt_pk_bf16_f32 v86, v96, v97
	v_cvt_pk_bf16_f32 v87, v104, v105
	global_store_dwordx4 v[100:101], v[80:83], off
	global_store_dwordx4 v[100:101], v[84:87], off offset:256
	global_load_dword v80, v[102:103], off
	v_lshlrev_b64 v[82:83], 12, v[98:99]
	v_lshl_add_u64 v[82:83], s[8:9], 0, v[82:83]
	v_lshl_add_u64 v[82:83], v[82:83], 0, v[132:133]
	s_waitcnt vmcnt(0)
	v_pk_mul_f32 v[84:85], v[112:113], v[80:81] op_sel_hi:[1,0]
	v_pk_mul_f32 v[86:87], v[114:115], v[80:81] op_sel_hi:[1,0]
	v_pk_mul_f32 v[88:89], v[116:117], v[80:81] op_sel_hi:[1,0]
	v_pk_mul_f32 v[90:91], v[118:119], v[80:81] op_sel_hi:[1,0]
	v_pk_mul_f32 v[92:93], v[120:121], v[80:81] op_sel_hi:[1,0]
	v_pk_mul_f32 v[94:95], v[122:123], v[80:81] op_sel_hi:[1,0]
	v_pk_mul_f32 v[96:97], v[124:125], v[80:81] op_sel_hi:[1,0]
	v_pk_mul_f32 v[80:81], v[126:127], v[80:81] op_sel_hi:[1,0]
	v_pk_mul_f32 v[78:79], v[84:85], v[78:79]
	v_pk_mul_f32 v[76:77], v[86:87], v[76:77]
	v_pk_mul_f32 v[74:75], v[88:89], v[74:75]
	v_pk_mul_f32 v[72:73], v[90:91], v[72:73]
	v_pk_mul_f32 v[70:71], v[92:93], v[70:71]
	v_pk_mul_f32 v[68:69], v[94:95], v[68:69]
	v_pk_mul_f32 v[84:85], v[96:97], v[66:67]
	v_pk_mul_f32 v[80:81], v[80:81], v[64:65]
	v_cvt_pk_bf16_f32 v64, v76, v77
	v_cvt_pk_bf16_f32 v65, v78, v79
	v_cvt_pk_bf16_f32 v66, v72, v73
	v_cvt_pk_bf16_f32 v67, v74, v75
	v_cvt_pk_bf16_f32 v68, v68, v69
	v_cvt_pk_bf16_f32 v69, v70, v71
	v_cvt_pk_bf16_f32 v70, v80, v81
	v_cvt_pk_bf16_f32 v71, v84, v85
	global_store_dwordx4 v[82:83], v[64:67], off
	global_store_dwordx4 v[82:83], v[68:71], off offset:256
	global_load_dword v64, v[128:129], off offset:512
	v_lshl_add_u64 v[66:67], v[130:131], 0, s[6:7]
	v_add_co_u32_e32 v68, vcc, s51, v130
	s_waitcnt vmcnt(0)
	v_pk_mul_f32 v[70:71], v[112:113], v[64:65] op_sel_hi:[1,0]
	v_pk_mul_f32 v[72:73], v[114:115], v[64:65] op_sel_hi:[1,0]
	v_pk_mul_f32 v[74:75], v[116:117], v[64:65] op_sel_hi:[1,0]
	v_pk_mul_f32 v[76:77], v[118:119], v[64:65] op_sel_hi:[1,0]
	v_pk_mul_f32 v[78:79], v[120:121], v[64:65] op_sel_hi:[1,0]
	v_pk_mul_f32 v[80:81], v[122:123], v[64:65] op_sel_hi:[1,0]
	v_pk_mul_f32 v[82:83], v[124:125], v[64:65] op_sel_hi:[1,0]
	v_pk_mul_f32 v[64:65], v[126:127], v[64:65] op_sel_hi:[1,0]
	v_pk_mul_f32 v[62:63], v[70:71], v[62:63]
	v_pk_mul_f32 v[60:61], v[72:73], v[60:61]
	v_pk_mul_f32 v[58:59], v[74:75], v[58:59]
	v_pk_mul_f32 v[56:57], v[76:77], v[56:57]
	v_addc_co_u32_e32 v69, vcc, 0, v131, vcc
	v_pk_mul_f32 v[54:55], v[78:79], v[54:55]
	v_pk_mul_f32 v[52:53], v[80:81], v[52:53]
	v_pk_mul_f32 v[70:71], v[82:83], v[50:51]
	v_pk_mul_f32 v[64:65], v[64:65], v[48:49]
	v_cvt_pk_bf16_f32 v48, v60, v61
	v_cvt_pk_bf16_f32 v49, v62, v63
	v_cvt_pk_bf16_f32 v50, v56, v57
	v_cvt_pk_bf16_f32 v51, v58, v59
	v_cvt_pk_bf16_f32 v52, v52, v53
	v_cvt_pk_bf16_f32 v53, v54, v55
	v_cvt_pk_bf16_f32 v54, v64, v65
	v_cvt_pk_bf16_f32 v55, v70, v71
	global_store_dwordx4 v[68:69], v[48:51], off
	global_store_dwordx4 v[66:67], v[52:55], off offset:256
	global_load_dword v48, v[128:129], off offset:576
	v_lshl_add_u64 v[50:51], v[130:131], 0, s[18:19]
	v_add_co_u32_e32 v52, vcc, s52, v130
	s_waitcnt vmcnt(0)
	v_pk_mul_f32 v[54:55], v[112:113], v[48:49] op_sel_hi:[1,0]
	v_pk_mul_f32 v[56:57], v[114:115], v[48:49] op_sel_hi:[1,0]
	v_pk_mul_f32 v[58:59], v[116:117], v[48:49] op_sel_hi:[1,0]
	v_pk_mul_f32 v[60:61], v[118:119], v[48:49] op_sel_hi:[1,0]
	v_pk_mul_f32 v[62:63], v[120:121], v[48:49] op_sel_hi:[1,0]
	v_pk_mul_f32 v[64:65], v[122:123], v[48:49] op_sel_hi:[1,0]
	v_pk_mul_f32 v[66:67], v[124:125], v[48:49] op_sel_hi:[1,0]
	v_pk_mul_f32 v[48:49], v[126:127], v[48:49] op_sel_hi:[1,0]
	v_pk_mul_f32 v[46:47], v[54:55], v[46:47]
	v_pk_mul_f32 v[44:45], v[56:57], v[44:45]
	v_pk_mul_f32 v[42:43], v[58:59], v[42:43]
	v_pk_mul_f32 v[40:41], v[60:61], v[40:41]
	v_addc_co_u32_e32 v53, vcc, 0, v131, vcc
	v_pk_mul_f32 v[38:39], v[62:63], v[38:39]
	v_pk_mul_f32 v[36:37], v[64:65], v[36:37]
	v_pk_mul_f32 v[54:55], v[66:67], v[34:35]
	v_pk_mul_f32 v[48:49], v[48:49], v[32:33]
	v_cvt_pk_bf16_f32 v32, v44, v45
	v_cvt_pk_bf16_f32 v33, v46, v47
	v_cvt_pk_bf16_f32 v34, v40, v41
	v_cvt_pk_bf16_f32 v35, v42, v43
	v_cvt_pk_bf16_f32 v36, v36, v37
	v_cvt_pk_bf16_f32 v37, v38, v39
	v_cvt_pk_bf16_f32 v38, v48, v49
	v_cvt_pk_bf16_f32 v39, v54, v55
	global_store_dwordx4 v[52:53], v[32:35], off
	global_store_dwordx4 v[50:51], v[36:39], off offset:256
	global_load_dword v32, v[128:129], off offset:640
	v_lshl_add_u64 v[34:35], v[130:131], 0, s[20:21]
	v_add_co_u32_e32 v36, vcc, s53, v130
	s_waitcnt vmcnt(0)
	v_pk_mul_f32 v[38:39], v[112:113], v[32:33] op_sel_hi:[1,0]
	v_pk_mul_f32 v[40:41], v[114:115], v[32:33] op_sel_hi:[1,0]
	v_pk_mul_f32 v[42:43], v[116:117], v[32:33] op_sel_hi:[1,0]
	v_pk_mul_f32 v[44:45], v[118:119], v[32:33] op_sel_hi:[1,0]
	v_pk_mul_f32 v[46:47], v[120:121], v[32:33] op_sel_hi:[1,0]
	v_pk_mul_f32 v[48:49], v[122:123], v[32:33] op_sel_hi:[1,0]
	v_pk_mul_f32 v[50:51], v[124:125], v[32:33] op_sel_hi:[1,0]
	v_pk_mul_f32 v[32:33], v[126:127], v[32:33] op_sel_hi:[1,0]
	v_pk_mul_f32 v[30:31], v[38:39], v[30:31]
	v_pk_mul_f32 v[28:29], v[40:41], v[28:29]
	v_pk_mul_f32 v[26:27], v[42:43], v[26:27]
	v_pk_mul_f32 v[24:25], v[44:45], v[24:25]
	v_addc_co_u32_e32 v37, vcc, 0, v131, vcc
	v_pk_mul_f32 v[22:23], v[46:47], v[22:23]
	v_pk_mul_f32 v[20:21], v[48:49], v[20:21]
	v_pk_mul_f32 v[38:39], v[50:51], v[18:19]
	v_pk_mul_f32 v[32:33], v[32:33], v[16:17]
	v_cvt_pk_bf16_f32 v16, v28, v29
	v_cvt_pk_bf16_f32 v17, v30, v31
	v_cvt_pk_bf16_f32 v18, v24, v25
	v_cvt_pk_bf16_f32 v19, v26, v27
	v_cvt_pk_bf16_f32 v20, v20, v21
	v_cvt_pk_bf16_f32 v21, v22, v23
	v_cvt_pk_bf16_f32 v22, v32, v33
	v_cvt_pk_bf16_f32 v23, v38, v39
	global_store_dwordx4 v[36:37], v[16:19], off
	global_store_dwordx4 v[34:35], v[20:23], off offset:256
	global_load_dword v16, v[128:129], off offset:704
	s_andn2_b64 vcc, exec, s[2:3]
	v_add_co_u32_e64 v20, s[2:3], s56, v130
	v_lshl_add_u64 v[18:19], v[130:131], 0, s[22:23]
	s_nop 0
	v_addc_co_u32_e64 v21, s[2:3], 0, v131, s[2:3]
	s_mov_b64 s[2:3], -1
	s_waitcnt vmcnt(0)
	v_pk_mul_f32 v[22:23], v[112:113], v[16:17] op_sel_hi:[1,0]
	v_pk_mul_f32 v[24:25], v[114:115], v[16:17] op_sel_hi:[1,0]
	v_pk_mul_f32 v[26:27], v[116:117], v[16:17] op_sel_hi:[1,0]
	v_pk_mul_f32 v[28:29], v[118:119], v[16:17] op_sel_hi:[1,0]
	v_pk_mul_f32 v[30:31], v[120:121], v[16:17] op_sel_hi:[1,0]
	v_pk_mul_f32 v[32:33], v[122:123], v[16:17] op_sel_hi:[1,0]
	v_pk_mul_f32 v[34:35], v[124:125], v[16:17] op_sel_hi:[1,0]
	v_pk_mul_f32 v[16:17], v[126:127], v[16:17] op_sel_hi:[1,0]
	v_pk_mul_f32 v[14:15], v[22:23], v[14:15]
	v_pk_mul_f32 v[12:13], v[24:25], v[12:13]
	v_pk_mul_f32 v[10:11], v[26:27], v[10:11]
	v_pk_mul_f32 v[8:9], v[28:29], v[8:9]
	v_pk_mul_f32 v[6:7], v[30:31], v[6:7]
	v_pk_mul_f32 v[4:5], v[32:33], v[4:5]
	v_pk_mul_f32 v[22:23], v[34:35], v[2:3]
	v_pk_mul_f32 v[16:17], v[16:17], v[0:1]
	v_cvt_pk_bf16_f32 v0, v12, v13
	v_cvt_pk_bf16_f32 v1, v14, v15
	v_cvt_pk_bf16_f32 v2, v8, v9
	v_cvt_pk_bf16_f32 v3, v10, v11
	v_cvt_pk_bf16_f32 v4, v4, v5
	v_cvt_pk_bf16_f32 v5, v6, v7
	v_cvt_pk_bf16_f32 v6, v16, v17
	v_cvt_pk_bf16_f32 v7, v22, v23
	global_store_dwordx4 v[20:21], v[0:3], off
	global_store_dwordx4 v[18:19], v[4:7], off offset:256
	s_cbranch_vccnz .LBB0_331
	s_andn2_b64 vcc, exec, s[4:5]
	s_cbranch_vccnz .LBB0_330
	s_mov_b32 s99, 1
	s_branch .LBB0_330

.LBB0_1341:
	s_ashr_i32 s23, s22, 31
	s_lshl_b64 s[24:25], s[22:23], 19
	s_add_u32 s24, s41, s24
	s_addc_u32 s25, s42, s25
	s_and_b64 s[26:27], s[2:3], exec
	s_cselect_b32 s5, s25, s29
	s_cselect_b32 s23, s24, s28
	s_ashr_i32 s21, s20, 31
	s_lshl_b64 s[26:27], s[20:21], 19
	s_add_u32 s26, s33, s26
	s_addc_u32 s27, s40, s27
	s_and_b64 s[34:35], s[2:3], exec
	s_cselect_b32 s21, s27, s31
	s_cselect_b32 s50, s26, s30
	s_add_u32 s51, s30, 0x100
	s_addc_u32 s52, s31, 0
	s_mov_b32 s53, -2
	v_mov_b64_e32 v[32:33], 0
	v_mov_b64_e32 v[34:35], 0
	v_mov_b64_e32 v[36:37], 0
	v_mov_b64_e32 v[38:39], 0
	v_mov_b64_e32 v[40:41], 0
	v_mov_b64_e32 v[42:43], 0
	v_mov_b64_e32 v[44:45], 0
	v_mov_b64_e32 v[46:47], 0
	v_mov_b64_e32 v[48:49], 0
	v_mov_b64_e32 v[50:51], 0
	v_mov_b64_e32 v[52:53], 0
	v_mov_b64_e32 v[54:55], 0
	v_mov_b64_e32 v[56:57], 0
	v_mov_b64_e32 v[58:59], 0
	v_mov_b64_e32 v[60:61], 0
	v_mov_b64_e32 v[62:63], 0
	v_mov_b64_e32 v[64:65], 0
	v_mov_b64_e32 v[66:67], 0
	v_mov_b64_e32 v[68:69], 0
	v_mov_b64_e32 v[70:71], 0
	v_mov_b64_e32 v[72:73], 0
	v_mov_b64_e32 v[74:75], 0
	v_mov_b64_e32 v[76:77], 0
	v_mov_b64_e32 v[78:79], 0
	v_mov_b64_e32 v[80:81], 0
	v_mov_b64_e32 v[82:83], 0
	v_mov_b64_e32 v[84:85], 0
	v_mov_b64_e32 v[86:87], 0
	v_mov_b64_e32 v[88:89], 0
	v_mov_b64_e32 v[90:91], 0
	v_mov_b64_e32 v[92:93], 0
	v_mov_b64_e32 v[94:95], 0
	v_mov_b64_e32 v[96:97], 0
	v_mov_b64_e32 v[98:99], 0
	v_mov_b64_e32 v[100:101], 0
	v_mov_b64_e32 v[102:103], 0
	v_mov_b64_e32 v[104:105], 0
	v_mov_b64_e32 v[106:107], 0
	v_mov_b64_e32 v[108:109], 0
	v_mov_b64_e32 v[110:111], 0
	v_mov_b64_e32 v[112:113], 0
	v_mov_b64_e32 v[114:115], 0
	v_mov_b64_e32 v[116:117], 0
	v_mov_b64_e32 v[118:119], 0
	v_mov_b64_e32 v[120:121], 0
	v_mov_b64_e32 v[122:123], 0
	v_mov_b64_e32 v[124:125], 0
	v_mov_b64_e32 v[126:127], 0
	v_mov_b64_e32 v[128:129], 0
	v_mov_b64_e32 v[130:131], 0
	v_mov_b64_e32 v[132:133], 0
	v_mov_b64_e32 v[134:135], 0
	v_mov_b64_e32 v[136:137], 0
	v_mov_b64_e32 v[138:139], 0
	v_mov_b64_e32 v[140:141], 0
	v_mov_b64_e32 v[142:143], 0
	v_mov_b64_e32 v[144:145], 0
	v_mov_b64_e32 v[146:147], 0
	v_mov_b64_e32 v[148:149], 0
	v_mov_b64_e32 v[150:151], 0
	v_mov_b64_e32 v[152:153], 0
	v_mov_b64_e32 v[154:155], 0
	v_mov_b64_e32 v[156:157], 0
	v_mov_b64_e32 v[158:159], 0
	s_cmp_eq_u32 s99, 1
	s_cbranch_scc0 .Lue_1342
	s_mov_b32 s99, 0
	s_barrier
.Lue_1342:
.LBB0_1342:
	ds_read_b128 v[16:19], v216
	ds_read_b128 v[24:27], v216 offset:2048
	ds_read_b128 v[20:23], v217
	ds_read_b128 v[28:31], v217 offset:2048
	ds_read_b128 v[0:3], v218
	ds_read_b128 v[8:11], v218 offset:2048
	ds_read_b128 v[4:7], v219
	ds_read_b128 v[12:15], v219 offset:2048
	s_add_u32 s30, s28, 0x100
	s_addc_u32 s31, s29, 0
	s_cmp_eq_u32 s53, 12
	s_cselect_b32 s38, s23, s30
	s_cselect_b32 s39, s5, s31
	s_cselect_b32 s36, s50, s51
	s_cselect_b32 s37, s21, s52
	s_add_u32 s34, s38, 0x80
	s_addc_u32 s35, s39, 0
	ds_read_b128 v[164:167], v220
	ds_read_b128 v[172:175], v220 offset:2048
	ds_read_b128 v[168:171], v221
	ds_read_b128 v[176:179], v221 offset:2048
	ds_read_b128 v[180:183], v220 offset:4096
	ds_read_b128 v[188:191], v220 offset:6144
	ds_read_b128 v[184:187], v221 offset:4096
	ds_read_b128 v[192:195], v221 offset:6144
	s_add_u32 s28, s28, 0x40080
	s_addc_u32 s29, s29, 0
	s_add_i32 m0, s1, 0xc000
	s_nop 0
	global_load_lds_dwordx4 v211, s[28:29]
	s_nop 0
	s_add_i32 m0, s1, 0xe000
	s_nop 0
	global_load_lds_dwordx4 v212, s[28:29]
	s_waitcnt vmcnt(8)
	s_waitcnt lgkmcnt(0)
	s_barrier
	s_setprio 1
	v_mfma_scale_f32_16x16x128_f8f6f4 v[156:159], v[16:23], v[164:171], v[156:159], v213, v213 op_sel_hi:[0,0,0]
	v_mfma_scale_f32_16x16x128_f8f6f4 v[148:151], v[24:31], v[164:171], v[148:151], v213, v213 op_sel_hi:[0,0,0]
	v_mfma_scale_f32_16x16x128_f8f6f4 v[140:143], v[16:23], v[172:179], v[140:143], v213, v213 op_sel_hi:[0,0,0]
	v_mfma_scale_f32_16x16x128_f8f6f4 v[132:135], v[24:31], v[172:179], v[132:135], v213, v213 op_sel_hi:[0,0,0]
	v_mfma_scale_f32_16x16x128_f8f6f4 v[124:127], v[16:23], v[180:187], v[124:127], v213, v213 op_sel_hi:[0,0,0]
	v_mfma_scale_f32_16x16x128_f8f6f4 v[116:119], v[24:31], v[180:187], v[116:119], v213, v213 op_sel_hi:[0,0,0]
	v_mfma_scale_f32_16x16x128_f8f6f4 v[108:111], v[16:23], v[188:195], v[108:111], v213, v213 op_sel_hi:[0,0,0]
	v_mfma_scale_f32_16x16x128_f8f6f4 v[100:103], v[24:31], v[188:195], v[100:103], v213, v213 op_sel_hi:[0,0,0]
	v_mfma_scale_f32_16x16x128_f8f6f4 v[152:155], v[0:7], v[164:171], v[152:155], v213, v213 op_sel_hi:[0,0,0]
	v_mfma_scale_f32_16x16x128_f8f6f4 v[144:147], v[8:15], v[164:171], v[144:147], v213, v213 op_sel_hi:[0,0,0]
	v_mfma_scale_f32_16x16x128_f8f6f4 v[136:139], v[0:7], v[172:179], v[136:139], v213, v213 op_sel_hi:[0,0,0]
	v_mfma_scale_f32_16x16x128_f8f6f4 v[128:131], v[8:15], v[172:179], v[128:131], v213, v213 op_sel_hi:[0,0,0]
	v_mfma_scale_f32_16x16x128_f8f6f4 v[120:123], v[0:7], v[180:187], v[120:123], v213, v213 op_sel_hi:[0,0,0]
	v_mfma_scale_f32_16x16x128_f8f6f4 v[112:115], v[8:15], v[180:187], v[112:115], v213, v213 op_sel_hi:[0,0,0]
	v_mfma_scale_f32_16x16x128_f8f6f4 v[104:107], v[0:7], v[188:195], v[104:107], v213, v213 op_sel_hi:[0,0,0]
	v_mfma_scale_f32_16x16x128_f8f6f4 v[96:99], v[8:15], v[188:195], v[96:99], v213, v213 op_sel_hi:[0,0,0]
	s_setprio 0
	s_barrier
	ds_read_b128 v[164:167], v220 offset:16384
	ds_read_b128 v[172:175], v220 offset:18432
	ds_read_b128 v[168:171], v221 offset:16384
	ds_read_b128 v[176:179], v221 offset:18432
	ds_read_b128 v[180:183], v220 offset:20480
	ds_read_b128 v[188:191], v220 offset:22528
	ds_read_b128 v[184:187], v221 offset:20480
	ds_read_b128 v[192:195], v221 offset:22528
	s_add_i32 m0, s1, 0x10000
	s_nop 0
	global_load_lds_dwordx4 v211, s[36:37]
	s_nop 0
	s_add_i32 m0, s1, 0x12000
	s_nop 0
	global_load_lds_dwordx4 v212, s[36:37]
	s_add_u32 s28, s36, 0x40000
	s_addc_u32 s29, s37, 0
	s_add_i32 m0, s1, 0x14000
	s_nop 0
	global_load_lds_dwordx4 v211, s[28:29]
	s_nop 0
	s_add_i32 m0, s1, 0x16000
	s_nop 0
	global_load_lds_dwordx4 v212, s[28:29]
	s_nop 0
	s_add_i32 m0, s1, 0
	s_nop 0
	global_load_lds_dwordx4 v211, s[38:39]
	s_nop 0
	s_add_i32 m0, s1, 0x2000
	s_nop 0
	global_load_lds_dwordx4 v212, s[38:39]
	s_waitcnt vmcnt(8)
	s_waitcnt lgkmcnt(0)
	s_barrier
	s_setprio 1
	v_mfma_scale_f32_16x16x128_f8f6f4 v[92:95], v[16:23], v[164:171], v[92:95], v213, v213 op_sel_hi:[0,0,0]
	v_mfma_scale_f32_16x16x128_f8f6f4 v[84:87], v[24:31], v[164:171], v[84:87], v213, v213 op_sel_hi:[0,0,0]
	v_mfma_scale_f32_16x16x128_f8f6f4 v[76:79], v[16:23], v[172:179], v[76:79], v213, v213 op_sel_hi:[0,0,0]
	v_mfma_scale_f32_16x16x128_f8f6f4 v[68:71], v[24:31], v[172:179], v[68:71], v213, v213 op_sel_hi:[0,0,0]
	v_mfma_scale_f32_16x16x128_f8f6f4 v[60:63], v[16:23], v[180:187], v[60:63], v213, v213 op_sel_hi:[0,0,0]
	v_mfma_scale_f32_16x16x128_f8f6f4 v[52:55], v[24:31], v[180:187], v[52:55], v213, v213 op_sel_hi:[0,0,0]
	v_mfma_scale_f32_16x16x128_f8f6f4 v[44:47], v[16:23], v[188:195], v[44:47], v213, v213 op_sel_hi:[0,0,0]
	v_mfma_scale_f32_16x16x128_f8f6f4 v[36:39], v[24:31], v[188:195], v[36:39], v213, v213 op_sel_hi:[0,0,0]
	v_mfma_scale_f32_16x16x128_f8f6f4 v[88:91], v[0:7], v[164:171], v[88:91], v213, v213 op_sel_hi:[0,0,0]
	v_mfma_scale_f32_16x16x128_f8f6f4 v[80:83], v[8:15], v[164:171], v[80:83], v213, v213 op_sel_hi:[0,0,0]
	v_mfma_scale_f32_16x16x128_f8f6f4 v[72:75], v[0:7], v[172:179], v[72:75], v213, v213 op_sel_hi:[0,0,0]
	v_mfma_scale_f32_16x16x128_f8f6f4 v[64:67], v[8:15], v[172:179], v[64:67], v213, v213 op_sel_hi:[0,0,0]
	v_mfma_scale_f32_16x16x128_f8f6f4 v[56:59], v[0:7], v[180:187], v[56:59], v213, v213 op_sel_hi:[0,0,0]
	v_mfma_scale_f32_16x16x128_f8f6f4 v[48:51], v[8:15], v[180:187], v[48:51], v213, v213 op_sel_hi:[0,0,0]
	v_mfma_scale_f32_16x16x128_f8f6f4 v[40:43], v[0:7], v[188:195], v[40:43], v213, v213 op_sel_hi:[0,0,0]
	v_mfma_scale_f32_16x16x128_f8f6f4 v[32:35], v[8:15], v[188:195], v[32:35], v213, v213 op_sel_hi:[0,0,0]
	s_setprio 0
	s_barrier
	ds_read_b128 v[0:3], v222
	ds_read_b128 v[8:11], v222 offset:2048
	ds_read_b128 v[4:7], v225
	ds_read_b128 v[12:15], v225 offset:2048
	ds_read_b128 v[16:19], v226
	ds_read_b128 v[24:27], v226 offset:2048
	ds_read_b128 v[20:23], v227
	ds_read_b128 v[28:31], v227 offset:2048
	ds_read_b128 v[164:167], v220 offset:32768
	ds_read_b128 v[172:175], v220 offset:34816
	ds_read_b128 v[168:171], v221 offset:32768
	ds_read_b128 v[176:179], v221 offset:34816
	ds_read_b128 v[180:183], v220 offset:36864
	ds_read_b128 v[188:191], v220 offset:38912
	ds_read_b128 v[184:187], v221 offset:36864
	ds_read_b128 v[192:195], v221 offset:38912
	s_add_u32 s28, s38, 0x40000
	s_addc_u32 s29, s39, 0
	s_add_i32 m0, s1, 0x4000
	s_nop 0
	global_load_lds_dwordx4 v211, s[28:29]
	s_nop 0
	s_add_i32 m0, s1, 0x6000
	s_nop 0
	global_load_lds_dwordx4 v212, s[28:29]
	s_waitcnt vmcnt(8)
	s_waitcnt lgkmcnt(0)
	s_barrier
	s_setprio 1
	v_mfma_scale_f32_16x16x128_f8f6f4 v[156:159], v[0:7], v[164:171], v[156:159], v213, v213 op_sel_hi:[0,0,0]
	v_mfma_scale_f32_16x16x128_f8f6f4 v[148:151], v[8:15], v[164:171], v[148:151], v213, v213 op_sel_hi:[0,0,0]
	v_mfma_scale_f32_16x16x128_f8f6f4 v[140:143], v[0:7], v[172:179], v[140:143], v213, v213 op_sel_hi:[0,0,0]
	v_mfma_scale_f32_16x16x128_f8f6f4 v[132:135], v[8:15], v[172:179], v[132:135], v213, v213 op_sel_hi:[0,0,0]
	v_mfma_scale_f32_16x16x128_f8f6f4 v[124:127], v[0:7], v[180:187], v[124:127], v213, v213 op_sel_hi:[0,0,0]
	v_mfma_scale_f32_16x16x128_f8f6f4 v[116:119], v[8:15], v[180:187], v[116:119], v213, v213 op_sel_hi:[0,0,0]
	v_mfma_scale_f32_16x16x128_f8f6f4 v[108:111], v[0:7], v[188:195], v[108:111], v213, v213 op_sel_hi:[0,0,0]
	v_mfma_scale_f32_16x16x128_f8f6f4 v[100:103], v[8:15], v[188:195], v[100:103], v213, v213 op_sel_hi:[0,0,0]
	v_mfma_scale_f32_16x16x128_f8f6f4 v[152:155], v[16:23], v[164:171], v[152:155], v213, v213 op_sel_hi:[0,0,0]
	v_mfma_scale_f32_16x16x128_f8f6f4 v[144:147], v[24:31], v[164:171], v[144:147], v213, v213 op_sel_hi:[0,0,0]
	v_mfma_scale_f32_16x16x128_f8f6f4 v[136:139], v[16:23], v[172:179], v[136:139], v213, v213 op_sel_hi:[0,0,0]
	v_mfma_scale_f32_16x16x128_f8f6f4 v[128:131], v[24:31], v[172:179], v[128:131], v213, v213 op_sel_hi:[0,0,0]
	v_mfma_scale_f32_16x16x128_f8f6f4 v[120:123], v[16:23], v[180:187], v[120:123], v213, v213 op_sel_hi:[0,0,0]
	v_mfma_scale_f32_16x16x128_f8f6f4 v[112:115], v[24:31], v[180:187], v[112:115], v213, v213 op_sel_hi:[0,0,0]
	v_mfma_scale_f32_16x16x128_f8f6f4 v[104:107], v[16:23], v[188:195], v[104:107], v213, v213 op_sel_hi:[0,0,0]
	v_mfma_scale_f32_16x16x128_f8f6f4 v[96:99], v[24:31], v[188:195], v[96:99], v213, v213 op_sel_hi:[0,0,0]
	s_setprio 0
	s_barrier
	s_add_u32 s28, s36, 0x80
	ds_read_b128 v[164:167], v220 offset:49152
	ds_read_b128 v[172:175], v220 offset:51200
	ds_read_b128 v[168:171], v221 offset:49152
	ds_read_b128 v[176:179], v221 offset:51200
	ds_read_b128 v[180:183], v220 offset:53248
	ds_read_b128 v[188:191], v220 offset:55296
	ds_read_b128 v[184:187], v221 offset:53248
	ds_read_b128 v[192:195], v221 offset:55296
	s_addc_u32 s29, s37, 0
	s_add_i32 m0, s1, 0x18000
	s_nop 0
	global_load_lds_dwordx4 v211, s[28:29]
	s_nop 0
	s_add_i32 m0, s1, 0x1a000
	s_nop 0
	global_load_lds_dwordx4 v212, s[28:29]
	s_add_u32 s28, s36, 0x40080
	s_addc_u32 s29, s37, 0
	s_add_i32 m0, s1, 0x1c000
	s_nop 0
	global_load_lds_dwordx4 v211, s[28:29]
	s_nop 0
	s_add_i32 m0, s1, 0x1e000
	s_nop 0
	global_load_lds_dwordx4 v212, s[28:29]
	s_nop 0
	s_add_i32 m0, s1, 0x8000
	s_nop 0
	global_load_lds_dwordx4 v211, s[34:35]
	s_nop 0
	s_add_i32 m0, s1, 0xa000
	s_nop 0
	global_load_lds_dwordx4 v212, s[34:35]
	s_waitcnt vmcnt(8)
	s_waitcnt lgkmcnt(0)
	s_barrier
	s_setprio 1
	v_mfma_scale_f32_16x16x128_f8f6f4 v[92:95], v[0:7], v[164:171], v[92:95], v213, v213 op_sel_hi:[0,0,0]
	v_mfma_scale_f32_16x16x128_f8f6f4 v[84:87], v[8:15], v[164:171], v[84:87], v213, v213 op_sel_hi:[0,0,0]
	v_mfma_scale_f32_16x16x128_f8f6f4 v[76:79], v[0:7], v[172:179], v[76:79], v213, v213 op_sel_hi:[0,0,0]
	v_mfma_scale_f32_16x16x128_f8f6f4 v[68:71], v[8:15], v[172:179], v[68:71], v213, v213 op_sel_hi:[0,0,0]
	v_mfma_scale_f32_16x16x128_f8f6f4 v[60:63], v[0:7], v[180:187], v[60:63], v213, v213 op_sel_hi:[0,0,0]
	v_mfma_scale_f32_16x16x128_f8f6f4 v[52:55], v[8:15], v[180:187], v[52:55], v213, v213 op_sel_hi:[0,0,0]
	v_mfma_scale_f32_16x16x128_f8f6f4 v[44:47], v[0:7], v[188:195], v[44:47], v213, v213 op_sel_hi:[0,0,0]
	v_mfma_scale_f32_16x16x128_f8f6f4 v[36:39], v[8:15], v[188:195], v[36:39], v213, v213 op_sel_hi:[0,0,0]
	v_mfma_scale_f32_16x16x128_f8f6f4 v[88:91], v[16:23], v[164:171], v[88:91], v213, v213 op_sel_hi:[0,0,0]
	v_mfma_scale_f32_16x16x128_f8f6f4 v[80:83], v[24:31], v[164:171], v[80:83], v213, v213 op_sel_hi:[0,0,0]
	v_mfma_scale_f32_16x16x128_f8f6f4 v[72:75], v[16:23], v[172:179], v[72:75], v213, v213 op_sel_hi:[0,0,0]
	v_mfma_scale_f32_16x16x128_f8f6f4 v[64:67], v[24:31], v[172:179], v[64:67], v213, v213 op_sel_hi:[0,0,0]
	v_mfma_scale_f32_16x16x128_f8f6f4 v[56:59], v[16:23], v[180:187], v[56:59], v213, v213 op_sel_hi:[0,0,0]
	v_mfma_scale_f32_16x16x128_f8f6f4 v[48:51], v[24:31], v[180:187], v[48:51], v213, v213 op_sel_hi:[0,0,0]
	v_mfma_scale_f32_16x16x128_f8f6f4 v[40:43], v[16:23], v[188:195], v[40:43], v213, v213 op_sel_hi:[0,0,0]
	v_mfma_scale_f32_16x16x128_f8f6f4 v[32:35], v[24:31], v[188:195], v[32:35], v213, v213 op_sel_hi:[0,0,0]
	s_setprio 0
	s_barrier
	s_add_i32 s53, s53, 2
	s_add_u32 s51, s51, 0x100
	s_addc_u32 s52, s52, 0
	s_cmp_gt_u32 s53, 13
	s_mov_b64 s[28:29], s[30:31]
	s_cbranch_scc0 .LBB0_1342
	s_and_b64 vcc, exec, s[16:17]
	s_cbranch_vccz .LBB0_1345
	s_barrier

.LBB0_1361:
	s_or_b64 exec, exec, s[4:5]
	s_andn2_b64 vcc, exec, s[2:3]
	s_mov_b64 s[2:3], -1
	s_cbranch_vccnz .LBB0_1334
	s_andn2_b64 vcc, exec, s[6:7]
	s_cbranch_vccnz .LBB0_1333
	s_mov_b32 s99, 1
	s_branch .LBB0_1333

.LBB0_1492:
	s_ashr_i32 s29, s28, 31
	s_lshl_b64 s[30:31], s[28:29], 20
	s_add_u32 s30, s25, s30
	s_addc_u32 s31, s33, s31
	s_and_b64 s[34:35], s[4:5], exec
	s_cselect_b32 s29, s31, s41
	s_cselect_b32 s37, s30, s40
	s_ashr_i32 s27, s26, 31
	s_lshl_b64 s[34:35], s[26:27], 20
	s_add_u32 s34, s48, s34
	s_addc_u32 s35, s49, s35
	s_and_b64 s[42:43], s[4:5], exec
	s_cselect_b32 s27, s35, s39
	s_cselect_b32 s57, s34, s38
	s_add_u32 s58, s38, 0x100
	s_addc_u32 s59, s39, 0
	s_mov_b32 s60, -2
	s_waitcnt lgkmcnt(0)
	s_waitcnt vmcnt(62)
	s_waitcnt vmcnt(61)
	s_waitcnt vmcnt(60)
	s_waitcnt vmcnt(59)
	s_waitcnt vmcnt(58)
	s_waitcnt vmcnt(49)
	s_waitcnt vmcnt(48)
	s_waitcnt vmcnt(47)
	s_waitcnt vmcnt(46)
	s_waitcnt vmcnt(45)
	s_waitcnt vmcnt(44)
	s_waitcnt vmcnt(43)
	s_waitcnt vmcnt(42)
	s_waitcnt vmcnt(41)
	s_waitcnt vmcnt(40)
	s_waitcnt vmcnt(39)
	s_waitcnt vmcnt(38)
	s_waitcnt vmcnt(37)
	s_waitcnt vmcnt(36)
	s_waitcnt vmcnt(35)
	s_waitcnt vmcnt(34)
	s_waitcnt vmcnt(33)
	s_waitcnt vmcnt(32)
	s_waitcnt vmcnt(31)
	s_waitcnt vmcnt(30)
	s_waitcnt vmcnt(29)
	s_waitcnt vmcnt(28)
	s_waitcnt vmcnt(27)
	s_waitcnt vmcnt(26)
	s_waitcnt vmcnt(17)
	s_waitcnt vmcnt(16)
	s_waitcnt vmcnt(15)
	s_waitcnt vmcnt(14)
	s_waitcnt vmcnt(13)
	s_waitcnt vmcnt(12)
	s_waitcnt vmcnt(11)
	s_waitcnt vmcnt(10)
	s_waitcnt vmcnt(1)
	s_waitcnt vmcnt(0)
	v_mov_b64_e32 v[0:1], 0
	v_mov_b64_e32 v[2:3], 0
	v_mov_b64_e32 v[4:5], 0
	v_mov_b64_e32 v[6:7], 0
	v_mov_b64_e32 v[8:9], 0
	v_mov_b64_e32 v[10:11], 0
	v_mov_b64_e32 v[12:13], 0
	v_mov_b64_e32 v[14:15], 0
	v_mov_b64_e32 v[16:17], 0
	v_mov_b64_e32 v[18:19], 0
	v_mov_b64_e32 v[20:21], 0
	v_mov_b64_e32 v[22:23], 0
	v_mov_b64_e32 v[24:25], 0
	v_mov_b64_e32 v[26:27], 0
	v_mov_b64_e32 v[28:29], 0
	v_mov_b64_e32 v[30:31], 0
	v_mov_b64_e32 v[32:33], 0
	v_mov_b64_e32 v[34:35], 0
	v_mov_b64_e32 v[36:37], 0
	v_mov_b64_e32 v[38:39], 0
	v_mov_b64_e32 v[40:41], 0
	v_mov_b64_e32 v[42:43], 0
	v_mov_b64_e32 v[44:45], 0
	v_mov_b64_e32 v[46:47], 0
	v_mov_b64_e32 v[48:49], 0
	v_mov_b64_e32 v[50:51], 0
	v_mov_b64_e32 v[52:53], 0
	v_mov_b64_e32 v[54:55], 0
	v_mov_b64_e32 v[56:57], 0
	v_mov_b64_e32 v[58:59], 0
	v_mov_b64_e32 v[60:61], 0
	v_mov_b64_e32 v[62:63], 0
	v_mov_b64_e32 v[64:65], 0
	v_mov_b64_e32 v[66:67], 0
	v_mov_b64_e32 v[68:69], 0
	v_mov_b64_e32 v[70:71], 0
	v_mov_b64_e32 v[72:73], 0
	v_mov_b64_e32 v[74:75], 0
	v_mov_b64_e32 v[76:77], 0
	v_mov_b64_e32 v[78:79], 0
	v_mov_b64_e32 v[80:81], 0
	v_mov_b64_e32 v[82:83], 0
	v_mov_b64_e32 v[84:85], 0
	v_mov_b64_e32 v[86:87], 0
	v_mov_b64_e32 v[88:89], 0
	v_mov_b64_e32 v[90:91], 0
	v_mov_b64_e32 v[92:93], 0
	v_mov_b64_e32 v[94:95], 0
	v_mov_b64_e32 v[96:97], 0
	v_mov_b64_e32 v[98:99], 0
	v_mov_b64_e32 v[100:101], 0
	v_mov_b64_e32 v[102:103], 0
	v_mov_b64_e32 v[104:105], 0
	v_mov_b64_e32 v[106:107], 0
	v_mov_b64_e32 v[108:109], 0
	v_mov_b64_e32 v[110:111], 0
	v_mov_b64_e32 v[112:113], 0
	v_mov_b64_e32 v[114:115], 0
	v_mov_b64_e32 v[116:117], 0
	v_mov_b64_e32 v[118:119], 0
	v_mov_b64_e32 v[120:121], 0
	v_mov_b64_e32 v[122:123], 0
	v_mov_b64_e32 v[124:125], 0
	v_mov_b64_e32 v[126:127], 0
	s_cmp_eq_u32 s99, 1
	s_cbranch_scc0 .Lue_1493
	s_mov_b32 s99, 0
	s_barrier
.Lue_1493:
.LBB0_1493:
	ds_read_b128 v[156:159], v229
	ds_read_b128 v[152:155], v229 offset:1024
	ds_read_b128 v[148:151], v229 offset:2048
	ds_read_b128 v[144:147], v229 offset:3072
	ds_read_b128 v[140:143], v230
	ds_read_b128 v[136:139], v230 offset:1024
	ds_read_b128 v[132:135], v230 offset:2048
	ds_read_b128 v[128:131], v230 offset:3072
	s_add_u32 s38, s40, 0x100
	s_addc_u32 s39, s41, 0
	s_cmp_eq_u32 s60, 28
	s_cselect_b32 s46, s37, s38
	s_cselect_b32 s47, s29, s39
	s_cselect_b32 s44, s57, s58
	s_cselect_b32 s45, s27, s59
	s_add_u32 s42, s46, 0x80
	s_addc_u32 s43, s47, 0
	ds_read_b128 v[160:163], v231
	ds_read_b128 v[164:167], v231 offset:1024
	ds_read_b128 v[168:171], v231 offset:2048
	ds_read_b128 v[172:175], v231 offset:3072
	ds_read_b128 v[176:179], v231 offset:4096
	ds_read_b128 v[180:183], v231 offset:5120
	ds_read_b128 v[184:187], v231 offset:6144
	ds_read_b128 v[192:195], v231 offset:7168
	s_add_u32 s40, s40, 0x80080
	s_addc_u32 s41, s41, 0
	s_add_i32 m0, s1, 0xc000
	s_nop 0
	global_load_lds_dwordx4 v225, s[40:41]
	s_nop 0
	s_add_i32 m0, s1, 0xe000
	s_nop 0
	global_load_lds_dwordx4 v226, s[40:41]
	s_waitcnt vmcnt(8)
	s_waitcnt lgkmcnt(0)
	s_barrier
	s_setprio 1
	v_mfma_i32_16x16x64_i8 v[124:127], v[156:159], v[160:163], v[124:127]
	v_mfma_i32_16x16x64_i8 v[124:127], v[152:155], v[164:167], v[124:127]
	v_mfma_i32_16x16x64_i8 v[120:123], v[148:151], v[160:163], v[120:123]
	s_nop 0
	v_mfma_i32_16x16x64_i8 v[120:123], v[144:147], v[164:167], v[120:123]
	v_mfma_i32_16x16x64_i8 v[108:111], v[156:159], v[168:171], v[108:111]
	v_mfma_i32_16x16x64_i8 v[108:111], v[152:155], v[172:175], v[108:111]
	v_mfma_i32_16x16x64_i8 v[104:107], v[148:151], v[168:171], v[104:107]
	s_nop 0
	v_mfma_i32_16x16x64_i8 v[104:107], v[144:147], v[172:175], v[104:107]
	v_mfma_i32_16x16x64_i8 v[92:95], v[156:159], v[176:179], v[92:95]
	v_mfma_i32_16x16x64_i8 v[92:95], v[152:155], v[180:183], v[92:95]
	v_mfma_i32_16x16x64_i8 v[88:91], v[148:151], v[176:179], v[88:91]
	s_nop 0
	v_mfma_i32_16x16x64_i8 v[88:91], v[144:147], v[180:183], v[88:91]
	v_mfma_i32_16x16x64_i8 v[76:79], v[156:159], v[184:187], v[76:79]
	v_mfma_i32_16x16x64_i8 v[76:79], v[152:155], v[192:195], v[76:79]
	v_mfma_i32_16x16x64_i8 v[72:75], v[148:151], v[184:187], v[72:75]
	s_nop 0
	v_mfma_i32_16x16x64_i8 v[72:75], v[144:147], v[192:195], v[72:75]
	v_mfma_i32_16x16x64_i8 v[116:119], v[140:143], v[160:163], v[116:119]
	s_nop 0
	v_mfma_i32_16x16x64_i8 v[116:119], v[136:139], v[164:167], v[116:119]
	v_mfma_i32_16x16x64_i8 v[112:115], v[132:135], v[160:163], v[112:115]
	s_nop 0
	v_mfma_i32_16x16x64_i8 v[112:115], v[128:131], v[164:167], v[112:115]
	v_mfma_i32_16x16x64_i8 v[100:103], v[140:143], v[168:171], v[100:103]
	s_nop 0
	v_mfma_i32_16x16x64_i8 v[100:103], v[136:139], v[172:175], v[100:103]
	v_mfma_i32_16x16x64_i8 v[96:99], v[132:135], v[168:171], v[96:99]
	s_nop 0
	v_mfma_i32_16x16x64_i8 v[96:99], v[128:131], v[172:175], v[96:99]
	v_mfma_i32_16x16x64_i8 v[84:87], v[140:143], v[176:179], v[84:87]
	s_nop 0
	v_mfma_i32_16x16x64_i8 v[84:87], v[136:139], v[180:183], v[84:87]
	v_mfma_i32_16x16x64_i8 v[80:83], v[132:135], v[176:179], v[80:83]
	s_nop 0
	v_mfma_i32_16x16x64_i8 v[80:83], v[128:131], v[180:183], v[80:83]
	v_mfma_i32_16x16x64_i8 v[68:71], v[140:143], v[184:187], v[68:71]
	s_nop 0
	v_mfma_i32_16x16x64_i8 v[68:71], v[136:139], v[192:195], v[68:71]
	v_mfma_i32_16x16x64_i8 v[64:67], v[132:135], v[184:187], v[64:67]
	s_nop 0
	v_mfma_i32_16x16x64_i8 v[64:67], v[128:131], v[192:195], v[64:67]
	s_setprio 0
	s_barrier
	ds_read_b128 v[160:163], v231 offset:16384
	ds_read_b128 v[164:167], v231 offset:17408
	ds_read_b128 v[168:171], v231 offset:18432
	ds_read_b128 v[172:175], v231 offset:19456
	ds_read_b128 v[176:179], v231 offset:20480
	ds_read_b128 v[180:183], v231 offset:21504
	ds_read_b128 v[184:187], v231 offset:22528
	ds_read_b128 v[192:195], v231 offset:23552
	s_add_i32 m0, s1, 0x10000
	s_nop 0
	global_load_lds_dwordx4 v225, s[44:45]
	s_nop 0
	s_add_i32 m0, s1, 0x12000
	s_nop 0
	global_load_lds_dwordx4 v226, s[44:45]
	s_add_u32 s40, s44, 0x80000
	s_addc_u32 s41, s45, 0
	s_add_i32 m0, s1, 0x14000
	s_nop 0
	global_load_lds_dwordx4 v225, s[40:41]
	s_nop 0
	s_add_i32 m0, s1, 0x16000
	s_nop 0
	global_load_lds_dwordx4 v226, s[40:41]
	s_nop 0
	s_add_i32 m0, s1, 0
	s_nop 0
	global_load_lds_dwordx4 v225, s[46:47]
	s_nop 0
	s_add_i32 m0, s1, 0x2000
	s_nop 0
	global_load_lds_dwordx4 v226, s[46:47]
	s_waitcnt vmcnt(8)
	s_waitcnt lgkmcnt(0)
	s_barrier
	s_setprio 1
	v_mfma_i32_16x16x64_i8 v[60:63], v[156:159], v[160:163], v[60:63]
	v_mfma_i32_16x16x64_i8 v[60:63], v[152:155], v[164:167], v[60:63]
	v_mfma_i32_16x16x64_i8 v[56:59], v[148:151], v[160:163], v[56:59]
	s_nop 0
	v_mfma_i32_16x16x64_i8 v[56:59], v[144:147], v[164:167], v[56:59]
	v_mfma_i32_16x16x64_i8 v[44:47], v[156:159], v[168:171], v[44:47]
	v_mfma_i32_16x16x64_i8 v[44:47], v[152:155], v[172:175], v[44:47]
	v_mfma_i32_16x16x64_i8 v[40:43], v[148:151], v[168:171], v[40:43]
	s_nop 0
	v_mfma_i32_16x16x64_i8 v[40:43], v[144:147], v[172:175], v[40:43]
	v_mfma_i32_16x16x64_i8 v[28:31], v[156:159], v[176:179], v[28:31]
	v_mfma_i32_16x16x64_i8 v[28:31], v[152:155], v[180:183], v[28:31]
	v_mfma_i32_16x16x64_i8 v[24:27], v[148:151], v[176:179], v[24:27]
	s_nop 0
	v_mfma_i32_16x16x64_i8 v[24:27], v[144:147], v[180:183], v[24:27]
	v_mfma_i32_16x16x64_i8 v[12:15], v[156:159], v[184:187], v[12:15]
	v_mfma_i32_16x16x64_i8 v[12:15], v[152:155], v[192:195], v[12:15]
	v_mfma_i32_16x16x64_i8 v[8:11], v[148:151], v[184:187], v[8:11]
	s_nop 0
	v_mfma_i32_16x16x64_i8 v[8:11], v[144:147], v[192:195], v[8:11]
	v_mfma_i32_16x16x64_i8 v[52:55], v[140:143], v[160:163], v[52:55]
	s_nop 0
	v_mfma_i32_16x16x64_i8 v[52:55], v[136:139], v[164:167], v[52:55]
	v_mfma_i32_16x16x64_i8 v[48:51], v[132:135], v[160:163], v[48:51]
	s_nop 0
	v_mfma_i32_16x16x64_i8 v[48:51], v[128:131], v[164:167], v[48:51]
	v_mfma_i32_16x16x64_i8 v[36:39], v[140:143], v[168:171], v[36:39]
	s_nop 0
	v_mfma_i32_16x16x64_i8 v[36:39], v[136:139], v[172:175], v[36:39]
	v_mfma_i32_16x16x64_i8 v[32:35], v[132:135], v[168:171], v[32:35]
	s_nop 0
	v_mfma_i32_16x16x64_i8 v[32:35], v[128:131], v[172:175], v[32:35]
	v_mfma_i32_16x16x64_i8 v[20:23], v[140:143], v[176:179], v[20:23]
	s_nop 0
	v_mfma_i32_16x16x64_i8 v[20:23], v[136:139], v[180:183], v[20:23]
	v_mfma_i32_16x16x64_i8 v[16:19], v[132:135], v[176:179], v[16:19]
	s_nop 0
	v_mfma_i32_16x16x64_i8 v[16:19], v[128:131], v[180:183], v[16:19]
	v_mfma_i32_16x16x64_i8 v[4:7], v[140:143], v[184:187], v[4:7]
	s_nop 0
	v_mfma_i32_16x16x64_i8 v[4:7], v[136:139], v[192:195], v[4:7]
	v_mfma_i32_16x16x64_i8 v[0:3], v[132:135], v[184:187], v[0:3]
	s_nop 0
	v_mfma_i32_16x16x64_i8 v[0:3], v[128:131], v[192:195], v[0:3]
	s_setprio 0
	s_barrier
	ds_read_b128 v[128:131], v232
	ds_read_b128 v[132:135], v232 offset:1024
	ds_read_b128 v[136:139], v232 offset:2048
	ds_read_b128 v[140:143], v232 offset:3072
	ds_read_b128 v[144:147], v233
	ds_read_b128 v[148:151], v233 offset:1024
	ds_read_b128 v[152:155], v233 offset:2048
	ds_read_b128 v[156:159], v233 offset:3072
	ds_read_b128 v[160:163], v231 offset:32768
	ds_read_b128 v[164:167], v231 offset:33792
	ds_read_b128 v[168:171], v231 offset:34816
	ds_read_b128 v[172:175], v231 offset:35840
	ds_read_b128 v[176:179], v231 offset:36864
	ds_read_b128 v[180:183], v231 offset:37888
	ds_read_b128 v[184:187], v231 offset:38912
	ds_read_b128 v[192:195], v231 offset:39936
	s_add_u32 s40, s46, 0x80000
	s_addc_u32 s41, s47, 0
	s_add_i32 m0, s1, 0x4000
	s_nop 0
	global_load_lds_dwordx4 v225, s[40:41]
	s_nop 0
	s_add_i32 m0, s1, 0x6000
	s_nop 0
	global_load_lds_dwordx4 v226, s[40:41]
	s_waitcnt vmcnt(8)
	s_waitcnt lgkmcnt(0)
	s_barrier
	s_setprio 1
	v_mfma_i32_16x16x64_i8 v[124:127], v[128:131], v[160:163], v[124:127]
	v_mfma_i32_16x16x64_i8 v[124:127], v[132:135], v[164:167], v[124:127]
	v_mfma_i32_16x16x64_i8 v[120:123], v[136:139], v[160:163], v[120:123]
	s_nop 0
	v_mfma_i32_16x16x64_i8 v[120:123], v[140:143], v[164:167], v[120:123]
	v_mfma_i32_16x16x64_i8 v[108:111], v[128:131], v[168:171], v[108:111]
	v_mfma_i32_16x16x64_i8 v[108:111], v[132:135], v[172:175], v[108:111]
	v_mfma_i32_16x16x64_i8 v[104:107], v[136:139], v[168:171], v[104:107]
	s_nop 0
	v_mfma_i32_16x16x64_i8 v[104:107], v[140:143], v[172:175], v[104:107]
	v_mfma_i32_16x16x64_i8 v[92:95], v[128:131], v[176:179], v[92:95]
	v_mfma_i32_16x16x64_i8 v[92:95], v[132:135], v[180:183], v[92:95]
	v_mfma_i32_16x16x64_i8 v[88:91], v[136:139], v[176:179], v[88:91]
	s_nop 0
	v_mfma_i32_16x16x64_i8 v[88:91], v[140:143], v[180:183], v[88:91]
	v_mfma_i32_16x16x64_i8 v[76:79], v[128:131], v[184:187], v[76:79]
	v_mfma_i32_16x16x64_i8 v[76:79], v[132:135], v[192:195], v[76:79]
	v_mfma_i32_16x16x64_i8 v[72:75], v[136:139], v[184:187], v[72:75]
	s_nop 0
	v_mfma_i32_16x16x64_i8 v[72:75], v[140:143], v[192:195], v[72:75]
	v_mfma_i32_16x16x64_i8 v[116:119], v[144:147], v[160:163], v[116:119]
	s_nop 0
	v_mfma_i32_16x16x64_i8 v[116:119], v[148:151], v[164:167], v[116:119]
	v_mfma_i32_16x16x64_i8 v[112:115], v[152:155], v[160:163], v[112:115]
	s_nop 0
	v_mfma_i32_16x16x64_i8 v[112:115], v[156:159], v[164:167], v[112:115]
	v_mfma_i32_16x16x64_i8 v[100:103], v[144:147], v[168:171], v[100:103]
	s_nop 0
	v_mfma_i32_16x16x64_i8 v[100:103], v[148:151], v[172:175], v[100:103]
	v_mfma_i32_16x16x64_i8 v[96:99], v[152:155], v[168:171], v[96:99]
	s_nop 0
	v_mfma_i32_16x16x64_i8 v[96:99], v[156:159], v[172:175], v[96:99]
	v_mfma_i32_16x16x64_i8 v[84:87], v[144:147], v[176:179], v[84:87]
	s_nop 0
	v_mfma_i32_16x16x64_i8 v[84:87], v[148:151], v[180:183], v[84:87]
	v_mfma_i32_16x16x64_i8 v[80:83], v[152:155], v[176:179], v[80:83]
	s_nop 0
	v_mfma_i32_16x16x64_i8 v[80:83], v[156:159], v[180:183], v[80:83]
	v_mfma_i32_16x16x64_i8 v[68:71], v[144:147], v[184:187], v[68:71]
	s_nop 0
	v_mfma_i32_16x16x64_i8 v[68:71], v[148:151], v[192:195], v[68:71]
	v_mfma_i32_16x16x64_i8 v[64:67], v[152:155], v[184:187], v[64:67]
	s_nop 0
	v_mfma_i32_16x16x64_i8 v[64:67], v[156:159], v[192:195], v[64:67]
	s_setprio 0
	s_barrier
	s_add_u32 s40, s44, 0x80
	s_addc_u32 s41, s45, 0
	ds_read_b128 v[160:163], v231 offset:49152
	ds_read_b128 v[164:167], v231 offset:50176
	ds_read_b128 v[168:171], v231 offset:51200
	ds_read_b128 v[172:175], v231 offset:52224
	ds_read_b128 v[176:179], v231 offset:53248
	ds_read_b128 v[180:183], v231 offset:54272
	ds_read_b128 v[184:187], v231 offset:55296
	ds_read_b128 v[192:195], v231 offset:56320
	s_add_i32 m0, s1, 0x18000
	s_nop 0
	global_load_lds_dwordx4 v225, s[40:41]
	s_nop 0
	s_add_i32 m0, s1, 0x1a000
	s_nop 0
	global_load_lds_dwordx4 v226, s[40:41]
	s_add_u32 s40, s44, 0x80080
	s_addc_u32 s41, s45, 0
	s_add_i32 m0, s1, 0x1c000
	s_nop 0
	global_load_lds_dwordx4 v225, s[40:41]
	s_nop 0
	s_add_i32 m0, s1, 0x1e000
	s_nop 0
	global_load_lds_dwordx4 v226, s[40:41]
	s_nop 0
	s_add_i32 m0, s1, 0x8000
	s_nop 0
	global_load_lds_dwordx4 v225, s[42:43]
	s_nop 0
	s_add_i32 m0, s1, 0xa000
	s_nop 0
	global_load_lds_dwordx4 v226, s[42:43]
	s_waitcnt vmcnt(8)
	s_waitcnt lgkmcnt(0)
	s_barrier
	s_setprio 1
	v_mfma_i32_16x16x64_i8 v[60:63], v[128:131], v[160:163], v[60:63]
	v_mfma_i32_16x16x64_i8 v[60:63], v[132:135], v[164:167], v[60:63]
	v_mfma_i32_16x16x64_i8 v[56:59], v[136:139], v[160:163], v[56:59]
	s_nop 0
	v_mfma_i32_16x16x64_i8 v[56:59], v[140:143], v[164:167], v[56:59]
	v_mfma_i32_16x16x64_i8 v[44:47], v[128:131], v[168:171], v[44:47]
	v_mfma_i32_16x16x64_i8 v[44:47], v[132:135], v[172:175], v[44:47]
	v_mfma_i32_16x16x64_i8 v[40:43], v[136:139], v[168:171], v[40:43]
	s_nop 0
	v_mfma_i32_16x16x64_i8 v[40:43], v[140:143], v[172:175], v[40:43]
	v_mfma_i32_16x16x64_i8 v[28:31], v[128:131], v[176:179], v[28:31]
	v_mfma_i32_16x16x64_i8 v[28:31], v[132:135], v[180:183], v[28:31]
	v_mfma_i32_16x16x64_i8 v[24:27], v[136:139], v[176:179], v[24:27]
	s_nop 0
	v_mfma_i32_16x16x64_i8 v[24:27], v[140:143], v[180:183], v[24:27]
	v_mfma_i32_16x16x64_i8 v[12:15], v[128:131], v[184:187], v[12:15]
	v_mfma_i32_16x16x64_i8 v[12:15], v[132:135], v[192:195], v[12:15]
	v_mfma_i32_16x16x64_i8 v[8:11], v[136:139], v[184:187], v[8:11]
	s_nop 0
	v_mfma_i32_16x16x64_i8 v[8:11], v[140:143], v[192:195], v[8:11]
	v_mfma_i32_16x16x64_i8 v[52:55], v[144:147], v[160:163], v[52:55]
	s_nop 0
	v_mfma_i32_16x16x64_i8 v[52:55], v[148:151], v[164:167], v[52:55]
	v_mfma_i32_16x16x64_i8 v[48:51], v[152:155], v[160:163], v[48:51]
	s_nop 0
	v_mfma_i32_16x16x64_i8 v[48:51], v[156:159], v[164:167], v[48:51]
	v_mfma_i32_16x16x64_i8 v[36:39], v[144:147], v[168:171], v[36:39]
	s_nop 0
	v_mfma_i32_16x16x64_i8 v[36:39], v[148:151], v[172:175], v[36:39]
	v_mfma_i32_16x16x64_i8 v[32:35], v[152:155], v[168:171], v[32:35]
	s_nop 0
	v_mfma_i32_16x16x64_i8 v[32:35], v[156:159], v[172:175], v[32:35]
	v_mfma_i32_16x16x64_i8 v[20:23], v[144:147], v[176:179], v[20:23]
	s_nop 0
	v_mfma_i32_16x16x64_i8 v[20:23], v[148:151], v[180:183], v[20:23]
	v_mfma_i32_16x16x64_i8 v[16:19], v[152:155], v[176:179], v[16:19]
	s_nop 0
	v_mfma_i32_16x16x64_i8 v[16:19], v[156:159], v[180:183], v[16:19]
	v_mfma_i32_16x16x64_i8 v[4:7], v[144:147], v[184:187], v[4:7]
	s_nop 0
	v_mfma_i32_16x16x64_i8 v[4:7], v[148:151], v[192:195], v[4:7]
	v_mfma_i32_16x16x64_i8 v[0:3], v[152:155], v[184:187], v[0:3]
	s_nop 0
	v_mfma_i32_16x16x64_i8 v[0:3], v[156:159], v[192:195], v[0:3]
	s_setprio 0
	s_barrier
	s_add_i32 s60, s60, 2
	s_add_u32 s58, s58, 0x100
	s_addc_u32 s59, s59, 0
	s_cmp_gt_u32 s60, 29
	s_mov_b64 s[40:41], s[38:39]
	s_cbranch_scc0 .LBB0_1493
	s_and_b64 vcc, exec, s[20:21]
	s_cbranch_vccz .LBB0_1496
	s_barrier

.LBB0_1512:
	s_or_b64 exec, exec, s[38:39]
	s_andn2_b64 vcc, exec, s[4:5]
	s_mov_b64 s[4:5], -1
	s_cbranch_vccnz .LBB0_1485
	s_andn2_b64 vcc, exec, s[8:9]
	s_cbranch_vccnz .LBB0_1484
	s_mov_b32 s99, 1
	s_branch .LBB0_1484

.LBB0_1604:
	s_ashr_i32 s25, s24, 31
	s_lshl_b64 s[26:27], s[24:25], 21
	s_add_u32 s26, s1, s26
	s_addc_u32 s27, s33, s27
	s_and_b64 s[28:29], s[4:5], exec
	s_cselect_b32 s25, s27, s35
	s_cselect_b32 s58, s26, s34
	s_ashr_i32 s23, s22, 31
	s_lshl_b64 s[28:29], s[22:23], 21
	s_add_u32 s28, s44, s28
	s_addc_u32 s29, s45, s29
	s_and_b64 s[38:39], s[4:5], exec
	s_cselect_b32 s23, s29, s37
	s_cselect_b32 s59, s28, s36
	s_add_u32 s60, s36, 0x100
	s_addc_u32 s61, s37, 0
	s_mov_b32 s62, -2
	s_waitcnt vmcnt(1)
	v_mov_b64_e32 v[0:1], 0
	v_mov_b64_e32 v[2:3], 0
	v_mov_b64_e32 v[4:5], 0
	v_mov_b64_e32 v[6:7], 0
	v_mov_b64_e32 v[8:9], 0
	v_mov_b64_e32 v[10:11], 0
	v_mov_b64_e32 v[12:13], 0
	v_mov_b64_e32 v[14:15], 0
	v_mov_b64_e32 v[16:17], 0
	v_mov_b64_e32 v[18:19], 0
	v_mov_b64_e32 v[20:21], 0
	v_mov_b64_e32 v[22:23], 0
	v_mov_b64_e32 v[24:25], 0
	v_mov_b64_e32 v[26:27], 0
	v_mov_b64_e32 v[28:29], 0
	v_mov_b64_e32 v[30:31], 0
	v_mov_b64_e32 v[32:33], 0
	v_mov_b64_e32 v[34:35], 0
	v_mov_b64_e32 v[36:37], 0
	v_mov_b64_e32 v[38:39], 0
	v_mov_b64_e32 v[40:41], 0
	v_mov_b64_e32 v[42:43], 0
	v_mov_b64_e32 v[44:45], 0
	v_mov_b64_e32 v[46:47], 0
	v_mov_b64_e32 v[48:49], 0
	v_mov_b64_e32 v[50:51], 0
	v_mov_b64_e32 v[52:53], 0
	v_mov_b64_e32 v[54:55], 0
	v_mov_b64_e32 v[56:57], 0
	v_mov_b64_e32 v[58:59], 0
	v_mov_b64_e32 v[60:61], 0
	v_mov_b64_e32 v[62:63], 0
	v_mov_b64_e32 v[64:65], 0
	v_mov_b64_e32 v[66:67], 0
	v_mov_b64_e32 v[68:69], 0
	v_mov_b64_e32 v[70:71], 0
	v_mov_b64_e32 v[72:73], 0
	v_mov_b64_e32 v[74:75], 0
	v_mov_b64_e32 v[76:77], 0
	v_mov_b64_e32 v[78:79], 0
	v_mov_b64_e32 v[80:81], 0
	v_mov_b64_e32 v[82:83], 0
	v_mov_b64_e32 v[84:85], 0
	v_mov_b64_e32 v[86:87], 0
	v_mov_b64_e32 v[88:89], 0
	v_mov_b64_e32 v[90:91], 0
	v_mov_b64_e32 v[92:93], 0
	v_mov_b64_e32 v[94:95], 0
	v_mov_b64_e32 v[96:97], 0
	v_mov_b64_e32 v[98:99], 0
	v_mov_b64_e32 v[100:101], 0
	v_mov_b64_e32 v[102:103], 0
	v_mov_b64_e32 v[104:105], 0
	v_mov_b64_e32 v[106:107], 0
	v_mov_b64_e32 v[108:109], 0
	v_mov_b64_e32 v[110:111], 0
	v_mov_b64_e32 v[112:113], 0
	v_mov_b64_e32 v[114:115], 0
	v_mov_b64_e32 v[116:117], 0
	v_mov_b64_e32 v[118:119], 0
	v_mov_b64_e32 v[128:129], 0
	v_mov_b64_e32 v[130:131], 0
	v_mov_b64_e32 v[132:133], 0
	v_mov_b64_e32 v[134:135], 0
	s_cmp_eq_u32 s99, 1
	s_cbranch_scc0 .Lue_1605
	s_mov_b32 s99, 0
	s_barrier
.Lue_1605:
.LBB0_1605:
	ds_read_b128 v[120:123], v154
	ds_read_b128 v[124:127], v154 offset:1024
	ds_read_b128 v[136:139], v154 offset:2048
	ds_read_b128 v[140:143], v154 offset:3072
	ds_read_b128 v[148:151], v155
	ds_read_b128 v[160:163], v155 offset:1024
	ds_read_b128 v[164:167], v155 offset:2048
	ds_read_b128 v[168:171], v155 offset:3072
	s_add_u32 s36, s34, 0x100
	s_addc_u32 s37, s35, 0
	s_cmp_eq_u32 s62, 60
	s_cselect_b32 s42, s58, s36
	s_cselect_b32 s43, s25, s37
	s_cselect_b32 s40, s59, s60
	s_cselect_b32 s41, s23, s61
	s_add_u32 s38, s42, 0x80
	s_addc_u32 s39, s43, 0
	ds_read_b128 v[172:175], v156
	ds_read_b128 v[176:179], v156 offset:1024
	ds_read_b128 v[180:183], v156 offset:2048
	ds_read_b128 v[184:187], v156 offset:3072
	ds_read_b128 v[188:191], v156 offset:4096
	ds_read_b128 v[192:195], v156 offset:5120
	ds_read_b128 v[196:199], v156 offset:6144
	ds_read_b128 v[200:203], v156 offset:7168
	s_add_u32 s34, s34, 0x100080
	s_addc_u32 s35, s35, 0
	s_add_i32 m0, s0, 0xc000
	s_nop 0
	global_load_lds_dwordx4 v152, s[34:35]
	s_nop 0
	s_add_i32 m0, s0, 0xe000
	s_nop 0
	global_load_lds_dwordx4 v153, s[34:35]
	s_waitcnt vmcnt(8)
	s_waitcnt lgkmcnt(0)
	s_barrier
	s_setprio 1
	v_mfma_f32_16x16x32_bf16 v[132:135], v[120:123], v[172:175], v[132:135]
	v_mfma_f32_16x16x32_bf16 v[128:131], v[136:139], v[172:175], v[128:131]
	v_mfma_f32_16x16x32_bf16 v[116:119], v[120:123], v[180:183], v[116:119]
	v_mfma_f32_16x16x32_bf16 v[112:115], v[136:139], v[180:183], v[112:115]
	v_mfma_f32_16x16x32_bf16 v[92:95], v[120:123], v[188:191], v[92:95]
	v_mfma_f32_16x16x32_bf16 v[88:91], v[136:139], v[188:191], v[88:91]
	v_mfma_f32_16x16x32_bf16 v[76:79], v[120:123], v[196:199], v[76:79]
	v_mfma_f32_16x16x32_bf16 v[72:75], v[136:139], v[196:199], v[72:75]
	v_mfma_f32_16x16x32_bf16 v[132:135], v[124:127], v[176:179], v[132:135]
	v_mfma_f32_16x16x32_bf16 v[128:131], v[140:143], v[176:179], v[128:131]
	v_mfma_f32_16x16x32_bf16 v[116:119], v[124:127], v[184:187], v[116:119]
	v_mfma_f32_16x16x32_bf16 v[112:115], v[140:143], v[184:187], v[112:115]
	v_mfma_f32_16x16x32_bf16 v[92:95], v[124:127], v[192:195], v[92:95]
	v_mfma_f32_16x16x32_bf16 v[88:91], v[140:143], v[192:195], v[88:91]
	v_mfma_f32_16x16x32_bf16 v[76:79], v[124:127], v[200:203], v[76:79]
	v_mfma_f32_16x16x32_bf16 v[72:75], v[140:143], v[200:203], v[72:75]
	v_mfma_f32_16x16x32_bf16 v[108:111], v[148:151], v[172:175], v[108:111]
	v_mfma_f32_16x16x32_bf16 v[104:107], v[164:167], v[172:175], v[104:107]
	v_mfma_f32_16x16x32_bf16 v[100:103], v[148:151], v[180:183], v[100:103]
	v_mfma_f32_16x16x32_bf16 v[96:99], v[164:167], v[180:183], v[96:99]
	v_mfma_f32_16x16x32_bf16 v[84:87], v[148:151], v[188:191], v[84:87]
	v_mfma_f32_16x16x32_bf16 v[80:83], v[164:167], v[188:191], v[80:83]
	v_mfma_f32_16x16x32_bf16 v[68:71], v[148:151], v[196:199], v[68:71]
	v_mfma_f32_16x16x32_bf16 v[64:67], v[164:167], v[196:199], v[64:67]
	v_mfma_f32_16x16x32_bf16 v[108:111], v[160:163], v[176:179], v[108:111]
	v_mfma_f32_16x16x32_bf16 v[104:107], v[168:171], v[176:179], v[104:107]
	v_mfma_f32_16x16x32_bf16 v[100:103], v[160:163], v[184:187], v[100:103]
	v_mfma_f32_16x16x32_bf16 v[96:99], v[168:171], v[184:187], v[96:99]
	v_mfma_f32_16x16x32_bf16 v[84:87], v[160:163], v[192:195], v[84:87]
	v_mfma_f32_16x16x32_bf16 v[80:83], v[168:171], v[192:195], v[80:83]
	v_mfma_f32_16x16x32_bf16 v[68:71], v[160:163], v[200:203], v[68:71]
	v_mfma_f32_16x16x32_bf16 v[64:67], v[168:171], v[200:203], v[64:67]
	s_setprio 0
	s_barrier
	ds_read_b128 v[172:175], v156 offset:16384
	ds_read_b128 v[176:179], v156 offset:17408
	ds_read_b128 v[180:183], v156 offset:18432
	ds_read_b128 v[184:187], v156 offset:19456
	ds_read_b128 v[188:191], v156 offset:20480
	ds_read_b128 v[192:195], v156 offset:21504
	ds_read_b128 v[196:199], v156 offset:22528
	ds_read_b128 v[200:203], v156 offset:23552
	s_add_i32 m0, s0, 0x10000
	s_nop 0
	global_load_lds_dwordx4 v152, s[40:41]
	s_nop 0
	s_add_i32 m0, s0, 0x12000
	s_nop 0
	global_load_lds_dwordx4 v153, s[40:41]
	s_add_u32 s34, s40, 0x100000
	s_addc_u32 s35, s41, 0
	s_add_i32 m0, s0, 0x14000
	s_nop 0
	global_load_lds_dwordx4 v152, s[34:35]
	s_nop 0
	s_add_i32 m0, s0, 0x16000
	s_nop 0
	global_load_lds_dwordx4 v153, s[34:35]
	s_nop 0
	s_add_i32 m0, s0, 0
	s_nop 0
	global_load_lds_dwordx4 v152, s[42:43]
	s_nop 0
	s_add_i32 m0, s0, 0x2000
	s_nop 0
	global_load_lds_dwordx4 v153, s[42:43]
	s_waitcnt vmcnt(8)
	s_waitcnt lgkmcnt(0)
	s_barrier
	s_setprio 1
	v_mfma_f32_16x16x32_bf16 v[60:63], v[120:123], v[172:175], v[60:63]
	v_mfma_f32_16x16x32_bf16 v[56:59], v[136:139], v[172:175], v[56:59]
	v_mfma_f32_16x16x32_bf16 v[52:55], v[120:123], v[180:183], v[52:55]
	v_mfma_f32_16x16x32_bf16 v[44:47], v[136:139], v[180:183], v[44:47]
	v_mfma_f32_16x16x32_bf16 v[36:39], v[120:123], v[188:191], v[36:39]
	v_mfma_f32_16x16x32_bf16 v[28:31], v[136:139], v[188:191], v[28:31]
	v_mfma_f32_16x16x32_bf16 v[16:19], v[120:123], v[196:199], v[16:19]
	v_mfma_f32_16x16x32_bf16 v[8:11], v[136:139], v[196:199], v[8:11]
	v_mfma_f32_16x16x32_bf16 v[60:63], v[124:127], v[176:179], v[60:63]
	v_mfma_f32_16x16x32_bf16 v[56:59], v[140:143], v[176:179], v[56:59]
	v_mfma_f32_16x16x32_bf16 v[52:55], v[124:127], v[184:187], v[52:55]
	v_mfma_f32_16x16x32_bf16 v[44:47], v[140:143], v[184:187], v[44:47]
	v_mfma_f32_16x16x32_bf16 v[36:39], v[124:127], v[192:195], v[36:39]
	v_mfma_f32_16x16x32_bf16 v[28:31], v[140:143], v[192:195], v[28:31]
	v_mfma_f32_16x16x32_bf16 v[16:19], v[124:127], v[200:203], v[16:19]
	v_mfma_f32_16x16x32_bf16 v[8:11], v[140:143], v[200:203], v[8:11]
	v_mfma_f32_16x16x32_bf16 v[48:51], v[148:151], v[172:175], v[48:51]
	v_mfma_f32_16x16x32_bf16 v[40:43], v[164:167], v[172:175], v[40:43]
	v_mfma_f32_16x16x32_bf16 v[32:35], v[148:151], v[180:183], v[32:35]
	v_mfma_f32_16x16x32_bf16 v[24:27], v[164:167], v[180:183], v[24:27]
	v_mfma_f32_16x16x32_bf16 v[20:23], v[148:151], v[188:191], v[20:23]
	v_mfma_f32_16x16x32_bf16 v[12:15], v[164:167], v[188:191], v[12:15]
	v_mfma_f32_16x16x32_bf16 v[4:7], v[148:151], v[196:199], v[4:7]
	v_mfma_f32_16x16x32_bf16 v[0:3], v[164:167], v[196:199], v[0:3]
	v_mfma_f32_16x16x32_bf16 v[48:51], v[160:163], v[176:179], v[48:51]
	v_mfma_f32_16x16x32_bf16 v[40:43], v[168:171], v[176:179], v[40:43]
	v_mfma_f32_16x16x32_bf16 v[32:35], v[160:163], v[184:187], v[32:35]
	v_mfma_f32_16x16x32_bf16 v[24:27], v[168:171], v[184:187], v[24:27]
	v_mfma_f32_16x16x32_bf16 v[20:23], v[160:163], v[192:195], v[20:23]
	v_mfma_f32_16x16x32_bf16 v[12:15], v[168:171], v[192:195], v[12:15]
	v_mfma_f32_16x16x32_bf16 v[4:7], v[160:163], v[200:203], v[4:7]
	v_mfma_f32_16x16x32_bf16 v[0:3], v[168:171], v[200:203], v[0:3]
	s_setprio 0
	s_barrier
	ds_read_b128 v[120:123], v157
	ds_read_b128 v[124:127], v157 offset:1024
	ds_read_b128 v[136:139], v157 offset:2048
	ds_read_b128 v[140:143], v157 offset:3072
	ds_read_b128 v[148:151], v158
	ds_read_b128 v[160:163], v158 offset:1024
	ds_read_b128 v[164:167], v158 offset:2048
	ds_read_b128 v[168:171], v158 offset:3072
	ds_read_b128 v[172:175], v156 offset:32768
	ds_read_b128 v[176:179], v156 offset:33792
	ds_read_b128 v[180:183], v156 offset:34816
	ds_read_b128 v[184:187], v156 offset:35840
	ds_read_b128 v[188:191], v156 offset:36864
	ds_read_b128 v[192:195], v156 offset:37888
	ds_read_b128 v[196:199], v156 offset:38912
	ds_read_b128 v[200:203], v156 offset:39936
	s_add_u32 s34, s42, 0x100000
	s_addc_u32 s35, s43, 0
	s_add_i32 m0, s0, 0x4000
	s_nop 0
	global_load_lds_dwordx4 v152, s[34:35]
	s_nop 0
	s_add_i32 m0, s0, 0x6000
	s_nop 0
	global_load_lds_dwordx4 v153, s[34:35]
	s_waitcnt vmcnt(8)
	s_waitcnt lgkmcnt(0)
	s_barrier
	s_setprio 1
	v_mfma_f32_16x16x32_bf16 v[132:135], v[120:123], v[172:175], v[132:135]
	v_mfma_f32_16x16x32_bf16 v[128:131], v[136:139], v[172:175], v[128:131]
	v_mfma_f32_16x16x32_bf16 v[116:119], v[120:123], v[180:183], v[116:119]
	v_mfma_f32_16x16x32_bf16 v[112:115], v[136:139], v[180:183], v[112:115]
	v_mfma_f32_16x16x32_bf16 v[92:95], v[120:123], v[188:191], v[92:95]
	v_mfma_f32_16x16x32_bf16 v[88:91], v[136:139], v[188:191], v[88:91]
	v_mfma_f32_16x16x32_bf16 v[76:79], v[120:123], v[196:199], v[76:79]
	v_mfma_f32_16x16x32_bf16 v[72:75], v[136:139], v[196:199], v[72:75]
	v_mfma_f32_16x16x32_bf16 v[132:135], v[124:127], v[176:179], v[132:135]
	v_mfma_f32_16x16x32_bf16 v[128:131], v[140:143], v[176:179], v[128:131]
	v_mfma_f32_16x16x32_bf16 v[116:119], v[124:127], v[184:187], v[116:119]
	v_mfma_f32_16x16x32_bf16 v[112:115], v[140:143], v[184:187], v[112:115]
	v_mfma_f32_16x16x32_bf16 v[92:95], v[124:127], v[192:195], v[92:95]
	v_mfma_f32_16x16x32_bf16 v[88:91], v[140:143], v[192:195], v[88:91]
	v_mfma_f32_16x16x32_bf16 v[76:79], v[124:127], v[200:203], v[76:79]
	v_mfma_f32_16x16x32_bf16 v[72:75], v[140:143], v[200:203], v[72:75]
	v_mfma_f32_16x16x32_bf16 v[108:111], v[148:151], v[172:175], v[108:111]
	v_mfma_f32_16x16x32_bf16 v[104:107], v[164:167], v[172:175], v[104:107]
	v_mfma_f32_16x16x32_bf16 v[100:103], v[148:151], v[180:183], v[100:103]
	v_mfma_f32_16x16x32_bf16 v[96:99], v[164:167], v[180:183], v[96:99]
	v_mfma_f32_16x16x32_bf16 v[84:87], v[148:151], v[188:191], v[84:87]
	v_mfma_f32_16x16x32_bf16 v[80:83], v[164:167], v[188:191], v[80:83]
	v_mfma_f32_16x16x32_bf16 v[68:71], v[148:151], v[196:199], v[68:71]
	v_mfma_f32_16x16x32_bf16 v[64:67], v[164:167], v[196:199], v[64:67]
	v_mfma_f32_16x16x32_bf16 v[108:111], v[160:163], v[176:179], v[108:111]
	v_mfma_f32_16x16x32_bf16 v[104:107], v[168:171], v[176:179], v[104:107]
	v_mfma_f32_16x16x32_bf16 v[100:103], v[160:163], v[184:187], v[100:103]
	v_mfma_f32_16x16x32_bf16 v[96:99], v[168:171], v[184:187], v[96:99]
	v_mfma_f32_16x16x32_bf16 v[84:87], v[160:163], v[192:195], v[84:87]
	v_mfma_f32_16x16x32_bf16 v[80:83], v[168:171], v[192:195], v[80:83]
	v_mfma_f32_16x16x32_bf16 v[68:71], v[160:163], v[200:203], v[68:71]
	v_mfma_f32_16x16x32_bf16 v[64:67], v[168:171], v[200:203], v[64:67]
	s_setprio 0
	s_barrier
	s_add_u32 s34, s40, 0x80
	ds_read_b128 v[172:175], v156 offset:49152
	ds_read_b128 v[176:179], v156 offset:50176
	ds_read_b128 v[180:183], v156 offset:51200
	ds_read_b128 v[184:187], v156 offset:52224
	ds_read_b128 v[188:191], v156 offset:53248
	ds_read_b128 v[192:195], v156 offset:54272
	ds_read_b128 v[196:199], v156 offset:55296
	ds_read_b128 v[200:203], v156 offset:56320
	s_addc_u32 s35, s41, 0
	s_add_i32 m0, s0, 0x18000
	s_nop 0
	global_load_lds_dwordx4 v152, s[34:35]
	s_nop 0
	s_add_i32 m0, s0, 0x1a000
	s_nop 0
	global_load_lds_dwordx4 v153, s[34:35]
	s_add_u32 s34, s40, 0x100080
	s_addc_u32 s35, s41, 0
	s_add_i32 m0, s0, 0x1c000
	s_nop 0
	global_load_lds_dwordx4 v152, s[34:35]
	s_nop 0
	s_add_i32 m0, s0, 0x1e000
	s_nop 0
	global_load_lds_dwordx4 v153, s[34:35]
	s_nop 0
	s_add_i32 m0, s0, 0x8000
	s_nop 0
	global_load_lds_dwordx4 v152, s[38:39]
	s_nop 0
	s_add_i32 m0, s0, 0xa000
	s_nop 0
	global_load_lds_dwordx4 v153, s[38:39]
	s_waitcnt vmcnt(8)
	s_waitcnt lgkmcnt(0)
	s_barrier
	s_setprio 1
	v_mfma_f32_16x16x32_bf16 v[60:63], v[120:123], v[172:175], v[60:63]
	v_mfma_f32_16x16x32_bf16 v[56:59], v[136:139], v[172:175], v[56:59]
	v_mfma_f32_16x16x32_bf16 v[52:55], v[120:123], v[180:183], v[52:55]
	v_mfma_f32_16x16x32_bf16 v[44:47], v[136:139], v[180:183], v[44:47]
	v_mfma_f32_16x16x32_bf16 v[36:39], v[120:123], v[188:191], v[36:39]
	v_mfma_f32_16x16x32_bf16 v[28:31], v[136:139], v[188:191], v[28:31]
	v_mfma_f32_16x16x32_bf16 v[16:19], v[120:123], v[196:199], v[16:19]
	v_mfma_f32_16x16x32_bf16 v[8:11], v[136:139], v[196:199], v[8:11]
	v_mfma_f32_16x16x32_bf16 v[60:63], v[124:127], v[176:179], v[60:63]
	v_mfma_f32_16x16x32_bf16 v[56:59], v[140:143], v[176:179], v[56:59]
	v_mfma_f32_16x16x32_bf16 v[52:55], v[124:127], v[184:187], v[52:55]
	v_mfma_f32_16x16x32_bf16 v[44:47], v[140:143], v[184:187], v[44:47]
	v_mfma_f32_16x16x32_bf16 v[36:39], v[124:127], v[192:195], v[36:39]
	v_mfma_f32_16x16x32_bf16 v[28:31], v[140:143], v[192:195], v[28:31]
	v_mfma_f32_16x16x32_bf16 v[16:19], v[124:127], v[200:203], v[16:19]
	v_mfma_f32_16x16x32_bf16 v[8:11], v[140:143], v[200:203], v[8:11]
	v_mfma_f32_16x16x32_bf16 v[48:51], v[148:151], v[172:175], v[48:51]
	v_mfma_f32_16x16x32_bf16 v[40:43], v[164:167], v[172:175], v[40:43]
	v_mfma_f32_16x16x32_bf16 v[32:35], v[148:151], v[180:183], v[32:35]
	v_mfma_f32_16x16x32_bf16 v[24:27], v[164:167], v[180:183], v[24:27]
	v_mfma_f32_16x16x32_bf16 v[20:23], v[148:151], v[188:191], v[20:23]
	v_mfma_f32_16x16x32_bf16 v[12:15], v[164:167], v[188:191], v[12:15]
	v_mfma_f32_16x16x32_bf16 v[4:7], v[148:151], v[196:199], v[4:7]
	v_mfma_f32_16x16x32_bf16 v[0:3], v[164:167], v[196:199], v[0:3]
	v_mfma_f32_16x16x32_bf16 v[48:51], v[160:163], v[176:179], v[48:51]
	v_mfma_f32_16x16x32_bf16 v[40:43], v[168:171], v[176:179], v[40:43]
	v_mfma_f32_16x16x32_bf16 v[32:35], v[160:163], v[184:187], v[32:35]
	v_mfma_f32_16x16x32_bf16 v[24:27], v[168:171], v[184:187], v[24:27]
	v_mfma_f32_16x16x32_bf16 v[20:23], v[160:163], v[192:195], v[20:23]
	v_mfma_f32_16x16x32_bf16 v[12:15], v[168:171], v[192:195], v[12:15]
	v_mfma_f32_16x16x32_bf16 v[4:7], v[160:163], v[200:203], v[4:7]
	v_mfma_f32_16x16x32_bf16 v[0:3], v[168:171], v[200:203], v[0:3]
	s_setprio 0
	s_barrier
	s_add_i32 s62, s62, 2
	s_add_u32 s60, s60, 0x100
	s_addc_u32 s61, s61, 0
	s_cmp_gt_u32 s62, 61
	s_mov_b64 s[34:35], s[36:37]
	s_cbranch_scc0 .LBB0_1605
	s_and_b64 vcc, exec, s[12:13]
	s_cbranch_vccz .LBB0_1608
	s_barrier
.LBB0_1608:
	v_mov_b32_e32 v150, v223
	s_lshl_b32 s23, s57, 8
	v_ashrrev_i32_e32 v120, 1, v150
	s_or_b32 s23, s23, s46
	v_and_b32_e32 v120, -8, v120
	v_add_u32_e32 v148, s23, v120
	v_ashrrev_i32_e32 v149, 31, v148
	v_and_b32_e32 v151, 15, v150
	v_lshlrev_b32_e32 v174, 2, v151
	v_add_u32_e32 v159, s49, v174
	s_lshl_b32 s23, s30, 8
	ds_read2_b32 v[164:165], v159 offset1:16
	s_add_i32 s23, s23, s31
	v_or_b32_e32 v150, s23, v151
	v_ashrrev_i32_e32 v151, 31, v150
	v_lshlrev_b64 v[162:163], 15, v[150:151]
	v_lshl_add_u64 v[162:163], s[8:9], 0, v[162:163]
	v_lshlrev_b64 v[166:167], 1, v[148:149]
	v_lshl_add_u64 v[148:149], v[162:163], 0, v[166:167]
	s_waitcnt lgkmcnt(0)
	v_mov_b32_e32 v162, v165
	v_or_b32_e32 v160, 16, v150
	v_ashrrev_i32_e32 v161, 31, v160
	v_lshlrev_b64 v[160:161], 15, v[160:161]
	v_lshl_add_u64 v[160:161], s[8:9], 0, v[160:161]
	v_lshl_add_u64 v[160:161], v[160:161], 0, v[166:167]
	v_pk_fma_f32 v[134:135], v[134:135], v[164:165], v[206:207] op_sel_hi:[1,0,1]
	v_pk_fma_f32 v[132:133], v[132:133], v[164:165], v[204:205] op_sel_hi:[1,0,1]
	v_pk_fma_f32 v[130:131], v[130:131], v[164:165], v[210:211] op_sel_hi:[1,0,1]
	v_pk_fma_f32 v[128:129], v[128:129], v[164:165], v[208:209] op_sel_hi:[1,0,1]
	v_pk_fma_f32 v[110:111], v[110:111], v[164:165], v[214:215] op_sel_hi:[1,0,1]
	v_pk_fma_f32 v[108:109], v[108:109], v[164:165], v[212:213] op_sel_hi:[1,0,1]
	v_pk_fma_f32 v[106:107], v[106:107], v[164:165], v[218:219] op_sel_hi:[1,0,1]
	v_pk_fma_f32 v[104:105], v[104:105], v[164:165], v[216:217] op_sel_hi:[1,0,1]
	v_max_f32_e32 v132, 0, v132
	v_max_f32_e32 v128, 0, v128
	v_max_f32_e32 v133, 0, v133
	v_max_f32_e32 v129, 0, v129
	v_max_f32_e32 v134, 0, v134
	v_max_f32_e32 v130, 0, v130
	v_max_f32_e32 v135, 0, v135
	v_max_f32_e32 v131, 0, v131
	v_max_f32_e32 v108, 0, v108
	v_max_f32_e32 v104, 0, v104
	v_max_f32_e32 v109, 0, v109
	v_max_f32_e32 v105, 0, v105
	v_max_f32_e32 v110, 0, v110
	v_max_f32_e32 v106, 0, v106
	v_max_f32_e32 v111, 0, v111
	v_max_f32_e32 v107, 0, v107
	v_pk_mul_f32 v[132:133], v[132:133], v[132:133]
	v_pk_mul_f32 v[128:129], v[128:129], v[128:129]
	v_pk_mul_f32 v[134:135], v[134:135], v[134:135]
	v_pk_mul_f32 v[130:131], v[130:131], v[130:131]
	v_pk_fma_f32 v[96:97], v[96:97], v[162:163], v[216:217] op_sel_hi:[1,0,1]
	v_pk_mul_f32 v[108:109], v[108:109], v[108:109]
	v_pk_mul_f32 v[164:165], v[104:105], v[104:105]
	v_pk_mul_f32 v[110:111], v[110:111], v[110:111]
	v_pk_mul_f32 v[168:169], v[106:107], v[106:107]
	v_cvt_pk_bf16_f32 v104, v132, v133
	v_cvt_pk_bf16_f32 v105, v134, v135
	v_cvt_pk_bf16_f32 v106, v128, v129
	v_cvt_pk_bf16_f32 v107, v130, v131
	v_pk_fma_f32 v[102:103], v[102:103], v[162:163], v[214:215] op_sel_hi:[1,0,1]
	v_pk_fma_f32 v[100:101], v[100:101], v[162:163], v[212:213] op_sel_hi:[1,0,1]
	v_pk_fma_f32 v[98:99], v[98:99], v[162:163], v[218:219] op_sel_hi:[1,0,1]
	v_max_f32_e32 v96, 0, v96
	v_max_f32_e32 v97, 0, v97
	v_cvt_pk_bf16_f32 v108, v108, v109
	v_cvt_pk_bf16_f32 v109, v110, v111
	v_cvt_pk_bf16_f32 v110, v164, v165
	v_cvt_pk_bf16_f32 v111, v168, v169
	global_store_dwordx4 v[148:149], v[104:107], off
	global_store_dwordx4 v[148:149], v[108:111], off offset:256
	v_max_f32_e32 v100, 0, v100
	v_max_f32_e32 v101, 0, v101
	v_pk_mul_f32 v[104:105], v[96:97], v[96:97]
	v_max_f32_e32 v96, 0, v102
	v_max_f32_e32 v98, 0, v98
	v_max_f32_e32 v97, 0, v103
	v_max_f32_e32 v99, 0, v99
	v_pk_mul_f32 v[100:101], v[100:101], v[100:101]
	v_pk_mul_f32 v[102:103], v[96:97], v[96:97]
	v_pk_mul_f32 v[106:107], v[98:99], v[98:99]
	v_cvt_pk_bf16_f32 v96, v100, v101
	v_cvt_pk_bf16_f32 v97, v102, v103
	v_cvt_pk_bf16_f32 v98, v104, v105
	v_cvt_pk_bf16_f32 v99, v106, v107
	global_store_dwordx4 v[160:161], v[96:99], off offset:256
	ds_read2_b32 v[98:99], v159 offset0:32 offset1:48
	v_pk_fma_f32 v[118:119], v[118:119], v[162:163], v[206:207] op_sel_hi:[1,0,1]
	v_or_b32_e32 v96, 32, v150
	v_ashrrev_i32_e32 v97, 31, v96
	v_lshlrev_b64 v[96:97], 15, v[96:97]
	s_waitcnt lgkmcnt(0)
	v_pk_fma_f32 v[88:89], v[88:89], v[98:99], v[208:209] op_sel_hi:[1,0,1]
	v_pk_fma_f32 v[94:95], v[94:95], v[98:99], v[206:207] op_sel_hi:[1,0,1]
	v_pk_fma_f32 v[92:93], v[92:93], v[98:99], v[204:205] op_sel_hi:[1,0,1]
	v_pk_fma_f32 v[90:91], v[90:91], v[98:99], v[210:211] op_sel_hi:[1,0,1]
	v_max_f32_e32 v88, 0, v88
	v_max_f32_e32 v89, 0, v89
	v_max_f32_e32 v92, 0, v92
	v_max_f32_e32 v93, 0, v93
	v_pk_mul_f32 v[100:101], v[88:89], v[88:89]
	v_max_f32_e32 v88, 0, v94
	v_max_f32_e32 v90, 0, v90
	v_max_f32_e32 v89, 0, v95
	v_max_f32_e32 v91, 0, v91
	v_lshl_add_u64 v[96:97], s[8:9], 0, v[96:97]
	v_pk_mul_f32 v[92:93], v[92:93], v[92:93]
	v_pk_mul_f32 v[94:95], v[88:89], v[88:89]
	v_pk_mul_f32 v[102:103], v[90:91], v[90:91]
	v_pk_fma_f32 v[80:81], v[80:81], v[98:99], v[216:217] op_sel_hi:[1,0,1]
	v_lshl_add_u64 v[96:97], v[96:97], 0, v[166:167]
	v_cvt_pk_bf16_f32 v88, v92, v93
	v_cvt_pk_bf16_f32 v89, v94, v95
	v_cvt_pk_bf16_f32 v90, v100, v101
	v_cvt_pk_bf16_f32 v91, v102, v103
	v_pk_fma_f32 v[86:87], v[86:87], v[98:99], v[214:215] op_sel_hi:[1,0,1]
	v_pk_fma_f32 v[84:85], v[84:85], v[98:99], v[212:213] op_sel_hi:[1,0,1]
	v_pk_fma_f32 v[82:83], v[82:83], v[98:99], v[218:219] op_sel_hi:[1,0,1]
	v_max_f32_e32 v80, 0, v80
	v_max_f32_e32 v81, 0, v81
	global_store_dwordx4 v[96:97], v[88:91], off
	v_max_f32_e32 v84, 0, v84
	v_max_f32_e32 v85, 0, v85
	v_pk_mul_f32 v[88:89], v[80:81], v[80:81]
	v_max_f32_e32 v80, 0, v86
	v_max_f32_e32 v82, 0, v82
	v_max_f32_e32 v81, 0, v87
	v_max_f32_e32 v83, 0, v83
	v_pk_mul_f32 v[84:85], v[84:85], v[84:85]
	v_pk_mul_f32 v[86:87], v[80:81], v[80:81]
	v_pk_mul_f32 v[90:91], v[82:83], v[82:83]
	v_cvt_pk_bf16_f32 v80, v84, v85
	v_cvt_pk_bf16_f32 v81, v86, v87
	v_cvt_pk_bf16_f32 v82, v88, v89
	v_cvt_pk_bf16_f32 v83, v90, v91
	global_store_dwordx4 v[96:97], v[80:83], off offset:256
	v_pk_fma_f32 v[116:117], v[116:117], v[162:163], v[204:205] op_sel_hi:[1,0,1]
	v_pk_fma_f32 v[114:115], v[114:115], v[162:163], v[210:211] op_sel_hi:[1,0,1]
	v_mov_b32_e32 v82, v99
	v_or_b32_e32 v80, 48, v150
	v_pk_fma_f32 v[72:73], v[72:73], v[82:83], v[208:209] op_sel_hi:[1,0,1]
	v_ashrrev_i32_e32 v81, 31, v80
	v_pk_fma_f32 v[78:79], v[78:79], v[82:83], v[206:207] op_sel_hi:[1,0,1]
	v_pk_fma_f32 v[76:77], v[76:77], v[82:83], v[204:205] op_sel_hi:[1,0,1]
	v_pk_fma_f32 v[74:75], v[74:75], v[82:83], v[210:211] op_sel_hi:[1,0,1]
	v_max_f32_e32 v72, 0, v72
	v_max_f32_e32 v73, 0, v73
	v_pk_fma_f32 v[70:71], v[70:71], v[82:83], v[214:215] op_sel_hi:[1,0,1]
	v_pk_fma_f32 v[68:69], v[68:69], v[82:83], v[212:213] op_sel_hi:[1,0,1]
	v_pk_fma_f32 v[64:65], v[64:65], v[82:83], v[216:217] op_sel_hi:[1,0,1]
	v_lshlrev_b64 v[80:81], 15, v[80:81]
	v_max_f32_e32 v76, 0, v76
	v_max_f32_e32 v77, 0, v77
	v_pk_mul_f32 v[84:85], v[72:73], v[72:73]
	v_max_f32_e32 v72, 0, v78
	v_max_f32_e32 v74, 0, v74
	v_max_f32_e32 v73, 0, v79
	v_max_f32_e32 v75, 0, v75
	v_max_f32_e32 v68, 0, v68
	v_max_f32_e32 v64, 0, v64
	v_max_f32_e32 v69, 0, v69
	v_max_f32_e32 v65, 0, v65
	v_max_f32_e32 v70, 0, v70
	v_max_f32_e32 v71, 0, v71
	v_lshl_add_u64 v[80:81], s[8:9], 0, v[80:81]
	v_pk_mul_f32 v[76:77], v[76:77], v[76:77]
	v_pk_mul_f32 v[78:79], v[72:73], v[72:73]
	v_pk_mul_f32 v[86:87], v[74:75], v[74:75]
	v_pk_fma_f32 v[66:67], v[66:67], v[82:83], v[218:219] op_sel_hi:[1,0,1]
	v_pk_mul_f32 v[68:69], v[68:69], v[68:69]
	v_pk_mul_f32 v[64:65], v[64:65], v[64:65]
	v_pk_mul_f32 v[70:71], v[70:71], v[70:71]
	v_lshl_add_u64 v[80:81], v[80:81], 0, v[166:167]
	v_cvt_pk_bf16_f32 v72, v76, v77
	v_cvt_pk_bf16_f32 v73, v78, v79
	v_cvt_pk_bf16_f32 v74, v84, v85
	v_cvt_pk_bf16_f32 v75, v86, v87
	v_max_f32_e32 v66, 0, v66
	v_max_f32_e32 v67, 0, v67
	v_cvt_pk_bf16_f32 v68, v68, v69
	v_cvt_pk_bf16_f32 v69, v70, v71
	v_cvt_pk_bf16_f32 v70, v64, v65
	v_add_u32_e32 v64, s50, v174
	global_store_dwordx4 v[80:81], v[72:75], off
	v_pk_fma_f32 v[112:113], v[112:113], v[162:163], v[208:209] op_sel_hi:[1,0,1]
	v_max_f32_e32 v116, 0, v116
	v_pk_mul_f32 v[72:73], v[66:67], v[66:67]
	ds_read_b32 v66, v64
	v_cvt_pk_bf16_f32 v71, v72, v73
	global_store_dwordx4 v[80:81], v[68:71], off offset:256
	ds_read_b32 v68, v159 offset:704
	v_lshl_add_u64 v[64:65], v[148:149], 0, s[14:15]
	s_waitcnt lgkmcnt(1)
	v_pk_fma_f32 v[60:61], v[60:61], v[66:67], v[204:205] op_sel_hi:[1,0,1]
	v_pk_fma_f32 v[56:57], v[56:57], v[66:67], v[208:209] op_sel_hi:[1,0,1]
	v_pk_fma_f32 v[62:63], v[62:63], v[66:67], v[206:207] op_sel_hi:[1,0,1]
	v_pk_fma_f32 v[58:59], v[58:59], v[66:67], v[210:211] op_sel_hi:[1,0,1]
	v_max_f32_e32 v60, 0, v60
	v_max_f32_e32 v56, 0, v56
	v_max_f32_e32 v61, 0, v61
	v_max_f32_e32 v57, 0, v57
	v_pk_mul_f32 v[60:61], v[60:61], v[60:61]
	v_pk_mul_f32 v[70:71], v[56:57], v[56:57]
	v_max_f32_e32 v56, 0, v62
	v_max_f32_e32 v58, 0, v58
	v_max_f32_e32 v57, 0, v63
	v_max_f32_e32 v59, 0, v59
	v_pk_mul_f32 v[62:63], v[56:57], v[56:57]
	v_pk_mul_f32 v[72:73], v[58:59], v[58:59]
	v_cvt_pk_bf16_f32 v56, v60, v61
	v_add_co_u32_e32 v60, vcc, s51, v148
	v_pk_fma_f32 v[48:49], v[48:49], v[66:67], v[212:213] op_sel_hi:[1,0,1]
	v_pk_fma_f32 v[40:41], v[40:41], v[66:67], v[216:217] op_sel_hi:[1,0,1]
	v_cvt_pk_bf16_f32 v57, v62, v63
	v_cvt_pk_bf16_f32 v58, v70, v71
	v_cvt_pk_bf16_f32 v59, v72, v73
	v_addc_co_u32_e32 v61, vcc, 0, v149, vcc
	v_pk_fma_f32 v[50:51], v[50:51], v[66:67], v[214:215] op_sel_hi:[1,0,1]
	v_max_f32_e32 v48, 0, v48
	v_max_f32_e32 v40, 0, v40
	v_max_f32_e32 v49, 0, v49
	v_max_f32_e32 v41, 0, v41
	global_store_dwordx4 v[60:61], v[56:59], off
	v_pk_mul_f32 v[48:49], v[48:49], v[48:49]
	v_pk_fma_f32 v[42:43], v[42:43], v[66:67], v[218:219] op_sel_hi:[1,0,1]
	v_pk_mul_f32 v[56:57], v[40:41], v[40:41]
	v_max_f32_e32 v40, 0, v50
	v_max_f32_e32 v41, 0, v51
	v_pk_mul_f32 v[50:51], v[40:41], v[40:41]
	v_cvt_pk_bf16_f32 v40, v48, v49
	ds_read2_b32 v[48:49], v159 offset0:144 offset1:160
	v_max_f32_e32 v42, 0, v42
	v_max_f32_e32 v43, 0, v43
	v_pk_mul_f32 v[58:59], v[42:43], v[42:43]
	v_cvt_pk_bf16_f32 v41, v50, v51
	v_cvt_pk_bf16_f32 v42, v56, v57
	v_cvt_pk_bf16_f32 v43, v58, v59
	global_store_dwordx4 v[64:65], v[40:43], off offset:256
	s_waitcnt lgkmcnt(0)
	v_pk_fma_f32 v[44:45], v[44:45], v[48:49], v[208:209] op_sel_hi:[1,0,1]
	v_pk_fma_f32 v[46:47], v[46:47], v[48:49], v[210:211] op_sel_hi:[1,0,1]
	v_pk_fma_f32 v[42:43], v[52:53], v[48:49], v[204:205] op_sel_hi:[1,0,1]
	v_pk_fma_f32 v[40:41], v[54:55], v[48:49], v[206:207] op_sel_hi:[1,0,1]
	v_max_f32_e32 v42, 0, v42
	v_max_f32_e32 v44, 0, v44
	v_max_f32_e32 v43, 0, v43
	v_max_f32_e32 v45, 0, v45
	v_pk_mul_f32 v[42:43], v[42:43], v[42:43]
	v_pk_mul_f32 v[44:45], v[44:45], v[44:45]
	v_max_f32_e32 v40, 0, v40
	v_max_f32_e32 v46, 0, v46
	v_max_f32_e32 v41, 0, v41
	v_max_f32_e32 v47, 0, v47
	v_pk_mul_f32 v[52:53], v[40:41], v[40:41]
	v_pk_mul_f32 v[46:47], v[46:47], v[46:47]
	v_cvt_pk_bf16_f32 v40, v42, v43
	v_cvt_pk_bf16_f32 v42, v44, v45
	v_add_co_u32_e32 v44, vcc, s52, v148
	v_pk_fma_f32 v[24:25], v[24:25], v[48:49], v[216:217] op_sel_hi:[1,0,1]
	v_cvt_pk_bf16_f32 v41, v52, v53
	v_cvt_pk_bf16_f32 v43, v46, v47
	v_addc_co_u32_e32 v45, vcc, 0, v149, vcc
	v_pk_fma_f32 v[34:35], v[34:35], v[48:49], v[214:215] op_sel_hi:[1,0,1]
	v_pk_fma_f32 v[32:33], v[32:33], v[48:49], v[212:213] op_sel_hi:[1,0,1]
	v_pk_fma_f32 v[26:27], v[26:27], v[48:49], v[218:219] op_sel_hi:[1,0,1]
	v_max_f32_e32 v24, 0, v24
	v_max_f32_e32 v25, 0, v25
	global_store_dwordx4 v[44:45], v[40:43], off
	v_max_f32_e32 v32, 0, v32
	v_max_f32_e32 v33, 0, v33
	v_pk_mul_f32 v[40:41], v[24:25], v[24:25]
	v_max_f32_e32 v24, 0, v34
	v_max_f32_e32 v26, 0, v26
	v_max_f32_e32 v25, 0, v35
	v_max_f32_e32 v27, 0, v27
	v_pk_mul_f32 v[32:33], v[32:33], v[32:33]
	v_pk_mul_f32 v[34:35], v[24:25], v[24:25]
	v_pk_mul_f32 v[42:43], v[26:27], v[26:27]
	v_lshl_add_u64 v[50:51], v[148:149], 0, s[16:17]
	v_cvt_pk_bf16_f32 v24, v32, v33
	v_cvt_pk_bf16_f32 v25, v34, v35
	v_cvt_pk_bf16_f32 v26, v40, v41
	v_cvt_pk_bf16_f32 v27, v42, v43
	v_mov_b32_e32 v34, v49
	global_store_dwordx4 v[50:51], v[24:27], off offset:256
	v_pk_fma_f32 v[28:29], v[28:29], v[34:35], v[208:209] op_sel_hi:[1,0,1]
	v_pk_fma_f32 v[30:31], v[30:31], v[34:35], v[210:211] op_sel_hi:[1,0,1]
	v_pk_fma_f32 v[26:27], v[36:37], v[34:35], v[204:205] op_sel_hi:[1,0,1]
	v_pk_fma_f32 v[24:25], v[38:39], v[34:35], v[206:207] op_sel_hi:[1,0,1]
	v_max_f32_e32 v26, 0, v26
	v_max_f32_e32 v28, 0, v28
	v_max_f32_e32 v27, 0, v27
	v_max_f32_e32 v29, 0, v29
	v_pk_mul_f32 v[26:27], v[26:27], v[26:27]
	v_pk_mul_f32 v[28:29], v[28:29], v[28:29]
	v_max_f32_e32 v24, 0, v24
	v_max_f32_e32 v30, 0, v30
	v_max_f32_e32 v25, 0, v25
	v_max_f32_e32 v31, 0, v31
	v_pk_mul_f32 v[36:37], v[24:25], v[24:25]
	v_pk_mul_f32 v[30:31], v[30:31], v[30:31]
	v_cvt_pk_bf16_f32 v24, v26, v27
	v_cvt_pk_bf16_f32 v26, v28, v29
	v_add_co_u32_e32 v28, vcc, s53, v148
	v_pk_fma_f32 v[12:13], v[12:13], v[34:35], v[216:217] op_sel_hi:[1,0,1]
	v_cvt_pk_bf16_f32 v25, v36, v37
	v_cvt_pk_bf16_f32 v27, v30, v31
	v_addc_co_u32_e32 v29, vcc, 0, v149, vcc
	v_pk_fma_f32 v[22:23], v[22:23], v[34:35], v[214:215] op_sel_hi:[1,0,1]
	v_pk_fma_f32 v[20:21], v[20:21], v[34:35], v[212:213] op_sel_hi:[1,0,1]
	v_pk_fma_f32 v[14:15], v[14:15], v[34:35], v[218:219] op_sel_hi:[1,0,1]
	v_max_f32_e32 v12, 0, v12
	v_max_f32_e32 v13, 0, v13
	global_store_dwordx4 v[28:29], v[24:27], off
	v_max_f32_e32 v20, 0, v20
	v_max_f32_e32 v21, 0, v21
	v_pk_mul_f32 v[24:25], v[12:13], v[12:13]
	v_max_f32_e32 v12, 0, v22
	v_max_f32_e32 v14, 0, v14
	v_max_f32_e32 v13, 0, v23
	v_max_f32_e32 v15, 0, v15
	v_pk_mul_f32 v[20:21], v[20:21], v[20:21]
	v_pk_mul_f32 v[22:23], v[12:13], v[12:13]
	v_pk_mul_f32 v[26:27], v[14:15], v[14:15]
	v_lshl_add_u64 v[32:33], v[148:149], 0, s[18:19]
	v_cvt_pk_bf16_f32 v12, v20, v21
	v_cvt_pk_bf16_f32 v13, v22, v23
	v_cvt_pk_bf16_f32 v14, v24, v25
	v_cvt_pk_bf16_f32 v15, v26, v27
	v_pk_fma_f32 v[8:9], v[8:9], v[68:69], v[208:209] op_sel_hi:[1,0,1]
	global_store_dwordx4 v[32:33], v[12:15], off offset:256
	v_max_f32_e32 v8, 0, v8
	v_max_f32_e32 v9, 0, v9
	v_pk_fma_f32 v[14:15], v[18:19], v[68:69], v[206:207] op_sel_hi:[1,0,1]
	v_pk_fma_f32 v[16:17], v[16:17], v[68:69], v[204:205] op_sel_hi:[1,0,1]
	v_pk_fma_f32 v[10:11], v[10:11], v[68:69], v[210:211] op_sel_hi:[1,0,1]
	v_pk_mul_f32 v[18:19], v[8:9], v[8:9]
	v_max_f32_e32 v8, 0, v14
	v_max_f32_e32 v9, 0, v15
	v_max_f32_e32 v16, 0, v16
	v_max_f32_e32 v17, 0, v17
	v_max_f32_e32 v10, 0, v10
	v_max_f32_e32 v11, 0, v11
	v_pk_mul_f32 v[14:15], v[8:9], v[8:9]
	v_pk_mul_f32 v[16:17], v[16:17], v[16:17]
	v_pk_mul_f32 v[20:21], v[10:11], v[10:11]
	v_cvt_pk_bf16_f32 v9, v14, v15
	v_add_co_u32_e32 v14, vcc, s56, v148
	v_pk_fma_f32 v[0:1], v[0:1], v[68:69], v[216:217] op_sel_hi:[1,0,1]
	v_cvt_pk_bf16_f32 v8, v16, v17
	v_cvt_pk_bf16_f32 v10, v18, v19
	v_cvt_pk_bf16_f32 v11, v20, v21
	v_addc_co_u32_e32 v15, vcc, 0, v149, vcc
	v_pk_fma_f32 v[6:7], v[6:7], v[68:69], v[214:215] op_sel_hi:[1,0,1]
	v_pk_fma_f32 v[4:5], v[4:5], v[68:69], v[212:213] op_sel_hi:[1,0,1]
	v_pk_fma_f32 v[2:3], v[2:3], v[68:69], v[218:219] op_sel_hi:[1,0,1]
	v_max_f32_e32 v0, 0, v0
	v_max_f32_e32 v1, 0, v1
	v_max_f32_e32 v112, 0, v112
	v_max_f32_e32 v117, 0, v117
	v_max_f32_e32 v113, 0, v113
	v_max_f32_e32 v118, 0, v118
	v_max_f32_e32 v114, 0, v114
	v_max_f32_e32 v119, 0, v119
	v_max_f32_e32 v115, 0, v115
	global_store_dwordx4 v[14:15], v[8:11], off
	v_max_f32_e32 v4, 0, v4
	v_max_f32_e32 v5, 0, v5
	v_pk_mul_f32 v[8:9], v[0:1], v[0:1]
	v_max_f32_e32 v0, 0, v6
	v_max_f32_e32 v2, 0, v2
	v_max_f32_e32 v1, 0, v7
	v_max_f32_e32 v3, 0, v3
	v_pk_mul_f32 v[116:117], v[116:117], v[116:117]
	v_pk_mul_f32 v[170:171], v[112:113], v[112:113]
	v_pk_mul_f32 v[118:119], v[118:119], v[118:119]
	v_pk_mul_f32 v[172:173], v[114:115], v[114:115]
	v_pk_mul_f32 v[4:5], v[4:5], v[4:5]
	v_pk_mul_f32 v[6:7], v[0:1], v[0:1]
	v_pk_mul_f32 v[10:11], v[2:3], v[2:3]
	v_cvt_pk_bf16_f32 v112, v116, v117
	v_cvt_pk_bf16_f32 v113, v118, v119
	v_cvt_pk_bf16_f32 v114, v170, v171
	v_cvt_pk_bf16_f32 v115, v172, v173
	v_lshl_add_u64 v[12:13], v[148:149], 0, s[20:21]
	v_cvt_pk_bf16_f32 v0, v4, v5
	v_cvt_pk_bf16_f32 v1, v6, v7
	v_cvt_pk_bf16_f32 v2, v8, v9
	v_cvt_pk_bf16_f32 v3, v10, v11
	s_andn2_b64 vcc, exec, s[4:5]
	s_mov_b64 s[4:5], -1
	global_store_dwordx4 v[160:161], v[112:115], off
	global_store_dwordx4 v[12:13], v[0:3], off offset:256
	s_cbranch_vccnz .LBB0_1597
	s_andn2_b64 vcc, exec, s[6:7]
	s_cbranch_vccnz .LBB0_1596
	s_mov_b32 s99, 1
	s_branch .LBB0_1596

.LBB0_1680:
	s_ashr_i32 s15, s14, 31
	s_lshl_b64 s[16:17], s[14:15], 23
	s_add_u32 s16, s36, s16
	s_addc_u32 s17, s37, s17
	s_and_b64 s[18:19], s[0:1], exec
	s_cselect_b32 s15, s17, s23
	s_cselect_b32 s41, s16, s22
	s_ashr_i32 s13, s12, 31
	s_lshl_b64 s[18:19], s[12:13], 23
	s_add_u32 s18, s34, s18
	s_addc_u32 s19, s35, s19
	s_and_b64 s[26:27], s[0:1], exec
	s_cselect_b32 s13, s19, s25
	s_cselect_b32 s42, s18, s24
	s_add_u32 s43, s24, 0x100
	s_addc_u32 s44, s25, 0
	s_mov_b32 s45, -2
	s_waitcnt vmcnt(0)
	v_mov_b64_e32 v[0:1], 0
	v_mov_b64_e32 v[2:3], 0
	v_mov_b64_e32 v[4:5], 0
	v_mov_b64_e32 v[6:7], 0
	v_mov_b64_e32 v[8:9], 0
	v_mov_b64_e32 v[10:11], 0
	v_mov_b64_e32 v[12:13], 0
	v_mov_b64_e32 v[14:15], 0
	v_mov_b64_e32 v[16:17], 0
	v_mov_b64_e32 v[18:19], 0
	v_mov_b64_e32 v[20:21], 0
	v_mov_b64_e32 v[22:23], 0
	v_mov_b64_e32 v[24:25], 0
	v_mov_b64_e32 v[26:27], 0
	v_mov_b64_e32 v[28:29], 0
	v_mov_b64_e32 v[30:31], 0
	v_mov_b64_e32 v[32:33], 0
	v_mov_b64_e32 v[34:35], 0
	v_mov_b64_e32 v[36:37], 0
	v_mov_b64_e32 v[38:39], 0
	v_mov_b64_e32 v[40:41], 0
	v_mov_b64_e32 v[42:43], 0
	v_mov_b64_e32 v[44:45], 0
	v_mov_b64_e32 v[46:47], 0
	v_mov_b64_e32 v[48:49], 0
	v_mov_b64_e32 v[50:51], 0
	v_mov_b64_e32 v[52:53], 0
	v_mov_b64_e32 v[54:55], 0
	v_mov_b64_e32 v[56:57], 0
	v_mov_b64_e32 v[58:59], 0
	v_mov_b64_e32 v[60:61], 0
	v_mov_b64_e32 v[62:63], 0
	v_mov_b64_e32 v[64:65], 0
	v_mov_b64_e32 v[66:67], 0
	v_mov_b64_e32 v[68:69], 0
	v_mov_b64_e32 v[70:71], 0
	v_mov_b64_e32 v[72:73], 0
	v_mov_b64_e32 v[74:75], 0
	v_mov_b64_e32 v[76:77], 0
	v_mov_b64_e32 v[78:79], 0
	v_mov_b64_e32 v[80:81], 0
	v_mov_b64_e32 v[82:83], 0
	v_mov_b64_e32 v[84:85], 0
	v_mov_b64_e32 v[86:87], 0
	v_mov_b64_e32 v[88:89], 0
	v_mov_b64_e32 v[90:91], 0
	v_mov_b64_e32 v[92:93], 0
	v_mov_b64_e32 v[94:95], 0
	v_mov_b64_e32 v[96:97], 0
	v_mov_b64_e32 v[98:99], 0
	v_mov_b64_e32 v[100:101], 0
	v_mov_b64_e32 v[102:103], 0
	v_mov_b64_e32 v[104:105], 0
	v_mov_b64_e32 v[106:107], 0
	v_mov_b64_e32 v[108:109], 0
	v_mov_b64_e32 v[110:111], 0
	v_mov_b64_e32 v[112:113], 0
	v_mov_b64_e32 v[114:115], 0
	v_mov_b64_e32 v[116:117], 0
	v_mov_b64_e32 v[118:119], 0
	v_mov_b64_e32 v[120:121], 0
	v_mov_b64_e32 v[122:123], 0
	v_mov_b64_e32 v[124:125], 0
	v_mov_b64_e32 v[126:127], 0
	s_cmp_eq_u32 s99, 1
	s_cbranch_scc0 .Lue_1681
	s_mov_b32 s99, 0
	s_barrier
.Lue_1681:
.LBB0_1681:
	ds_read_b128 v[128:131], v158
	ds_read_b128 v[132:135], v158 offset:1024
	ds_read_b128 v[136:139], v158 offset:2048
	ds_read_b128 v[140:143], v158 offset:3072
	ds_read_b128 v[148:151], v159
	ds_read_b128 v[152:155], v159 offset:1024
	ds_read_b128 v[164:167], v159 offset:2048
	ds_read_b128 v[168:171], v159 offset:3072
	s_add_u32 s24, s22, 0x100
	s_addc_u32 s25, s23, 0
	s_cmpk_eq_i32 s45, 0xfc
	s_cselect_b32 s30, s41, s24
	s_cselect_b32 s31, s15, s25
	s_cselect_b32 s28, s42, s43
	s_cselect_b32 s29, s13, s44
	s_add_u32 s26, s30, 0x80
	s_addc_u32 s27, s31, 0
	ds_read_b128 v[172:175], v160
	ds_read_b128 v[176:179], v160 offset:1024
	ds_read_b128 v[180:183], v160 offset:2048
	ds_read_b128 v[184:187], v160 offset:3072
	ds_read_b128 v[188:191], v160 offset:4096
	ds_read_b128 v[192:195], v160 offset:5120
	ds_read_b128 v[196:199], v160 offset:6144
	ds_read_b128 v[200:203], v160 offset:7168
	s_add_u32 s22, s22, 0x400080
	s_addc_u32 s23, s23, 0
	s_add_i32 m0, s33, 0xc000
	s_nop 0
	global_load_lds_dwordx4 v156, s[22:23]
	s_nop 0
	s_add_i32 m0, s33, 0xe000
	s_nop 0
	global_load_lds_dwordx4 v157, s[22:23]
	s_waitcnt vmcnt(8)
	s_waitcnt lgkmcnt(0)
	s_barrier
	s_setprio 1
	v_mfma_f32_16x16x32_bf16 v[124:127], v[128:131], v[172:175], v[124:127]
	v_mfma_f32_16x16x32_bf16 v[120:123], v[136:139], v[172:175], v[120:123]
	v_mfma_f32_16x16x32_bf16 v[116:119], v[128:131], v[180:183], v[116:119]
	v_mfma_f32_16x16x32_bf16 v[112:115], v[136:139], v[180:183], v[112:115]
	v_mfma_f32_16x16x32_bf16 v[96:99], v[128:131], v[188:191], v[96:99]
	v_mfma_f32_16x16x32_bf16 v[88:91], v[136:139], v[188:191], v[88:91]
	v_mfma_f32_16x16x32_bf16 v[80:83], v[128:131], v[196:199], v[80:83]
	v_mfma_f32_16x16x32_bf16 v[72:75], v[136:139], v[196:199], v[72:75]
	v_mfma_f32_16x16x32_bf16 v[124:127], v[132:135], v[176:179], v[124:127]
	v_mfma_f32_16x16x32_bf16 v[120:123], v[140:143], v[176:179], v[120:123]
	v_mfma_f32_16x16x32_bf16 v[116:119], v[132:135], v[184:187], v[116:119]
	v_mfma_f32_16x16x32_bf16 v[112:115], v[140:143], v[184:187], v[112:115]
	v_mfma_f32_16x16x32_bf16 v[96:99], v[132:135], v[192:195], v[96:99]
	v_mfma_f32_16x16x32_bf16 v[88:91], v[140:143], v[192:195], v[88:91]
	v_mfma_f32_16x16x32_bf16 v[80:83], v[132:135], v[200:203], v[80:83]
	v_mfma_f32_16x16x32_bf16 v[72:75], v[140:143], v[200:203], v[72:75]
	v_mfma_f32_16x16x32_bf16 v[108:111], v[148:151], v[172:175], v[108:111]
	v_mfma_f32_16x16x32_bf16 v[104:107], v[164:167], v[172:175], v[104:107]
	v_mfma_f32_16x16x32_bf16 v[100:103], v[148:151], v[180:183], v[100:103]
	v_mfma_f32_16x16x32_bf16 v[92:95], v[164:167], v[180:183], v[92:95]
	v_mfma_f32_16x16x32_bf16 v[84:87], v[148:151], v[188:191], v[84:87]
	v_mfma_f32_16x16x32_bf16 v[76:79], v[164:167], v[188:191], v[76:79]
	v_mfma_f32_16x16x32_bf16 v[68:71], v[148:151], v[196:199], v[68:71]
	v_mfma_f32_16x16x32_bf16 v[64:67], v[164:167], v[196:199], v[64:67]
	v_mfma_f32_16x16x32_bf16 v[108:111], v[152:155], v[176:179], v[108:111]
	v_mfma_f32_16x16x32_bf16 v[104:107], v[168:171], v[176:179], v[104:107]
	v_mfma_f32_16x16x32_bf16 v[100:103], v[152:155], v[184:187], v[100:103]
	v_mfma_f32_16x16x32_bf16 v[92:95], v[168:171], v[184:187], v[92:95]
	v_mfma_f32_16x16x32_bf16 v[84:87], v[152:155], v[192:195], v[84:87]
	v_mfma_f32_16x16x32_bf16 v[76:79], v[168:171], v[192:195], v[76:79]
	v_mfma_f32_16x16x32_bf16 v[68:71], v[152:155], v[200:203], v[68:71]
	v_mfma_f32_16x16x32_bf16 v[64:67], v[168:171], v[200:203], v[64:67]
	s_setprio 0
	s_barrier
	ds_read_b128 v[172:175], v160 offset:16384
	ds_read_b128 v[176:179], v160 offset:17408
	ds_read_b128 v[180:183], v160 offset:18432
	ds_read_b128 v[184:187], v160 offset:19456
	ds_read_b128 v[188:191], v160 offset:20480
	ds_read_b128 v[192:195], v160 offset:21504
	ds_read_b128 v[196:199], v160 offset:22528
	ds_read_b128 v[200:203], v160 offset:23552
	s_add_i32 m0, s33, 0x10000
	s_nop 0
	global_load_lds_dwordx4 v156, s[28:29]
	s_nop 0
	s_add_i32 m0, s33, 0x12000
	s_nop 0
	global_load_lds_dwordx4 v157, s[28:29]
	s_add_u32 s22, s28, 0x400000
	s_addc_u32 s23, s29, 0
	s_add_i32 m0, s33, 0x14000
	s_nop 0
	global_load_lds_dwordx4 v156, s[22:23]
	s_nop 0
	s_add_i32 m0, s33, 0x16000
	s_nop 0
	global_load_lds_dwordx4 v157, s[22:23]
	s_nop 0
	s_add_i32 m0, s33, 0
	s_nop 0
	global_load_lds_dwordx4 v156, s[30:31]
	s_nop 0
	s_add_i32 m0, s33, 0x2000
	s_nop 0
	global_load_lds_dwordx4 v157, s[30:31]
	s_waitcnt vmcnt(8)
	s_waitcnt lgkmcnt(0)
	s_barrier
	s_setprio 1
	v_mfma_f32_16x16x32_bf16 v[60:63], v[128:131], v[172:175], v[60:63]
	v_mfma_f32_16x16x32_bf16 v[56:59], v[136:139], v[172:175], v[56:59]
	v_mfma_f32_16x16x32_bf16 v[48:51], v[128:131], v[180:183], v[48:51]
	v_mfma_f32_16x16x32_bf16 v[40:43], v[136:139], v[180:183], v[40:43]
	v_mfma_f32_16x16x32_bf16 v[32:35], v[128:131], v[188:191], v[32:35]
	v_mfma_f32_16x16x32_bf16 v[24:27], v[136:139], v[188:191], v[24:27]
	v_mfma_f32_16x16x32_bf16 v[16:19], v[128:131], v[196:199], v[16:19]
	v_mfma_f32_16x16x32_bf16 v[8:11], v[136:139], v[196:199], v[8:11]
	v_mfma_f32_16x16x32_bf16 v[60:63], v[132:135], v[176:179], v[60:63]
	v_mfma_f32_16x16x32_bf16 v[56:59], v[140:143], v[176:179], v[56:59]
	v_mfma_f32_16x16x32_bf16 v[48:51], v[132:135], v[184:187], v[48:51]
	v_mfma_f32_16x16x32_bf16 v[40:43], v[140:143], v[184:187], v[40:43]
	v_mfma_f32_16x16x32_bf16 v[32:35], v[132:135], v[192:195], v[32:35]
	v_mfma_f32_16x16x32_bf16 v[24:27], v[140:143], v[192:195], v[24:27]
	v_mfma_f32_16x16x32_bf16 v[16:19], v[132:135], v[200:203], v[16:19]
	v_mfma_f32_16x16x32_bf16 v[8:11], v[140:143], v[200:203], v[8:11]
	v_mfma_f32_16x16x32_bf16 v[52:55], v[148:151], v[172:175], v[52:55]
	v_mfma_f32_16x16x32_bf16 v[44:47], v[164:167], v[172:175], v[44:47]
	v_mfma_f32_16x16x32_bf16 v[36:39], v[148:151], v[180:183], v[36:39]
	v_mfma_f32_16x16x32_bf16 v[28:31], v[164:167], v[180:183], v[28:31]
	v_mfma_f32_16x16x32_bf16 v[20:23], v[148:151], v[188:191], v[20:23]
	v_mfma_f32_16x16x32_bf16 v[12:15], v[164:167], v[188:191], v[12:15]
	v_mfma_f32_16x16x32_bf16 v[4:7], v[148:151], v[196:199], v[4:7]
	v_mfma_f32_16x16x32_bf16 v[0:3], v[164:167], v[196:199], v[0:3]
	v_mfma_f32_16x16x32_bf16 v[52:55], v[152:155], v[176:179], v[52:55]
	v_mfma_f32_16x16x32_bf16 v[44:47], v[168:171], v[176:179], v[44:47]
	v_mfma_f32_16x16x32_bf16 v[36:39], v[152:155], v[184:187], v[36:39]
	v_mfma_f32_16x16x32_bf16 v[28:31], v[168:171], v[184:187], v[28:31]
	v_mfma_f32_16x16x32_bf16 v[20:23], v[152:155], v[192:195], v[20:23]
	v_mfma_f32_16x16x32_bf16 v[12:15], v[168:171], v[192:195], v[12:15]
	v_mfma_f32_16x16x32_bf16 v[4:7], v[152:155], v[200:203], v[4:7]
	v_mfma_f32_16x16x32_bf16 v[0:3], v[168:171], v[200:203], v[0:3]
	s_setprio 0
	s_barrier
	ds_read_b128 v[128:131], v161
	ds_read_b128 v[132:135], v161 offset:1024
	ds_read_b128 v[136:139], v161 offset:2048
	ds_read_b128 v[140:143], v161 offset:3072
	ds_read_b128 v[148:151], v162
	ds_read_b128 v[152:155], v162 offset:1024
	ds_read_b128 v[164:167], v162 offset:2048
	ds_read_b128 v[168:171], v162 offset:3072
	ds_read_b128 v[172:175], v160 offset:32768
	ds_read_b128 v[176:179], v160 offset:33792
	ds_read_b128 v[180:183], v160 offset:34816
	ds_read_b128 v[184:187], v160 offset:35840
	ds_read_b128 v[188:191], v160 offset:36864
	ds_read_b128 v[192:195], v160 offset:37888
	ds_read_b128 v[196:199], v160 offset:38912
	ds_read_b128 v[200:203], v160 offset:39936
	s_add_u32 s22, s30, 0x400000
	s_addc_u32 s23, s31, 0
	s_add_i32 m0, s33, 0x4000
	s_nop 0
	global_load_lds_dwordx4 v156, s[22:23]
	s_nop 0
	s_add_i32 m0, s33, 0x6000
	s_nop 0
	global_load_lds_dwordx4 v157, s[22:23]
	s_waitcnt vmcnt(8)
	s_waitcnt lgkmcnt(0)
	s_barrier
	s_setprio 1
	v_mfma_f32_16x16x32_bf16 v[124:127], v[128:131], v[172:175], v[124:127]
	v_mfma_f32_16x16x32_bf16 v[120:123], v[136:139], v[172:175], v[120:123]
	v_mfma_f32_16x16x32_bf16 v[116:119], v[128:131], v[180:183], v[116:119]
	v_mfma_f32_16x16x32_bf16 v[112:115], v[136:139], v[180:183], v[112:115]
	v_mfma_f32_16x16x32_bf16 v[96:99], v[128:131], v[188:191], v[96:99]
	v_mfma_f32_16x16x32_bf16 v[88:91], v[136:139], v[188:191], v[88:91]
	v_mfma_f32_16x16x32_bf16 v[80:83], v[128:131], v[196:199], v[80:83]
	v_mfma_f32_16x16x32_bf16 v[72:75], v[136:139], v[196:199], v[72:75]
	v_mfma_f32_16x16x32_bf16 v[124:127], v[132:135], v[176:179], v[124:127]
	v_mfma_f32_16x16x32_bf16 v[120:123], v[140:143], v[176:179], v[120:123]
	v_mfma_f32_16x16x32_bf16 v[116:119], v[132:135], v[184:187], v[116:119]
	v_mfma_f32_16x16x32_bf16 v[112:115], v[140:143], v[184:187], v[112:115]
	v_mfma_f32_16x16x32_bf16 v[96:99], v[132:135], v[192:195], v[96:99]
	v_mfma_f32_16x16x32_bf16 v[88:91], v[140:143], v[192:195], v[88:91]
	v_mfma_f32_16x16x32_bf16 v[80:83], v[132:135], v[200:203], v[80:83]
	v_mfma_f32_16x16x32_bf16 v[72:75], v[140:143], v[200:203], v[72:75]
	v_mfma_f32_16x16x32_bf16 v[108:111], v[148:151], v[172:175], v[108:111]
	v_mfma_f32_16x16x32_bf16 v[104:107], v[164:167], v[172:175], v[104:107]
	v_mfma_f32_16x16x32_bf16 v[100:103], v[148:151], v[180:183], v[100:103]
	v_mfma_f32_16x16x32_bf16 v[92:95], v[164:167], v[180:183], v[92:95]
	v_mfma_f32_16x16x32_bf16 v[84:87], v[148:151], v[188:191], v[84:87]
	v_mfma_f32_16x16x32_bf16 v[76:79], v[164:167], v[188:191], v[76:79]
	v_mfma_f32_16x16x32_bf16 v[68:71], v[148:151], v[196:199], v[68:71]
	v_mfma_f32_16x16x32_bf16 v[64:67], v[164:167], v[196:199], v[64:67]
	v_mfma_f32_16x16x32_bf16 v[108:111], v[152:155], v[176:179], v[108:111]
	v_mfma_f32_16x16x32_bf16 v[104:107], v[168:171], v[176:179], v[104:107]
	v_mfma_f32_16x16x32_bf16 v[100:103], v[152:155], v[184:187], v[100:103]
	v_mfma_f32_16x16x32_bf16 v[92:95], v[168:171], v[184:187], v[92:95]
	v_mfma_f32_16x16x32_bf16 v[84:87], v[152:155], v[192:195], v[84:87]
	v_mfma_f32_16x16x32_bf16 v[76:79], v[168:171], v[192:195], v[76:79]
	v_mfma_f32_16x16x32_bf16 v[68:71], v[152:155], v[200:203], v[68:71]
	v_mfma_f32_16x16x32_bf16 v[64:67], v[168:171], v[200:203], v[64:67]
	s_setprio 0
	s_barrier
	s_add_u32 s22, s28, 0x80
	ds_read_b128 v[172:175], v160 offset:49152
	ds_read_b128 v[176:179], v160 offset:50176
	ds_read_b128 v[180:183], v160 offset:51200
	ds_read_b128 v[184:187], v160 offset:52224
	ds_read_b128 v[188:191], v160 offset:53248
	ds_read_b128 v[192:195], v160 offset:54272
	ds_read_b128 v[196:199], v160 offset:55296
	ds_read_b128 v[200:203], v160 offset:56320
	s_addc_u32 s23, s29, 0
	s_add_i32 m0, s33, 0x18000
	s_nop 0
	global_load_lds_dwordx4 v156, s[22:23]
	s_nop 0
	s_add_i32 m0, s33, 0x1a000
	s_nop 0
	global_load_lds_dwordx4 v157, s[22:23]
	s_add_u32 s22, s28, 0x400080
	s_addc_u32 s23, s29, 0
	s_add_i32 m0, s33, 0x1c000
	s_nop 0
	global_load_lds_dwordx4 v156, s[22:23]
	s_nop 0
	s_add_i32 m0, s33, 0x1e000
	s_nop 0
	global_load_lds_dwordx4 v157, s[22:23]
	s_nop 0
	s_add_i32 m0, s33, 0x8000
	s_nop 0
	global_load_lds_dwordx4 v156, s[26:27]
	s_nop 0
	s_add_i32 m0, s33, 0xa000
	s_nop 0
	global_load_lds_dwordx4 v157, s[26:27]
	s_waitcnt vmcnt(8)
	s_waitcnt lgkmcnt(0)
	s_barrier
	s_setprio 1
	v_mfma_f32_16x16x32_bf16 v[60:63], v[128:131], v[172:175], v[60:63]
	v_mfma_f32_16x16x32_bf16 v[56:59], v[136:139], v[172:175], v[56:59]
	v_mfma_f32_16x16x32_bf16 v[48:51], v[128:131], v[180:183], v[48:51]
	v_mfma_f32_16x16x32_bf16 v[40:43], v[136:139], v[180:183], v[40:43]
	v_mfma_f32_16x16x32_bf16 v[32:35], v[128:131], v[188:191], v[32:35]
	v_mfma_f32_16x16x32_bf16 v[24:27], v[136:139], v[188:191], v[24:27]
	v_mfma_f32_16x16x32_bf16 v[16:19], v[128:131], v[196:199], v[16:19]
	v_mfma_f32_16x16x32_bf16 v[8:11], v[136:139], v[196:199], v[8:11]
	v_mfma_f32_16x16x32_bf16 v[60:63], v[132:135], v[176:179], v[60:63]
	v_mfma_f32_16x16x32_bf16 v[56:59], v[140:143], v[176:179], v[56:59]
	v_mfma_f32_16x16x32_bf16 v[48:51], v[132:135], v[184:187], v[48:51]
	v_mfma_f32_16x16x32_bf16 v[40:43], v[140:143], v[184:187], v[40:43]
	v_mfma_f32_16x16x32_bf16 v[32:35], v[132:135], v[192:195], v[32:35]
	v_mfma_f32_16x16x32_bf16 v[24:27], v[140:143], v[192:195], v[24:27]
	v_mfma_f32_16x16x32_bf16 v[16:19], v[132:135], v[200:203], v[16:19]
	v_mfma_f32_16x16x32_bf16 v[8:11], v[140:143], v[200:203], v[8:11]
	v_mfma_f32_16x16x32_bf16 v[52:55], v[148:151], v[172:175], v[52:55]
	v_mfma_f32_16x16x32_bf16 v[44:47], v[164:167], v[172:175], v[44:47]
	v_mfma_f32_16x16x32_bf16 v[36:39], v[148:151], v[180:183], v[36:39]
	v_mfma_f32_16x16x32_bf16 v[28:31], v[164:167], v[180:183], v[28:31]
	v_mfma_f32_16x16x32_bf16 v[20:23], v[148:151], v[188:191], v[20:23]
	v_mfma_f32_16x16x32_bf16 v[12:15], v[164:167], v[188:191], v[12:15]
	v_mfma_f32_16x16x32_bf16 v[4:7], v[148:151], v[196:199], v[4:7]
	v_mfma_f32_16x16x32_bf16 v[0:3], v[164:167], v[196:199], v[0:3]
	v_mfma_f32_16x16x32_bf16 v[52:55], v[152:155], v[176:179], v[52:55]
	v_mfma_f32_16x16x32_bf16 v[44:47], v[168:171], v[176:179], v[44:47]
	v_mfma_f32_16x16x32_bf16 v[36:39], v[152:155], v[184:187], v[36:39]
	v_mfma_f32_16x16x32_bf16 v[28:31], v[168:171], v[184:187], v[28:31]
	v_mfma_f32_16x16x32_bf16 v[20:23], v[152:155], v[192:195], v[20:23]
	v_mfma_f32_16x16x32_bf16 v[12:15], v[168:171], v[192:195], v[12:15]
	v_mfma_f32_16x16x32_bf16 v[4:7], v[152:155], v[200:203], v[4:7]
	v_mfma_f32_16x16x32_bf16 v[0:3], v[168:171], v[200:203], v[0:3]
	s_setprio 0
	s_barrier
	s_add_i32 s45, s45, 2
	s_add_u32 s43, s43, 0x100
	s_addc_u32 s44, s44, 0
	s_cmpk_gt_u32 s45, 0xfd
	s_mov_b64 s[22:23], s[24:25]
	s_cbranch_scc0 .LBB0_1681
	s_and_b64 vcc, exec, s[10:11]
	s_cbranch_vccz .LBB0_1684
	s_barrier
.LBB0_1684:
	v_mov_b32_e32 v130, v223
	s_lshl_b32 s13, s20, 8
	s_lshl_b32 s15, s40, 8
	v_ashrrev_i32_e32 v128, 1, v130
	s_add_i32 s13, s13, s21
	s_or_b32 s15, s15, s38
	v_and_b32_e32 v128, -8, v128
	v_add_u32_e32 v128, s15, v128
	v_and_or_b32 v152, v130, 15, s13
	v_ashrrev_i32_e32 v129, 31, v128
	v_ashrrev_i32_e32 v153, 31, v152
	v_lshl_add_u64 v[150:151], v[128:129], 1, s[8:9]
	v_lshlrev_b64 v[130:131], 13, v[152:153]
	v_or_b32_e32 v184, 16, v152
	v_lshl_add_u64 v[130:131], v[150:151], 0, v[130:131]
	v_ashrrev_i32_e32 v185, 31, v184
	global_load_dwordx4 v[164:167], v[130:131], off
	global_load_dwordx4 v[168:171], v[130:131], off offset:256
	v_lshlrev_b64 v[130:131], 13, v[184:185]
	v_lshlrev_b64 v[148:149], 2, v[128:129]
	v_lshl_add_u64 v[130:131], v[150:151], 0, v[130:131]
	v_lshl_add_u64 v[128:129], s[6:7], 0, v[148:149]
	v_or_b32_e32 v196, 32, v152
	global_load_dwordx4 v[172:175], v[130:131], off
	global_load_dwordx4 v[176:179], v[130:131], off offset:256
	global_load_dwordx4 v[140:143], v[128:129], off
	global_load_dwordx4 v[136:139], v[128:129], off offset:16
	global_load_dwordx4 v[132:135], v[128:129], off offset:512
	s_nop 0
	global_load_dwordx4 v[128:131], v[128:129], off offset:528
	v_ashrrev_i32_e32 v197, 31, v196
	v_lshlrev_b64 v[154:155], 13, v[196:197]
	v_lshl_add_u64 v[186:187], v[150:151], 0, v[154:155]
	global_load_dwordx4 v[180:183], v[186:187], off
	v_or_b32_e32 v154, 48, v152
	v_ashrrev_i32_e32 v155, 31, v154
	v_lshlrev_b64 v[192:193], 14, v[184:185]
	global_load_dwordx4 v[184:187], v[186:187], off offset:256
	v_lshlrev_b64 v[188:189], 14, v[152:153]
	v_lshlrev_b64 v[190:191], 13, v[154:155]
	v_lshl_add_u64 v[188:189], s[4:5], 0, v[188:189]
	v_lshl_add_u64 v[192:193], s[4:5], 0, v[192:193]
	v_lshl_add_u64 v[194:195], v[150:151], 0, v[190:191]
	v_lshl_add_u64 v[198:199], v[188:189], 0, v[148:149]
	v_lshl_add_u64 v[200:201], v[192:193], 0, v[148:149]
	global_load_dwordx4 v[188:191], v[194:195], off
	s_nop 0
	global_load_dwordx4 v[192:195], v[194:195], off offset:256
	s_andn2_b64 vcc, exec, s[0:1]
	s_mov_b64 s[0:1], -1
	s_waitcnt vmcnt(11)
	v_lshlrev_b32_e32 v202, 16, v164
	v_and_b32_e32 v203, 0xffff0000, v164
	v_lshlrev_b32_e32 v164, 16, v165
	v_and_b32_e32 v165, 0xffff0000, v165
	s_waitcnt vmcnt(10)
	v_lshlrev_b32_e32 v206, 16, v168
	v_and_b32_e32 v207, 0xffff0000, v168
	v_lshlrev_b32_e32 v208, 16, v170
	v_and_b32_e32 v209, 0xffff0000, v170
	v_lshlrev_b32_e32 v170, 16, v171
	v_and_b32_e32 v171, 0xffff0000, v171
	v_lshlrev_b32_e32 v204, 16, v166
	v_and_b32_e32 v205, 0xffff0000, v166
	v_lshlrev_b32_e32 v166, 16, v167
	v_and_b32_e32 v167, 0xffff0000, v167
	v_lshlrev_b32_e32 v168, 16, v169
	v_and_b32_e32 v169, 0xffff0000, v169
	s_waitcnt vmcnt(9)
	v_lshlrev_b32_e32 v210, 16, v172
	v_and_b32_e32 v211, 0xffff0000, v172
	v_lshlrev_b32_e32 v172, 16, v173
	v_and_b32_e32 v173, 0xffff0000, v173
	v_lshlrev_b32_e32 v212, 16, v174
	v_and_b32_e32 v213, 0xffff0000, v174
	v_lshlrev_b32_e32 v174, 16, v175
	v_and_b32_e32 v175, 0xffff0000, v175
	s_waitcnt vmcnt(7)
	v_pk_fma_f32 v[126:127], v[126:127], v[142:143], v[164:165]
	v_pk_fma_f32 v[124:125], v[124:125], v[140:141], v[202:203]
	s_waitcnt vmcnt(5)
	v_pk_fma_f32 v[108:109], v[108:109], v[132:133], v[206:207]
	s_waitcnt vmcnt(4)
	v_pk_fma_f32 v[106:107], v[106:107], v[130:131], v[170:171]
	v_pk_fma_f32 v[122:123], v[122:123], v[138:139], v[166:167]
	v_pk_fma_f32 v[120:121], v[120:121], v[136:137], v[204:205]
	v_pk_fma_f32 v[110:111], v[110:111], v[134:135], v[168:169]
	v_pk_fma_f32 v[104:105], v[104:105], v[128:129], v[208:209]
	v_pk_fma_f32 v[118:119], v[118:119], v[142:143], v[172:173]
	v_pk_fma_f32 v[116:117], v[116:117], v[140:141], v[210:211]
	v_pk_fma_f32 v[114:115], v[114:115], v[138:139], v[174:175]
	v_pk_fma_f32 v[112:113], v[112:113], v[136:137], v[212:213]
	global_store_dwordx4 v[198:199], v[124:127], off
	global_store_dwordx4 v[198:199], v[120:123], off offset:16
	global_store_dwordx4 v[198:199], v[108:111], off offset:512
	global_store_dwordx4 v[198:199], v[104:107], off offset:528
	global_store_dwordx4 v[200:201], v[116:119], off
	global_store_dwordx4 v[200:201], v[112:115], off offset:16
	v_lshlrev_b32_e32 v106, 16, v178
	v_and_b32_e32 v107, 0xffff0000, v178
	v_lshlrev_b32_e32 v108, 16, v179
	v_and_b32_e32 v109, 0xffff0000, v179
	v_pk_fma_f32 v[94:95], v[94:95], v[130:131], v[108:109]
	v_pk_fma_f32 v[92:93], v[92:93], v[128:129], v[106:107]
	global_store_dwordx4 v[200:201], v[92:95], off offset:528
	v_lshlrev_b32_e32 v214, 16, v176
	v_and_b32_e32 v215, 0xffff0000, v176
	s_waitcnt vmcnt(10)
	v_lshlrev_b32_e32 v92, 16, v180
	v_and_b32_e32 v93, 0xffff0000, v180
	v_pk_fma_f32 v[92:93], v[96:97], v[140:141], v[92:93]
	v_lshlrev_b64 v[96:97], 14, v[196:197]
	v_lshlrev_b32_e32 v104, 16, v177
	v_and_b32_e32 v105, 0xffff0000, v177
	v_lshlrev_b32_e32 v94, 16, v181
	v_and_b32_e32 v95, 0xffff0000, v181
	v_lshl_add_u64 v[96:97], s[4:5], 0, v[96:97]
	v_pk_fma_f32 v[102:103], v[102:103], v[134:135], v[104:105]
	v_pk_fma_f32 v[100:101], v[100:101], v[132:133], v[214:215]
	v_pk_fma_f32 v[94:95], v[98:99], v[142:143], v[94:95]
	v_lshl_add_u64 v[96:97], v[96:97], 0, v[148:149]
	global_store_dwordx4 v[200:201], v[100:103], off offset:512
	global_store_dwordx4 v[96:97], v[92:95], off
	v_add_u32_e32 v98, 0x90, v152
	v_lshlrev_b32_e32 v100, 16, v182
	v_and_b32_e32 v101, 0xffff0000, v182
	v_lshlrev_b32_e32 v102, 16, v183
	v_and_b32_e32 v103, 0xffff0000, v183
	s_waitcnt vmcnt(11)
	v_lshlrev_b32_e32 v92, 16, v186
	v_and_b32_e32 v93, 0xffff0000, v186
	v_lshlrev_b32_e32 v94, 16, v187
	v_and_b32_e32 v95, 0xffff0000, v187
	v_pk_fma_f32 v[90:91], v[90:91], v[138:139], v[102:103]
	v_pk_fma_f32 v[88:89], v[88:89], v[136:137], v[100:101]
	v_pk_fma_f32 v[78:79], v[78:79], v[130:131], v[94:95]
	v_pk_fma_f32 v[76:77], v[76:77], v[128:129], v[92:93]
	global_store_dwordx4 v[96:97], v[88:91], off offset:16
	global_store_dwordx4 v[96:97], v[76:79], off offset:528
	v_ashrrev_i32_e32 v99, 31, v98
	v_lshlrev_b32_e32 v88, 16, v184
	v_and_b32_e32 v89, 0xffff0000, v184
	v_lshlrev_b32_e32 v90, 16, v185
	v_and_b32_e32 v91, 0xffff0000, v185
	s_waitcnt vmcnt(12)
	v_lshlrev_b32_e32 v76, 16, v188
	v_and_b32_e32 v77, 0xffff0000, v188
	v_pk_fma_f32 v[86:87], v[86:87], v[134:135], v[90:91]
	v_pk_fma_f32 v[84:85], v[84:85], v[132:133], v[88:89]
	v_pk_fma_f32 v[76:77], v[80:81], v[140:141], v[76:77]
	v_lshlrev_b64 v[80:81], 14, v[154:155]
	global_store_dwordx4 v[96:97], v[84:87], off offset:512
	v_lshlrev_b32_e32 v78, 16, v189
	v_and_b32_e32 v79, 0xffff0000, v189
	v_lshlrev_b32_e32 v84, 16, v190
	v_and_b32_e32 v85, 0xffff0000, v190
	v_lshlrev_b32_e32 v86, 16, v191
	v_and_b32_e32 v87, 0xffff0000, v191
	v_lshl_add_u64 v[80:81], s[4:5], 0, v[80:81]
	v_pk_fma_f32 v[78:79], v[82:83], v[142:143], v[78:79]
	v_lshl_add_u64 v[80:81], v[80:81], 0, v[148:149]
	v_pk_fma_f32 v[74:75], v[74:75], v[138:139], v[86:87]
	v_pk_fma_f32 v[72:73], v[72:73], v[136:137], v[84:85]
	global_store_dwordx4 v[80:81], v[76:79], off
	global_store_dwordx4 v[80:81], v[72:75], off offset:16
	v_add_u32_e32 v96, 0x80, v152
	s_waitcnt vmcnt(14)
	v_lshlrev_b32_e32 v76, 16, v194
	v_lshlrev_b32_e32 v72, 16, v192
	v_and_b32_e32 v73, 0xffff0000, v192
	v_lshlrev_b32_e32 v74, 16, v193
	v_and_b32_e32 v75, 0xffff0000, v193
	v_and_b32_e32 v77, 0xffff0000, v194
	v_lshlrev_b32_e32 v78, 16, v195
	v_and_b32_e32 v79, 0xffff0000, v195
	v_pk_fma_f32 v[70:71], v[70:71], v[134:135], v[74:75]
	v_pk_fma_f32 v[68:69], v[68:69], v[132:133], v[72:73]
	v_pk_fma_f32 v[66:67], v[66:67], v[130:131], v[78:79]
	v_pk_fma_f32 v[64:65], v[64:65], v[128:129], v[76:77]
	v_ashrrev_i32_e32 v97, 31, v96
	global_store_dwordx4 v[80:81], v[68:71], off offset:512
	global_store_dwordx4 v[80:81], v[64:67], off offset:528
	v_add_u32_e32 v100, 0xa0, v152
	v_ashrrev_i32_e32 v101, 31, v100
	v_lshlrev_b64 v[64:65], 13, v[96:97]
	v_lshl_add_u64 v[64:65], v[150:151], 0, v[64:65]
	global_load_dwordx4 v[68:71], v[64:65], off
	global_load_dwordx4 v[72:75], v[64:65], off offset:256
	v_lshlrev_b64 v[64:65], 13, v[98:99]
	v_lshl_add_u64 v[64:65], v[150:151], 0, v[64:65]
	global_load_dwordx4 v[76:79], v[64:65], off
	global_load_dwordx4 v[80:83], v[64:65], off offset:256
	v_lshlrev_b64 v[64:65], 13, v[100:101]
	v_lshl_add_u64 v[64:65], v[150:151], 0, v[64:65]
	global_load_dwordx4 v[84:87], v[64:65], off
	global_load_dwordx4 v[88:91], v[64:65], off offset:256
	v_add_u32_e32 v102, 0xb0, v152
	v_ashrrev_i32_e32 v103, 31, v102
	v_lshlrev_b64 v[64:65], 13, v[102:103]
	v_lshl_add_u64 v[64:65], v[150:151], 0, v[64:65]
	global_load_dwordx4 v[92:95], v[64:65], off
	s_nop 0
	global_load_dwordx4 v[64:67], v[64:65], off offset:256
	s_waitcnt vmcnt(7)
	v_lshlrev_b32_e32 v104, 16, v68
	v_and_b32_e32 v105, 0xffff0000, v68
	v_lshlrev_b32_e32 v68, 16, v69
	v_and_b32_e32 v69, 0xffff0000, v69
	v_pk_fma_f32 v[62:63], v[62:63], v[142:143], v[68:69]
	v_lshlrev_b64 v[68:69], 14, v[96:97]
	v_lshl_add_u64 v[68:69], s[4:5], 0, v[68:69]
	v_pk_fma_f32 v[60:61], v[60:61], v[140:141], v[104:105]
	v_lshl_add_u64 v[68:69], v[68:69], 0, v[148:149]
	global_store_dwordx4 v[68:69], v[60:63], off
	v_lshlrev_b32_e32 v106, 16, v70
	v_and_b32_e32 v107, 0xffff0000, v70
	s_waitcnt vmcnt(7)
	v_lshlrev_b32_e32 v60, 16, v74
	v_and_b32_e32 v61, 0xffff0000, v74
	v_lshlrev_b32_e32 v62, 16, v75
	v_and_b32_e32 v63, 0xffff0000, v75
	v_pk_fma_f32 v[46:47], v[46:47], v[130:131], v[62:63]
	v_pk_fma_f32 v[44:45], v[44:45], v[128:129], v[60:61]
	global_store_dwordx4 v[68:69], v[44:47], off offset:528
	v_lshlrev_b32_e32 v70, 16, v71
	v_and_b32_e32 v71, 0xffff0000, v71
	s_waitcnt vmcnt(7)
	v_lshlrev_b32_e32 v44, 16, v76
	v_and_b32_e32 v45, 0xffff0000, v76
	v_pk_fma_f32 v[44:45], v[48:49], v[140:141], v[44:45]
	v_lshlrev_b64 v[48:49], 14, v[98:99]
	v_lshlrev_b32_e32 v46, 16, v77
	v_and_b32_e32 v47, 0xffff0000, v77
	v_lshl_add_u64 v[48:49], s[4:5], 0, v[48:49]
	v_pk_fma_f32 v[58:59], v[58:59], v[138:139], v[70:71]
	v_pk_fma_f32 v[56:57], v[56:57], v[136:137], v[106:107]
	v_pk_fma_f32 v[46:47], v[50:51], v[142:143], v[46:47]
	v_lshl_add_u64 v[48:49], v[48:49], 0, v[148:149]
	global_store_dwordx4 v[68:69], v[56:59], off offset:16
	global_store_dwordx4 v[48:49], v[44:47], off
	s_nop 0
	v_lshlrev_b32_e32 v56, 16, v72
	v_and_b32_e32 v57, 0xffff0000, v72
	v_lshlrev_b32_e32 v58, 16, v73
	v_and_b32_e32 v59, 0xffff0000, v73
	s_waitcnt vmcnt(8)
	v_lshlrev_b32_e32 v44, 16, v82
	v_and_b32_e32 v45, 0xffff0000, v82
	v_lshlrev_b32_e32 v46, 16, v83
	v_and_b32_e32 v47, 0xffff0000, v83
	v_pk_fma_f32 v[54:55], v[54:55], v[134:135], v[58:59]
	v_pk_fma_f32 v[52:53], v[52:53], v[132:133], v[56:57]
	v_pk_fma_f32 v[30:31], v[30:31], v[130:131], v[46:47]
	v_pk_fma_f32 v[28:29], v[28:29], v[128:129], v[44:45]
	global_store_dwordx4 v[68:69], v[52:55], off offset:512
	global_store_dwordx4 v[48:49], v[28:31], off offset:528
	s_nop 0
	v_lshlrev_b32_e32 v52, 16, v78
	v_and_b32_e32 v53, 0xffff0000, v78
	v_lshlrev_b32_e32 v54, 16, v79
	v_and_b32_e32 v55, 0xffff0000, v79
	s_waitcnt vmcnt(9)
	v_lshlrev_b32_e32 v28, 16, v84
	v_and_b32_e32 v29, 0xffff0000, v84
	v_pk_fma_f32 v[42:43], v[42:43], v[138:139], v[54:55]
	v_pk_fma_f32 v[40:41], v[40:41], v[136:137], v[52:53]
	v_pk_fma_f32 v[28:29], v[32:33], v[140:141], v[28:29]
	v_lshlrev_b64 v[32:33], 14, v[100:101]
	global_store_dwordx4 v[48:49], v[40:43], off offset:16
	v_lshlrev_b32_e32 v30, 16, v85
	v_and_b32_e32 v31, 0xffff0000, v85
	v_lshlrev_b32_e32 v40, 16, v80
	v_and_b32_e32 v41, 0xffff0000, v80
	v_lshlrev_b32_e32 v42, 16, v81
	v_and_b32_e32 v43, 0xffff0000, v81
	v_lshl_add_u64 v[32:33], s[4:5], 0, v[32:33]
	v_pk_fma_f32 v[38:39], v[38:39], v[134:135], v[42:43]
	v_pk_fma_f32 v[36:37], v[36:37], v[132:133], v[40:41]
	v_pk_fma_f32 v[30:31], v[34:35], v[142:143], v[30:31]
	v_lshl_add_u64 v[32:33], v[32:33], 0, v[148:149]
	global_store_dwordx4 v[48:49], v[36:39], off offset:512
	global_store_dwordx4 v[32:33], v[28:31], off
	s_nop 0
	v_lshlrev_b32_e32 v36, 16, v86
	v_and_b32_e32 v37, 0xffff0000, v86
	v_lshlrev_b32_e32 v38, 16, v87
	v_and_b32_e32 v39, 0xffff0000, v87
	s_waitcnt vmcnt(11)
	v_lshlrev_b32_e32 v28, 16, v90
	v_and_b32_e32 v29, 0xffff0000, v90
	v_lshlrev_b32_e32 v30, 16, v91
	v_and_b32_e32 v31, 0xffff0000, v91
	v_pk_fma_f32 v[26:27], v[26:27], v[138:139], v[38:39]
	v_pk_fma_f32 v[24:25], v[24:25], v[136:137], v[36:37]
	v_pk_fma_f32 v[14:15], v[14:15], v[130:131], v[30:31]
	v_pk_fma_f32 v[12:13], v[12:13], v[128:129], v[28:29]
	global_store_dwordx4 v[32:33], v[24:27], off offset:16
	global_store_dwordx4 v[32:33], v[12:15], off offset:528
	s_nop 0
	v_lshlrev_b32_e32 v24, 16, v88
	v_and_b32_e32 v25, 0xffff0000, v88
	v_lshlrev_b32_e32 v26, 16, v89
	v_and_b32_e32 v27, 0xffff0000, v89
	s_waitcnt vmcnt(12)
	v_lshlrev_b32_e32 v12, 16, v92
	v_and_b32_e32 v13, 0xffff0000, v92
	v_pk_fma_f32 v[22:23], v[22:23], v[134:135], v[26:27]
	v_pk_fma_f32 v[20:21], v[20:21], v[132:133], v[24:25]
	v_pk_fma_f32 v[12:13], v[16:17], v[140:141], v[12:13]
	v_lshlrev_b64 v[16:17], 14, v[102:103]
	global_store_dwordx4 v[32:33], v[20:23], off offset:512
	v_lshlrev_b32_e32 v14, 16, v93
	v_and_b32_e32 v15, 0xffff0000, v93
	v_lshlrev_b32_e32 v20, 16, v94
	v_and_b32_e32 v21, 0xffff0000, v94
	v_lshlrev_b32_e32 v22, 16, v95
	v_and_b32_e32 v23, 0xffff0000, v95
	v_lshl_add_u64 v[16:17], s[4:5], 0, v[16:17]
	v_pk_fma_f32 v[14:15], v[18:19], v[142:143], v[14:15]
	v_lshl_add_u64 v[16:17], v[16:17], 0, v[148:149]
	v_pk_fma_f32 v[10:11], v[10:11], v[138:139], v[22:23]
	v_pk_fma_f32 v[8:9], v[8:9], v[136:137], v[20:21]
	global_store_dwordx4 v[16:17], v[12:15], off
	global_store_dwordx4 v[16:17], v[8:11], off offset:16
	s_waitcnt vmcnt(14)
	v_lshlrev_b32_e32 v12, 16, v66
	v_lshlrev_b32_e32 v8, 16, v64
	v_and_b32_e32 v9, 0xffff0000, v64
	v_lshlrev_b32_e32 v10, 16, v65
	v_and_b32_e32 v11, 0xffff0000, v65
	v_and_b32_e32 v13, 0xffff0000, v66
	v_lshlrev_b32_e32 v14, 16, v67
	v_and_b32_e32 v15, 0xffff0000, v67
	v_pk_fma_f32 v[6:7], v[6:7], v[134:135], v[10:11]
	v_pk_fma_f32 v[4:5], v[4:5], v[132:133], v[8:9]
	v_pk_fma_f32 v[2:3], v[2:3], v[130:131], v[14:15]
	v_pk_fma_f32 v[0:1], v[0:1], v[128:129], v[12:13]
	global_store_dwordx4 v[16:17], v[4:7], off offset:512
	global_store_dwordx4 v[16:17], v[0:3], off offset:528
	s_cbranch_vccnz .LBB0_1673
	s_andn2_b64 vcc, exec, s[2:3]
	s_cbranch_vccnz .LBB0_1672
	s_mov_b32 s99, 1
	s_branch .LBB0_1672
